# mid-segment s_setprio 0/1 toggles removed: the MFMA wave keeps its raised priority across the whole 32-MFMA segment
# speedup vs baseline: 1.0029x; 1.0029x over previous
; #define PG8_STAGE(bufoff, gbase, voff) do { _Pragma("unroll") for (int _i = 0; _i < 2; ++_i) \
;         __builtin_amdgcn_global_load_lds((const unsigned*)((const char*)(gbase) + (voff)[_i]), (PG8_LAS unsigned*)(lds + (bufoff) + ldsw + _i * 8192), 16, 0, 0); } while (0)
; #define PG8_LDA(dst, b, h) do { _Pragma("unroll") for (int m = 0; m < 4; ++m) _Pragma("unroll") for (int k = 0; k < 2; ++k) dst[m][k] = *(const PG8_LAS bf16x8*)(lds + PG8_SA(b, h) + aoff + m * 2048 + k * 1024); } while (0)
; #define PG8_LDB(dst, b, h) do { _Pragma("unroll") for (int n = 0; n < 2; ++n) _Pragma("unroll") for (int k = 0; k < 2; ++k) dst[n][k] = *(const PG8_LAS bf16x8*)(lds + PG8_SB(b, h) + boff + n * 2048 + k * 1024); } while (0)
; #define PG8_WAIT_V(n) asm volatile("s_waitcnt vmcnt(" #n ")" ::: "memory")
; #define PG8_WAIT_L(n) asm volatile("s_waitcnt lgkmcnt(" #n ")" ::: "memory")
; #define PG8_BAR __builtin_amdgcn_s_barrier()
; #define PG8_SCHED __builtin_amdgcn_sched_barrier(0)
; template <class Epi, class Sched, bool ALIGN_EPI = false, bool SP2 = false>
; __device__ __forceinline__ void gemm_phase(PG8_LAS unsigned char* lds, const Gemm g, const Sched& S, const Epi& E) {
;     ...
;         const char* nA = has_next ? (const char*)g.A + (size_t)nxt.pm * tstepA : cA; const char* nB = has_next ? (const char*)g.Bt + (size_t)nxt.pn * tstepB : cB;
;         for (int t = 0; t < nt; t += 2) {
;             const bool last = (t == nt - 2);
;             if constexpr (Epi::HAS_MID) { if (t == E.mid_t) E.mid(acc, cur, wr, wc, fr, fq); }
;             const char* a1 = cA + (size_t)(t + 1) * kstep;
;             const char* a2 = last ? nA : cA + (size_t)(t + 2) * kstep; const char* b2 = last ? nB : cB + (size_t)(t + 2) * kstep;
;             const char* a3 = a2 + kstep; const char* b3 = b2 + kstep;
;             if (last && has_next) S.a_ready(nxt);
;             if constexpr (SP2) {
;             PG8_LDB(B0, 0, 0); PG8_LDB(B1, 0, 1); PG8_SCHED; PG8_LDA(At, 0, 0); PG8_STAGE(PG8_SA(1, 1), a1 + hstepA, voffA);
;             PG8_WAIT_V(8); PG8_WAIT_L(0); PG8_BAR; PG8_MMA(0, 0, At, B0); PG8_MMA(0, 1, At, B1); PG8_BAR; PG8_SCHED;
;             PG8_LDA(At, 0, 1); PG8_STAGE(PG8_SB(0, 0), b2, voffB); PG8_STAGE(PG8_SB(0, 1), b2 + hstepB, voffB); PG8_STAGE(PG8_SA(0, 0), a2, voffA);
;             PG8_WAIT_V(8); PG8_WAIT_L(0); PG8_BAR; PG8_MMA(1, 0, At, B0); PG8_MMA(1, 1, At, B1); PG8_BAR; PG8_SCHED;
.LBB0_187:
	ds_read_b128 v[128:131], v173
	ds_read_b128 v[132:135], v173 offset:1024
	ds_read_b128 v[152:155], v173 offset:2048
	ds_read_b128 v[156:159], v173 offset:3072
	ds_read_b128 v[160:163], v174
	ds_read_b128 v[164:167], v174 offset:1024
	ds_read_b128 v[180:183], v174 offset:2048
	ds_read_b128 v[184:187], v174 offset:3072
	s_add_u32 s16, s12, 0xfff80080
	s_addc_u32 s17, s13, -1
	s_cmp_eq_u32 s61, 28
	s_cselect_b32 s19, s1, s17
	s_cselect_b32 s18, s26, s16
	s_cselect_b32 s17, s15, s60
	s_cselect_b32 s16, s36, s37
	ds_read_b128 v[188:191], v175
	ds_read_b128 v[192:195], v175 offset:1024
	ds_read_b128 v[196:199], v175 offset:2048
	ds_read_b128 v[200:203], v175 offset:3072
	ds_read_b128 v[204:207], v175 offset:4096
	ds_read_b128 v[208:211], v175 offset:5120
	ds_read_b128 v[212:215], v175 offset:6144
	ds_read_b128 v[216:219], v175 offset:7168
	s_add_u32 s98, s12, 0xfff80000
	s_addc_u32 s99, s13, -1
	s_mov_b32 m0, s7
	s_nop 0
	global_load_lds_dwordx4 v136, s[98:99]
	s_mov_b32 m0, s46
	s_nop 0
	global_load_lds_dwordx4 v140, s[98:99]
	s_add_i32 m0, s77, 0xc000
	s_nop 0
	global_load_lds_dwordx4 v144, s[12:13]
	s_add_i32 m0, s77, 0xe000
	s_nop 0
	global_load_lds_dwordx4 v146, s[12:13]
	s_waitcnt vmcnt(8)
	s_waitcnt lgkmcnt(0)
	s_barrier
	s_setprio 1
	v_mfma_f32_16x16x32_bf16 v[124:127], v[128:131], v[188:191], v[124:127]
	v_mfma_f32_16x16x32_bf16 v[120:123], v[152:155], v[188:191], v[120:123]
	v_mfma_f32_16x16x32_bf16 v[108:111], v[128:131], v[196:199], v[108:111]
	v_mfma_f32_16x16x32_bf16 v[104:107], v[152:155], v[196:199], v[104:107]
	v_mfma_f32_16x16x32_bf16 v[92:95], v[128:131], v[204:207], v[92:95]
	v_mfma_f32_16x16x32_bf16 v[88:91], v[152:155], v[204:207], v[88:91]
	v_mfma_f32_16x16x32_bf16 v[76:79], v[128:131], v[212:215], v[76:79]
	v_mfma_f32_16x16x32_bf16 v[72:75], v[152:155], v[212:215], v[72:75]
	v_mfma_f32_16x16x32_bf16 v[124:127], v[132:135], v[192:195], v[124:127]
	v_mfma_f32_16x16x32_bf16 v[120:123], v[156:159], v[192:195], v[120:123]
	v_mfma_f32_16x16x32_bf16 v[108:111], v[132:135], v[200:203], v[108:111]
	v_mfma_f32_16x16x32_bf16 v[104:107], v[156:159], v[200:203], v[104:107]
	v_mfma_f32_16x16x32_bf16 v[92:95], v[132:135], v[208:211], v[92:95]
	v_mfma_f32_16x16x32_bf16 v[88:91], v[156:159], v[208:211], v[88:91]
	v_mfma_f32_16x16x32_bf16 v[76:79], v[132:135], v[216:219], v[76:79]
	v_mfma_f32_16x16x32_bf16 v[72:75], v[156:159], v[216:219], v[72:75]
	v_mfma_f32_16x16x32_bf16 v[116:119], v[160:163], v[188:191], v[116:119]
	v_mfma_f32_16x16x32_bf16 v[112:115], v[180:183], v[188:191], v[112:115]
	v_mfma_f32_16x16x32_bf16 v[100:103], v[160:163], v[196:199], v[100:103]
	v_mfma_f32_16x16x32_bf16 v[96:99], v[180:183], v[196:199], v[96:99]
	v_mfma_f32_16x16x32_bf16 v[84:87], v[160:163], v[204:207], v[84:87]
	v_mfma_f32_16x16x32_bf16 v[80:83], v[180:183], v[204:207], v[80:83]
	v_mfma_f32_16x16x32_bf16 v[68:71], v[160:163], v[212:215], v[68:71]
	v_mfma_f32_16x16x32_bf16 v[64:67], v[180:183], v[212:215], v[64:67]
	v_mfma_f32_16x16x32_bf16 v[116:119], v[164:167], v[192:195], v[116:119]
	v_mfma_f32_16x16x32_bf16 v[112:115], v[184:187], v[192:195], v[112:115]
	v_mfma_f32_16x16x32_bf16 v[100:103], v[164:167], v[200:203], v[100:103]
	v_mfma_f32_16x16x32_bf16 v[96:99], v[184:187], v[200:203], v[96:99]
	v_mfma_f32_16x16x32_bf16 v[84:87], v[164:167], v[208:211], v[84:87]
	v_mfma_f32_16x16x32_bf16 v[80:83], v[184:187], v[208:211], v[80:83]
	v_mfma_f32_16x16x32_bf16 v[68:71], v[164:167], v[216:219], v[68:71]
	v_mfma_f32_16x16x32_bf16 v[64:67], v[184:187], v[216:219], v[64:67]
	s_setprio 0
	s_barrier
	s_add_i32 s69, s47, s33
	s_mov_b32 m0, s69
	ds_read_b128 v[188:191], v175 offset:16384
	ds_read_b128 v[192:195], v175 offset:17408
	ds_read_b128 v[196:199], v175 offset:18432
	ds_read_b128 v[200:203], v175 offset:19456
	ds_read_b128 v[204:207], v175 offset:20480
	ds_read_b128 v[208:211], v175 offset:21504
	ds_read_b128 v[212:215], v175 offset:22528
	ds_read_b128 v[216:219], v175 offset:23552
	global_load_lds_dwordx4 v138, s[16:17]
	s_add_i32 m0, s69, 0x2000
	s_add_u32 s70, s16, 0x80000
	s_addc_u32 s71, s17, 0
	s_add_i32 s69, s56, s33
	global_load_lds_dwordx4 v142, s[16:17]
	s_mov_b32 m0, s69
	s_nop 0
	global_load_lds_dwordx4 v138, s[70:71]
	s_add_i32 m0, s69, 0x2000
	s_nop 0
	global_load_lds_dwordx4 v142, s[70:71]
	s_waitcnt vmcnt(6)
	s_waitcnt lgkmcnt(0)
	s_barrier
	s_setprio 1
	v_mfma_f32_16x16x32_bf16 v[60:63], v[128:131], v[188:191], v[60:63]
	v_mfma_f32_16x16x32_bf16 v[56:59], v[152:155], v[188:191], v[56:59]
	v_mfma_f32_16x16x32_bf16 v[44:47], v[128:131], v[196:199], v[44:47]
	v_mfma_f32_16x16x32_bf16 v[40:43], v[152:155], v[196:199], v[40:43]
	v_mfma_f32_16x16x32_bf16 v[28:31], v[128:131], v[204:207], v[28:31]
	v_mfma_f32_16x16x32_bf16 v[24:27], v[152:155], v[204:207], v[24:27]
	v_mfma_f32_16x16x32_bf16 v[12:15], v[128:131], v[212:215], v[12:15]
	v_mfma_f32_16x16x32_bf16 v[8:11], v[152:155], v[212:215], v[8:11]
	v_mfma_f32_16x16x32_bf16 v[60:63], v[132:135], v[192:195], v[60:63]
	v_mfma_f32_16x16x32_bf16 v[56:59], v[156:159], v[192:195], v[56:59]
	v_mfma_f32_16x16x32_bf16 v[44:47], v[132:135], v[200:203], v[44:47]
	v_mfma_f32_16x16x32_bf16 v[40:43], v[156:159], v[200:203], v[40:43]
	v_mfma_f32_16x16x32_bf16 v[28:31], v[132:135], v[208:211], v[28:31]
	v_mfma_f32_16x16x32_bf16 v[24:27], v[156:159], v[208:211], v[24:27]
	v_mfma_f32_16x16x32_bf16 v[12:15], v[132:135], v[216:219], v[12:15]
	v_mfma_f32_16x16x32_bf16 v[8:11], v[156:159], v[216:219], v[8:11]
	v_mfma_f32_16x16x32_bf16 v[52:55], v[160:163], v[188:191], v[52:55]
	v_mfma_f32_16x16x32_bf16 v[48:51], v[180:183], v[188:191], v[48:51]
	v_mfma_f32_16x16x32_bf16 v[36:39], v[160:163], v[196:199], v[36:39]
	v_mfma_f32_16x16x32_bf16 v[32:35], v[180:183], v[196:199], v[32:35]
	v_mfma_f32_16x16x32_bf16 v[20:23], v[160:163], v[204:207], v[20:23]
	v_mfma_f32_16x16x32_bf16 v[16:19], v[180:183], v[204:207], v[16:19]
	v_mfma_f32_16x16x32_bf16 v[4:7], v[160:163], v[212:215], v[4:7]
	v_mfma_f32_16x16x32_bf16 v[0:3], v[180:183], v[212:215], v[0:3]
	v_mfma_f32_16x16x32_bf16 v[52:55], v[164:167], v[192:195], v[52:55]
	v_mfma_f32_16x16x32_bf16 v[48:51], v[184:187], v[192:195], v[48:51]
	v_mfma_f32_16x16x32_bf16 v[36:39], v[164:167], v[200:203], v[36:39]
	v_mfma_f32_16x16x32_bf16 v[32:35], v[184:187], v[200:203], v[32:35]
	v_mfma_f32_16x16x32_bf16 v[20:23], v[164:167], v[208:211], v[20:23]
	v_mfma_f32_16x16x32_bf16 v[16:19], v[184:187], v[208:211], v[16:19]
	v_mfma_f32_16x16x32_bf16 v[4:7], v[164:167], v[216:219], v[4:7]
	v_mfma_f32_16x16x32_bf16 v[0:3], v[184:187], v[216:219], v[0:3]
	s_setprio 0
	s_barrier
; #define PG8_STAGE(bufoff, gbase, voff) do { _Pragma("unroll") for (int _i = 0; _i < 2; ++_i) \
;         __builtin_amdgcn_global_load_lds((const unsigned*)((const char*)(gbase) + (voff)[_i]), (PG8_LAS unsigned*)(lds + (bufoff) + ldsw + _i * 8192), 16, 0, 0); } while (0)
; #define PG8_LDA(dst, b, h) do { _Pragma("unroll") for (int m = 0; m < 4; ++m) _Pragma("unroll") for (int k = 0; k < 2; ++k) dst[m][k] = *(const PG8_LAS bf16x8*)(lds + PG8_SA(b, h) + aoff + m * 2048 + k * 1024); } while (0)
; #define PG8_WAIT_V(n) asm volatile("s_waitcnt vmcnt(" #n ")" ::: "memory")
; #define PG8_BAR __builtin_amdgcn_s_barrier()
; template <class Epi, class Sched, bool ALIGN_EPI = false, bool SP2 = false>
; __device__ __forceinline__ void gemm_phase(PG8_LAS unsigned char* lds, const Gemm g, const Sched& S, const Epi& E) {
;     ...
;         for (int t = 0; t < nt; t += 2) {
;             const bool last = (t == nt - 2);
;             if constexpr (Epi::HAS_MID) { if (t == E.mid_t) E.mid(acc, cur, wr, wc, fr, fq); }
;             const char* a1 = cA + (size_t)(t + 1) * kstep;
;             const char* a2 = last ? nA : cA + (size_t)(t + 2) * kstep; const char* b2 = last ? nB : cB + (size_t)(t + 2) * kstep;
;             const char* a3 = a2 + kstep; const char* b3 = b2 + kstep;
;             if (last && has_next) S.a_ready(nxt);
;             if constexpr (SP2) {
;             PG8_LDB(B0, 0, 0); PG8_LDB(B1, 0, 1); PG8_SCHED; PG8_LDA(At, 0, 0); PG8_STAGE(PG8_SA(1, 1), a1 + hstepA, voffA);
;             PG8_WAIT_V(8); PG8_WAIT_L(0); PG8_BAR; PG8_MMA(0, 0, At, B0); PG8_MMA(0, 1, At, B1); PG8_BAR; PG8_SCHED;
;             PG8_LDA(At, 0, 1); PG8_STAGE(PG8_SB(0, 0), b2, voffB); PG8_STAGE(PG8_SB(0, 1), b2 + hstepB, voffB); PG8_STAGE(PG8_SA(0, 0), a2, voffA);
;             PG8_WAIT_V(8); PG8_WAIT_L(0); PG8_BAR; PG8_MMA(1, 0, At, B0); PG8_MMA(1, 1, At, B1); PG8_BAR; PG8_SCHED;
;             PG8_LDB(B0, 1, 0); PG8_LDB(B1, 1, 1); PG8_SCHED; PG8_LDA(At, 1, 0); PG8_STAGE(PG8_SA(0, 1), a2 + hstepA, voffA);
;             PG8_WAIT_V(8); PG8_WAIT_L(0); PG8_BAR; PG8_MMA(0, 0, At, B0); PG8_MMA(0, 1, At, B1); PG8_BAR; PG8_SCHED;
;             PG8_LDA(At, 1, 1); PG8_STAGE(PG8_SB(1, 0), b3, voffB); PG8_STAGE(PG8_SB(1, 1), b3 + hstepB, voffB); PG8_STAGE(PG8_SA(1, 0), a3, voffA);
;             PG8_WAIT_V(8); PG8_WAIT_L(0); PG8_BAR; PG8_MMA(1, 0, At, B0); PG8_MMA(1, 1, At, B1); PG8_BAR; PG8_SCHED;
	s_add_i32 s69, 0, 0x18000
	s_add_i32 s70, 0, 0x1c000
	v_add_u32_e32 v156, s69, v172
	v_add_u32_e32 v179, s70, v172
	ds_read_b128 v[128:131], v156
	ds_read_b128 v[132:135], v156 offset:1024
	ds_read_b128 v[152:155], v156 offset:2048
	ds_read_b128 v[156:159], v156 offset:3072
	ds_read_b128 v[160:163], v179
	ds_read_b128 v[164:167], v179 offset:1024
	ds_read_b128 v[180:183], v179 offset:2048
	ds_read_b128 v[184:187], v179 offset:3072
	s_mov_b64 s[100:101], s[18:19]
	s_add_u32 s18, s18, 0x80000
	s_addc_u32 s19, s19, 0
	ds_read_b128 v[188:191], v175 offset:32768
	ds_read_b128 v[192:195], v175 offset:33792
	ds_read_b128 v[196:199], v175 offset:34816
	ds_read_b128 v[200:203], v175 offset:35840
	ds_read_b128 v[204:207], v175 offset:36864
	ds_read_b128 v[208:211], v175 offset:37888
	ds_read_b128 v[212:215], v175 offset:38912
	ds_read_b128 v[216:219], v175 offset:39936
	s_mov_b32 m0, s77
	s_nop 0
	global_load_lds_dwordx4 v136, s[100:101]
	s_mov_b32 m0, s22
	s_nop 0
	global_load_lds_dwordx4 v140, s[100:101]
	s_mov_b32 m0, s23
	s_nop 0
	global_load_lds_dwordx4 v136, s[18:19]
	s_mov_b32 m0, s4
	s_nop 0
	global_load_lds_dwordx4 v140, s[18:19]
	s_waitcnt vmcnt(8)
	s_waitcnt lgkmcnt(0)
	s_barrier
	s_setprio 1
	v_mfma_f32_16x16x32_bf16 v[124:127], v[128:131], v[188:191], v[124:127]
	v_mfma_f32_16x16x32_bf16 v[120:123], v[152:155], v[188:191], v[120:123]
	v_mfma_f32_16x16x32_bf16 v[108:111], v[128:131], v[196:199], v[108:111]
	v_mfma_f32_16x16x32_bf16 v[104:107], v[152:155], v[196:199], v[104:107]
	v_mfma_f32_16x16x32_bf16 v[92:95], v[128:131], v[204:207], v[92:95]
	v_mfma_f32_16x16x32_bf16 v[88:91], v[152:155], v[204:207], v[88:91]
	v_mfma_f32_16x16x32_bf16 v[76:79], v[128:131], v[212:215], v[76:79]
	v_mfma_f32_16x16x32_bf16 v[72:75], v[152:155], v[212:215], v[72:75]
	v_mfma_f32_16x16x32_bf16 v[124:127], v[132:135], v[192:195], v[124:127]
	v_mfma_f32_16x16x32_bf16 v[120:123], v[156:159], v[192:195], v[120:123]
	v_mfma_f32_16x16x32_bf16 v[108:111], v[132:135], v[200:203], v[108:111]
	v_mfma_f32_16x16x32_bf16 v[104:107], v[156:159], v[200:203], v[104:107]
	v_mfma_f32_16x16x32_bf16 v[92:95], v[132:135], v[208:211], v[92:95]
	v_mfma_f32_16x16x32_bf16 v[88:91], v[156:159], v[208:211], v[88:91]
	v_mfma_f32_16x16x32_bf16 v[76:79], v[132:135], v[216:219], v[76:79]
	v_mfma_f32_16x16x32_bf16 v[72:75], v[156:159], v[216:219], v[72:75]
	v_mfma_f32_16x16x32_bf16 v[116:119], v[160:163], v[188:191], v[116:119]
	v_mfma_f32_16x16x32_bf16 v[112:115], v[180:183], v[188:191], v[112:115]
	v_mfma_f32_16x16x32_bf16 v[100:103], v[160:163], v[196:199], v[100:103]
	v_mfma_f32_16x16x32_bf16 v[96:99], v[180:183], v[196:199], v[96:99]
	v_mfma_f32_16x16x32_bf16 v[84:87], v[160:163], v[204:207], v[84:87]
	v_mfma_f32_16x16x32_bf16 v[80:83], v[180:183], v[204:207], v[80:83]
	v_mfma_f32_16x16x32_bf16 v[68:71], v[160:163], v[212:215], v[68:71]
	v_mfma_f32_16x16x32_bf16 v[64:67], v[180:183], v[212:215], v[64:67]
	v_mfma_f32_16x16x32_bf16 v[116:119], v[164:167], v[192:195], v[116:119]
	v_mfma_f32_16x16x32_bf16 v[112:115], v[184:187], v[192:195], v[112:115]
	v_mfma_f32_16x16x32_bf16 v[100:103], v[164:167], v[200:203], v[100:103]
	v_mfma_f32_16x16x32_bf16 v[96:99], v[184:187], v[200:203], v[96:99]
	v_mfma_f32_16x16x32_bf16 v[84:87], v[164:167], v[208:211], v[84:87]
	v_mfma_f32_16x16x32_bf16 v[80:83], v[184:187], v[208:211], v[80:83]
	v_mfma_f32_16x16x32_bf16 v[68:71], v[164:167], v[216:219], v[68:71]
	v_mfma_f32_16x16x32_bf16 v[64:67], v[184:187], v[216:219], v[64:67]
	s_setprio 0
	s_barrier
	s_add_i32 s18, s69, s33
	s_add_u32 s98, s16, 0x80
	s_addc_u32 s99, s17, 0
	s_mov_b32 m0, s18
	ds_read_b128 v[188:191], v175 offset:49152
	ds_read_b128 v[192:195], v175 offset:50176
	ds_read_b128 v[196:199], v175 offset:51200
	ds_read_b128 v[200:203], v175 offset:52224
	ds_read_b128 v[204:207], v175 offset:53248
	ds_read_b128 v[208:211], v175 offset:54272
	ds_read_b128 v[212:215], v175 offset:55296
	ds_read_b128 v[216:219], v175 offset:56320
	global_load_lds_dwordx4 v138, s[98:99]
	s_add_i32 m0, s18, 0x2000
	s_add_u32 s16, s16, 0x80080
	s_addc_u32 s17, s17, 0
	s_add_i32 s18, s70, s33
	global_load_lds_dwordx4 v142, s[98:99]
	s_mov_b32 m0, s18
	s_nop 0
	global_load_lds_dwordx4 v138, s[16:17]
	s_add_i32 m0, s18, 0x2000
	s_nop 0
	global_load_lds_dwordx4 v142, s[16:17]
	s_waitcnt vmcnt(6)
	s_waitcnt lgkmcnt(0)
	s_barrier
	s_setprio 1
	v_mfma_f32_16x16x32_bf16 v[60:63], v[128:131], v[188:191], v[60:63]
	v_mfma_f32_16x16x32_bf16 v[56:59], v[152:155], v[188:191], v[56:59]
	v_mfma_f32_16x16x32_bf16 v[44:47], v[128:131], v[196:199], v[44:47]
	v_mfma_f32_16x16x32_bf16 v[40:43], v[152:155], v[196:199], v[40:43]
	v_mfma_f32_16x16x32_bf16 v[28:31], v[128:131], v[204:207], v[28:31]
	v_mfma_f32_16x16x32_bf16 v[24:27], v[152:155], v[204:207], v[24:27]
	v_mfma_f32_16x16x32_bf16 v[12:15], v[128:131], v[212:215], v[12:15]
	v_mfma_f32_16x16x32_bf16 v[8:11], v[152:155], v[212:215], v[8:11]
	v_mfma_f32_16x16x32_bf16 v[60:63], v[132:135], v[192:195], v[60:63]
	v_mfma_f32_16x16x32_bf16 v[56:59], v[156:159], v[192:195], v[56:59]
	v_mfma_f32_16x16x32_bf16 v[44:47], v[132:135], v[200:203], v[44:47]
	v_mfma_f32_16x16x32_bf16 v[40:43], v[156:159], v[200:203], v[40:43]
	v_mfma_f32_16x16x32_bf16 v[28:31], v[132:135], v[208:211], v[28:31]
	v_mfma_f32_16x16x32_bf16 v[24:27], v[156:159], v[208:211], v[24:27]
	v_mfma_f32_16x16x32_bf16 v[12:15], v[132:135], v[216:219], v[12:15]
	v_mfma_f32_16x16x32_bf16 v[8:11], v[156:159], v[216:219], v[8:11]
	v_mfma_f32_16x16x32_bf16 v[52:55], v[160:163], v[188:191], v[52:55]
	v_mfma_f32_16x16x32_bf16 v[48:51], v[180:183], v[188:191], v[48:51]
	v_mfma_f32_16x16x32_bf16 v[36:39], v[160:163], v[196:199], v[36:39]
	v_mfma_f32_16x16x32_bf16 v[32:35], v[180:183], v[196:199], v[32:35]
	v_mfma_f32_16x16x32_bf16 v[20:23], v[160:163], v[204:207], v[20:23]
	v_mfma_f32_16x16x32_bf16 v[16:19], v[180:183], v[204:207], v[16:19]
	v_mfma_f32_16x16x32_bf16 v[4:7], v[160:163], v[212:215], v[4:7]
	v_mfma_f32_16x16x32_bf16 v[0:3], v[180:183], v[212:215], v[0:3]
	v_mfma_f32_16x16x32_bf16 v[52:55], v[164:167], v[192:195], v[52:55]
	v_mfma_f32_16x16x32_bf16 v[48:51], v[184:187], v[192:195], v[48:51]
	v_mfma_f32_16x16x32_bf16 v[36:39], v[164:167], v[200:203], v[36:39]
	v_mfma_f32_16x16x32_bf16 v[32:35], v[184:187], v[200:203], v[32:35]
	v_mfma_f32_16x16x32_bf16 v[20:23], v[164:167], v[208:211], v[20:23]
	v_mfma_f32_16x16x32_bf16 v[16:19], v[184:187], v[208:211], v[16:19]
	v_mfma_f32_16x16x32_bf16 v[4:7], v[164:167], v[216:219], v[4:7]
	v_mfma_f32_16x16x32_bf16 v[0:3], v[184:187], v[216:219], v[0:3]
	s_setprio 0
	s_barrier
	s_add_i32 s61, s61, 2
	s_add_u32 s12, s12, 0x100
	s_addc_u32 s13, s13, 0
	s_add_u32 s37, s37, 0x100
	s_addc_u32 s60, s60, 0
	s_cmp_gt_u32 s61, 29
	s_cbranch_scc0 .LBB0_187
	s_and_b64 vcc, exec, s[96:97]
	s_cbranch_vccz .LBB0_190
	s_barrier

; #define PG8_STAGE(bufoff, gbase, voff) do { _Pragma("unroll") for (int _i = 0; _i < 2; ++_i) \
;         __builtin_amdgcn_global_load_lds((const unsigned*)((const char*)(gbase) + (voff)[_i]), (PG8_LAS unsigned*)(lds + (bufoff) + ldsw + _i * 8192), 16, 0, 0); } while (0)
; #define PG8_LDA(dst, b, h) do { _Pragma("unroll") for (int m = 0; m < 4; ++m) _Pragma("unroll") for (int k = 0; k < 2; ++k) dst[m][k] = *(const PG8_LAS bf16x8*)(lds + PG8_SA(b, h) + aoff + m * 2048 + k * 1024); } while (0)
; #define PG8_LDB(dst, b, h) do { _Pragma("unroll") for (int n = 0; n < 2; ++n) _Pragma("unroll") for (int k = 0; k < 2; ++k) dst[n][k] = *(const PG8_LAS bf16x8*)(lds + PG8_SB(b, h) + boff + n * 2048 + k * 1024); } while (0)
; #define PG8_WAIT_V(n) asm volatile("s_waitcnt vmcnt(" #n ")" ::: "memory")
; #define PG8_WAIT_L(n) asm volatile("s_waitcnt lgkmcnt(" #n ")" ::: "memory")
; #define PG8_BAR __builtin_amdgcn_s_barrier()
; #define PG8_SCHED __builtin_amdgcn_sched_barrier(0)
; template <class Epi, class Sched, bool ALIGN_EPI = false, bool SP2 = false>
; __device__ __forceinline__ void gemm_phase(PG8_LAS unsigned char* lds, const Gemm g, const Sched& S, const Epi& E) {
;     ...
;         const char* nA = has_next ? (const char*)g.A + (size_t)nxt.pm * tstepA : cA; const char* nB = has_next ? (const char*)g.Bt + (size_t)nxt.pn * tstepB : cB;
;         for (int t = 0; t < nt; t += 2) {
;             const bool last = (t == nt - 2);
;             if constexpr (Epi::HAS_MID) { if (t == E.mid_t) E.mid(acc, cur, wr, wc, fr, fq); }
;             const char* a1 = cA + (size_t)(t + 1) * kstep;
;             const char* a2 = last ? nA : cA + (size_t)(t + 2) * kstep; const char* b2 = last ? nB : cB + (size_t)(t + 2) * kstep;
;             const char* a3 = a2 + kstep; const char* b3 = b2 + kstep;
;             if (last && has_next) S.a_ready(nxt);
;             if constexpr (SP2) {
;             PG8_LDB(B0, 0, 0); PG8_LDB(B1, 0, 1); PG8_SCHED; PG8_LDA(At, 0, 0); PG8_STAGE(PG8_SA(1, 1), a1 + hstepA, voffA);
;             PG8_WAIT_V(8); PG8_WAIT_L(0); PG8_BAR; PG8_MMA(0, 0, At, B0); PG8_MMA(0, 1, At, B1); PG8_BAR; PG8_SCHED;
;             PG8_LDA(At, 0, 1); PG8_STAGE(PG8_SB(0, 0), b2, voffB); PG8_STAGE(PG8_SB(0, 1), b2 + hstepB, voffB); PG8_STAGE(PG8_SA(0, 0), a2, voffA);
;             PG8_WAIT_V(8); PG8_WAIT_L(0); PG8_BAR; PG8_MMA(1, 0, At, B0); PG8_MMA(1, 1, At, B1); PG8_BAR; PG8_SCHED;
.LBB0_519:
	ds_read_b128 v[128:131], v169
	ds_read_b128 v[132:135], v169 offset:1024
	ds_read_b128 v[148:151], v169 offset:2048
	ds_read_b128 v[152:155], v169 offset:3072
	ds_read_b128 v[156:159], v170
	ds_read_b128 v[160:163], v170 offset:1024
	ds_read_b128 v[174:177], v170 offset:2048
	ds_read_b128 v[178:181], v170 offset:3072
	s_add_u32 s18, s16, 0xfff80080
	s_addc_u32 s19, s17, -1
	s_cmp_eq_u32 s69, 28
	s_cselect_b32 s43, s13, s19
	s_cselect_b32 s42, s39, s18
	s_cselect_b32 s19, s37, s68
	s_cselect_b32 s18, s66, s67
	v_lshl_add_u64 v[164:165], s[16:17], 0, v[144:145]
	s_add_i32 m0, s6, 0xc000
	ds_read_b128 v[182:185], v171
	ds_read_b128 v[186:189], v171 offset:1024
	ds_read_b128 v[190:193], v171 offset:2048
	ds_read_b128 v[194:197], v171 offset:3072
	ds_read_b128 v[198:201], v171 offset:4096
	ds_read_b128 v[202:205], v171 offset:5120
	ds_read_b128 v[206:209], v171 offset:6144
	ds_read_b128 v[210:213], v171 offset:7168
	global_load_lds_dwordx4 v[164:165], off
	v_lshl_add_u64 v[164:165], s[16:17], 0, v[146:147]
	s_add_i32 m0, s6, 0xe000
	s_nop 0
	global_load_lds_dwordx4 v[164:165], off
	s_waitcnt vmcnt(8)
	s_waitcnt lgkmcnt(0)
	s_barrier
	s_setprio 1
	s_waitcnt lgkmcnt(0)
	v_mfma_f32_16x16x32_bf16 v[124:127], v[128:131], v[182:185], v[124:127]
	v_mfma_f32_16x16x32_bf16 v[120:123], v[148:151], v[182:185], v[120:123]
	v_mfma_f32_16x16x32_bf16 v[108:111], v[128:131], v[190:193], v[108:111]
	v_mfma_f32_16x16x32_bf16 v[104:107], v[148:151], v[190:193], v[104:107]
	v_mfma_f32_16x16x32_bf16 v[92:95], v[128:131], v[198:201], v[92:95]
	v_mfma_f32_16x16x32_bf16 v[88:91], v[148:151], v[198:201], v[88:91]
	v_mfma_f32_16x16x32_bf16 v[76:79], v[128:131], v[206:209], v[76:79]
	v_mfma_f32_16x16x32_bf16 v[72:75], v[148:151], v[206:209], v[72:75]
	v_mfma_f32_16x16x32_bf16 v[124:127], v[132:135], v[186:189], v[124:127]
	v_mfma_f32_16x16x32_bf16 v[120:123], v[152:155], v[186:189], v[120:123]
	v_mfma_f32_16x16x32_bf16 v[108:111], v[132:135], v[194:197], v[108:111]
	v_mfma_f32_16x16x32_bf16 v[104:107], v[152:155], v[194:197], v[104:107]
	v_mfma_f32_16x16x32_bf16 v[92:95], v[132:135], v[202:205], v[92:95]
	v_mfma_f32_16x16x32_bf16 v[88:91], v[152:155], v[202:205], v[88:91]
	v_mfma_f32_16x16x32_bf16 v[76:79], v[132:135], v[210:213], v[76:79]
	v_mfma_f32_16x16x32_bf16 v[72:75], v[152:155], v[210:213], v[72:75]
	v_mfma_f32_16x16x32_bf16 v[116:119], v[156:159], v[182:185], v[116:119]
	v_mfma_f32_16x16x32_bf16 v[112:115], v[174:177], v[182:185], v[112:115]
	v_mfma_f32_16x16x32_bf16 v[100:103], v[156:159], v[190:193], v[100:103]
	v_mfma_f32_16x16x32_bf16 v[96:99], v[174:177], v[190:193], v[96:99]
	v_mfma_f32_16x16x32_bf16 v[84:87], v[156:159], v[198:201], v[84:87]
	v_mfma_f32_16x16x32_bf16 v[80:83], v[174:177], v[198:201], v[80:83]
	v_mfma_f32_16x16x32_bf16 v[68:71], v[156:159], v[206:209], v[68:71]
	v_mfma_f32_16x16x32_bf16 v[64:67], v[174:177], v[206:209], v[64:67]
	v_mfma_f32_16x16x32_bf16 v[116:119], v[160:163], v[186:189], v[116:119]
	v_mfma_f32_16x16x32_bf16 v[112:115], v[178:181], v[186:189], v[112:115]
	v_mfma_f32_16x16x32_bf16 v[100:103], v[160:163], v[194:197], v[100:103]
	v_mfma_f32_16x16x32_bf16 v[96:99], v[178:181], v[194:197], v[96:99]
	v_mfma_f32_16x16x32_bf16 v[84:87], v[160:163], v[202:205], v[84:87]
	v_mfma_f32_16x16x32_bf16 v[80:83], v[178:181], v[202:205], v[80:83]
	v_mfma_f32_16x16x32_bf16 v[68:71], v[160:163], v[210:213], v[68:71]
	v_mfma_f32_16x16x32_bf16 v[64:67], v[178:181], v[210:213], v[64:67]
	s_setprio 0
	s_barrier
	s_add_i32 s70, s59, s5
	v_lshl_add_u64 v[164:165], s[18:19], 0, v[138:139]
	s_mov_b32 m0, s70
	ds_read_b128 v[182:185], v171 offset:16384
	ds_read_b128 v[186:189], v171 offset:17408
	ds_read_b128 v[190:193], v171 offset:18432
	ds_read_b128 v[194:197], v171 offset:19456
	ds_read_b128 v[198:201], v171 offset:20480
	ds_read_b128 v[202:205], v171 offset:21504
	ds_read_b128 v[206:209], v171 offset:22528
	ds_read_b128 v[210:213], v171 offset:23552
	global_load_lds_dwordx4 v[164:165], off
	s_add_i32 m0, s70, 0x2000
	s_add_u32 s70, s18, 0x80000
	v_lshl_add_u64 v[214:215], s[18:19], 0, v[142:143]
	s_addc_u32 s71, s19, 0
	s_add_i32 s74, s62, s5
	global_load_lds_dwordx4 v[214:215], off
	v_lshl_add_u64 v[216:217], s[70:71], 0, v[138:139]
	s_mov_b32 m0, s74
	v_lshl_add_u64 v[218:219], s[42:43], 0, v[140:141]
	global_load_lds_dwordx4 v[216:217], off
	v_lshl_add_u64 v[216:217], s[70:71], 0, v[142:143]
	s_add_i32 m0, s74, 0x2000
	s_nop 0
	global_load_lds_dwordx4 v[216:217], off
	v_lshl_add_u64 v[216:217], s[42:43], 0, v[136:137]
	s_mov_b32 m0, s6
	s_nop 0
	global_load_lds_dwordx4 v[216:217], off
	s_mov_b32 m0, s7
	s_nop 0
	global_load_lds_dwordx4 v[218:219], off
	s_waitcnt vmcnt(8)
	s_waitcnt lgkmcnt(0)
	s_barrier
; #define PG8_STAGE(bufoff, gbase, voff) do { _Pragma("unroll") for (int _i = 0; _i < 2; ++_i) \
;         __builtin_amdgcn_global_load_lds((const unsigned*)((const char*)(gbase) + (voff)[_i]), (PG8_LAS unsigned*)(lds + (bufoff) + ldsw + _i * 8192), 16, 0, 0); } while (0)
; #define PG8_LDA(dst, b, h) do { _Pragma("unroll") for (int m = 0; m < 4; ++m) _Pragma("unroll") for (int k = 0; k < 2; ++k) dst[m][k] = *(const PG8_LAS bf16x8*)(lds + PG8_SA(b, h) + aoff + m * 2048 + k * 1024); } while (0)
; #define PG8_LDB(dst, b, h) do { _Pragma("unroll") for (int n = 0; n < 2; ++n) _Pragma("unroll") for (int k = 0; k < 2; ++k) dst[n][k] = *(const PG8_LAS bf16x8*)(lds + PG8_SB(b, h) + boff + n * 2048 + k * 1024); } while (0)
; #define PG8_MMA(ai, bj, At, Bt) do { __builtin_amdgcn_s_setprio(1); _Pragma("unroll") for (int m = 0; m < 4; ++m) _Pragma("unroll") for (int n = 0; n < 2; ++n) _Pragma("unroll") for (int k = 0; k < 2; ++k) \
;         acc[ai][bj][m][n] = __builtin_amdgcn_mfma_f32_16x16x32_bf16(Bt[n][k], At[m][k], acc[ai][bj][m][n], 0, 0, 0); __builtin_amdgcn_s_setprio(0); } while (0)
; #define PG8_WAIT_V(n) asm volatile("s_waitcnt vmcnt(" #n ")" ::: "memory")
; #define PG8_WAIT_L(n) asm volatile("s_waitcnt lgkmcnt(" #n ")" ::: "memory")
; #define PG8_BAR __builtin_amdgcn_s_barrier()
; template <class Epi, class Sched, bool ALIGN_EPI = false, bool SP2 = false>
; __device__ __forceinline__ void gemm_phase(PG8_LAS unsigned char* lds, const Gemm g, const Sched& S, const Epi& E) {
;     ...
;             PG8_WAIT_V(8); PG8_WAIT_L(0); PG8_BAR; PG8_MMA(0, 0, At, B0); PG8_MMA(0, 1, At, B1); PG8_BAR; PG8_SCHED;
;             PG8_LDA(At, 0, 1); PG8_STAGE(PG8_SB(0, 0), b2, voffB); PG8_STAGE(PG8_SB(0, 1), b2 + hstepB, voffB); PG8_STAGE(PG8_SA(0, 0), a2, voffA);
;             PG8_WAIT_V(8); PG8_WAIT_L(0); PG8_BAR; PG8_MMA(1, 0, At, B0); PG8_MMA(1, 1, At, B1); PG8_BAR; PG8_SCHED;
;             PG8_LDB(B0, 1, 0); PG8_LDB(B1, 1, 1); PG8_SCHED; PG8_LDA(At, 1, 0); PG8_STAGE(PG8_SA(0, 1), a2 + hstepA, voffA);
;             PG8_WAIT_V(8); PG8_WAIT_L(0); PG8_BAR; PG8_MMA(0, 0, At, B0); PG8_MMA(0, 1, At, B1); PG8_BAR; PG8_SCHED;
;             PG8_LDA(At, 1, 1); PG8_STAGE(PG8_SB(1, 0), b3, voffB); PG8_STAGE(PG8_SB(1, 1), b3 + hstepB, voffB); PG8_STAGE(PG8_SA(1, 0), a3, voffA);
;             PG8_WAIT_V(8); PG8_WAIT_L(0); PG8_BAR; PG8_MMA(1, 0, At, B0); PG8_MMA(1, 1, At, B1); PG8_BAR; PG8_SCHED;
	s_setprio 1
	s_waitcnt lgkmcnt(0)
	v_mfma_f32_16x16x32_bf16 v[60:63], v[128:131], v[182:185], v[60:63]
	v_mfma_f32_16x16x32_bf16 v[56:59], v[148:151], v[182:185], v[56:59]
	v_mfma_f32_16x16x32_bf16 v[44:47], v[128:131], v[190:193], v[44:47]
	v_mfma_f32_16x16x32_bf16 v[40:43], v[148:151], v[190:193], v[40:43]
	v_mfma_f32_16x16x32_bf16 v[28:31], v[128:131], v[198:201], v[28:31]
	v_mfma_f32_16x16x32_bf16 v[24:27], v[148:151], v[198:201], v[24:27]
	v_mfma_f32_16x16x32_bf16 v[12:15], v[128:131], v[206:209], v[12:15]
	v_mfma_f32_16x16x32_bf16 v[8:11], v[148:151], v[206:209], v[8:11]
	v_mfma_f32_16x16x32_bf16 v[60:63], v[132:135], v[186:189], v[60:63]
	v_mfma_f32_16x16x32_bf16 v[56:59], v[152:155], v[186:189], v[56:59]
	v_mfma_f32_16x16x32_bf16 v[44:47], v[132:135], v[194:197], v[44:47]
	v_mfma_f32_16x16x32_bf16 v[40:43], v[152:155], v[194:197], v[40:43]
	v_mfma_f32_16x16x32_bf16 v[28:31], v[132:135], v[202:205], v[28:31]
	v_mfma_f32_16x16x32_bf16 v[24:27], v[152:155], v[202:205], v[24:27]
	v_mfma_f32_16x16x32_bf16 v[12:15], v[132:135], v[210:213], v[12:15]
	v_mfma_f32_16x16x32_bf16 v[8:11], v[152:155], v[210:213], v[8:11]
	v_mfma_f32_16x16x32_bf16 v[52:55], v[156:159], v[182:185], v[52:55]
	v_mfma_f32_16x16x32_bf16 v[48:51], v[174:177], v[182:185], v[48:51]
	v_mfma_f32_16x16x32_bf16 v[36:39], v[156:159], v[190:193], v[36:39]
	v_mfma_f32_16x16x32_bf16 v[32:35], v[174:177], v[190:193], v[32:35]
	v_mfma_f32_16x16x32_bf16 v[20:23], v[156:159], v[198:201], v[20:23]
	v_mfma_f32_16x16x32_bf16 v[16:19], v[174:177], v[198:201], v[16:19]
	v_mfma_f32_16x16x32_bf16 v[4:7], v[156:159], v[206:209], v[4:7]
	v_mfma_f32_16x16x32_bf16 v[0:3], v[174:177], v[206:209], v[0:3]
	v_mfma_f32_16x16x32_bf16 v[52:55], v[160:163], v[186:189], v[52:55]
	v_mfma_f32_16x16x32_bf16 v[48:51], v[178:181], v[186:189], v[48:51]
	v_mfma_f32_16x16x32_bf16 v[36:39], v[160:163], v[194:197], v[36:39]
	v_mfma_f32_16x16x32_bf16 v[32:35], v[178:181], v[194:197], v[32:35]
	v_mfma_f32_16x16x32_bf16 v[20:23], v[160:163], v[202:205], v[20:23]
	v_mfma_f32_16x16x32_bf16 v[16:19], v[178:181], v[202:205], v[16:19]
	v_mfma_f32_16x16x32_bf16 v[4:7], v[160:163], v[210:213], v[4:7]
	v_mfma_f32_16x16x32_bf16 v[0:3], v[178:181], v[210:213], v[0:3]
	s_setprio 0
	s_barrier
	s_add_i32 s70, 0, 0x18000
	s_add_i32 s71, 0, 0x1c000
	v_add_u32_e32 v152, s70, v168
	v_add_u32_e32 v173, s71, v168
	ds_read_b128 v[128:131], v152
	ds_read_b128 v[132:135], v152 offset:1024
	ds_read_b128 v[148:151], v152 offset:2048
	ds_read_b128 v[152:155], v152 offset:3072
	ds_read_b128 v[156:159], v173
	ds_read_b128 v[160:163], v173 offset:1024
	ds_read_b128 v[174:177], v173 offset:2048
	ds_read_b128 v[178:181], v173 offset:3072
	s_add_u32 s42, s42, 0x80000
	s_addc_u32 s43, s43, 0
	s_mov_b32 m0, s22
	v_lshl_add_u64 v[220:221], s[42:43], 0, v[136:137]
	ds_read_b128 v[182:185], v171 offset:32768
	ds_read_b128 v[186:189], v171 offset:33792
	ds_read_b128 v[190:193], v171 offset:34816
	ds_read_b128 v[194:197], v171 offset:35840
	ds_read_b128 v[198:201], v171 offset:36864
	ds_read_b128 v[202:205], v171 offset:37888
	ds_read_b128 v[206:209], v171 offset:38912
	ds_read_b128 v[210:213], v171 offset:39936
	global_load_lds_dwordx4 v[220:221], off
	v_lshl_add_u64 v[220:221], s[42:43], 0, v[140:141]
	s_mov_b32 m0, s23
	s_nop 0
	global_load_lds_dwordx4 v[220:221], off
	s_waitcnt vmcnt(8)
	s_waitcnt lgkmcnt(0)
	s_barrier
	s_setprio 1
	s_waitcnt lgkmcnt(0)
	v_mfma_f32_16x16x32_bf16 v[124:127], v[128:131], v[182:185], v[124:127]
	v_mfma_f32_16x16x32_bf16 v[120:123], v[148:151], v[182:185], v[120:123]
	v_mfma_f32_16x16x32_bf16 v[108:111], v[128:131], v[190:193], v[108:111]
	v_mfma_f32_16x16x32_bf16 v[104:107], v[148:151], v[190:193], v[104:107]
	v_mfma_f32_16x16x32_bf16 v[92:95], v[128:131], v[198:201], v[92:95]
	v_mfma_f32_16x16x32_bf16 v[88:91], v[148:151], v[198:201], v[88:91]
	v_mfma_f32_16x16x32_bf16 v[76:79], v[128:131], v[206:209], v[76:79]
	v_mfma_f32_16x16x32_bf16 v[72:75], v[148:151], v[206:209], v[72:75]
	v_mfma_f32_16x16x32_bf16 v[124:127], v[132:135], v[186:189], v[124:127]
	v_mfma_f32_16x16x32_bf16 v[120:123], v[152:155], v[186:189], v[120:123]
	v_mfma_f32_16x16x32_bf16 v[108:111], v[132:135], v[194:197], v[108:111]
	v_mfma_f32_16x16x32_bf16 v[104:107], v[152:155], v[194:197], v[104:107]
	v_mfma_f32_16x16x32_bf16 v[92:95], v[132:135], v[202:205], v[92:95]
	v_mfma_f32_16x16x32_bf16 v[88:91], v[152:155], v[202:205], v[88:91]
	v_mfma_f32_16x16x32_bf16 v[76:79], v[132:135], v[210:213], v[76:79]
	v_mfma_f32_16x16x32_bf16 v[72:75], v[152:155], v[210:213], v[72:75]
	v_mfma_f32_16x16x32_bf16 v[116:119], v[156:159], v[182:185], v[116:119]
	v_mfma_f32_16x16x32_bf16 v[112:115], v[174:177], v[182:185], v[112:115]
	v_mfma_f32_16x16x32_bf16 v[100:103], v[156:159], v[190:193], v[100:103]
	v_mfma_f32_16x16x32_bf16 v[96:99], v[174:177], v[190:193], v[96:99]
	v_mfma_f32_16x16x32_bf16 v[84:87], v[156:159], v[198:201], v[84:87]
	v_mfma_f32_16x16x32_bf16 v[80:83], v[174:177], v[198:201], v[80:83]
	v_mfma_f32_16x16x32_bf16 v[68:71], v[156:159], v[206:209], v[68:71]
	v_mfma_f32_16x16x32_bf16 v[64:67], v[174:177], v[206:209], v[64:67]
	v_mfma_f32_16x16x32_bf16 v[116:119], v[160:163], v[186:189], v[116:119]
	v_mfma_f32_16x16x32_bf16 v[112:115], v[178:181], v[186:189], v[112:115]
	v_mfma_f32_16x16x32_bf16 v[100:103], v[160:163], v[194:197], v[100:103]
	v_mfma_f32_16x16x32_bf16 v[96:99], v[178:181], v[194:197], v[96:99]
	v_mfma_f32_16x16x32_bf16 v[84:87], v[160:163], v[202:205], v[84:87]
	v_mfma_f32_16x16x32_bf16 v[80:83], v[178:181], v[202:205], v[80:83]
	v_mfma_f32_16x16x32_bf16 v[68:71], v[160:163], v[210:213], v[68:71]
	v_mfma_f32_16x16x32_bf16 v[64:67], v[178:181], v[210:213], v[64:67]
	s_setprio 0
	s_barrier
; #define PG8_STAGE(bufoff, gbase, voff) do { _Pragma("unroll") for (int _i = 0; _i < 2; ++_i) \
;         __builtin_amdgcn_global_load_lds((const unsigned*)((const char*)(gbase) + (voff)[_i]), (PG8_LAS unsigned*)(lds + (bufoff) + ldsw + _i * 8192), 16, 0, 0); } while (0)
; #define PG8_LDA(dst, b, h) do { _Pragma("unroll") for (int m = 0; m < 4; ++m) _Pragma("unroll") for (int k = 0; k < 2; ++k) dst[m][k] = *(const PG8_LAS bf16x8*)(lds + PG8_SA(b, h) + aoff + m * 2048 + k * 1024); } while (0)
; #define PG8_LDB(dst, b, h) do { _Pragma("unroll") for (int n = 0; n < 2; ++n) _Pragma("unroll") for (int k = 0; k < 2; ++k) dst[n][k] = *(const PG8_LAS bf16x8*)(lds + PG8_SB(b, h) + boff + n * 2048 + k * 1024); } while (0)
; #define PG8_MMA(ai, bj, At, Bt) do { __builtin_amdgcn_s_setprio(1); _Pragma("unroll") for (int m = 0; m < 4; ++m) _Pragma("unroll") for (int n = 0; n < 2; ++n) _Pragma("unroll") for (int k = 0; k < 2; ++k) \
;         acc[ai][bj][m][n] = __builtin_amdgcn_mfma_f32_16x16x32_bf16(Bt[n][k], At[m][k], acc[ai][bj][m][n], 0, 0, 0); __builtin_amdgcn_s_setprio(0); } while (0)
; #define PG8_WAIT_V(n) asm volatile("s_waitcnt vmcnt(" #n ")" ::: "memory")
; #define PG8_WAIT_L(n) asm volatile("s_waitcnt lgkmcnt(" #n ")" ::: "memory")
; #define PG8_BAR __builtin_amdgcn_s_barrier()
; #define PG8_SCHED __builtin_amdgcn_sched_barrier(0)
; template <class Epi, class Sched, bool ALIGN_EPI = false, bool SP2 = false>
; __device__ __forceinline__ void gemm_phase(PG8_LAS unsigned char* lds, const Gemm g, const Sched& S, const Epi& E) {
;     ...
;             PG8_LDB(B0, 1, 0); PG8_LDB(B1, 1, 1); PG8_SCHED; PG8_LDA(At, 1, 0); PG8_STAGE(PG8_SA(0, 1), a2 + hstepA, voffA);
;             PG8_WAIT_V(8); PG8_WAIT_L(0); PG8_BAR; PG8_MMA(0, 0, At, B0); PG8_MMA(0, 1, At, B1); PG8_BAR; PG8_SCHED;
;             PG8_LDA(At, 1, 1); PG8_STAGE(PG8_SB(1, 0), b3, voffB); PG8_STAGE(PG8_SB(1, 1), b3 + hstepB, voffB); PG8_STAGE(PG8_SA(1, 0), a3, voffA);
;             PG8_WAIT_V(8); PG8_WAIT_L(0); PG8_BAR; PG8_MMA(1, 0, At, B0); PG8_MMA(1, 1, At, B1); PG8_BAR; PG8_SCHED;
	s_add_i32 s42, s70, s5
	v_lshl_add_u64 v[164:165], v[164:165], 0, s[26:27]
	s_mov_b32 m0, s42
	ds_read_b128 v[182:185], v171 offset:49152
	ds_read_b128 v[186:189], v171 offset:50176
	ds_read_b128 v[190:193], v171 offset:51200
	ds_read_b128 v[194:197], v171 offset:52224
	ds_read_b128 v[198:201], v171 offset:53248
	ds_read_b128 v[202:205], v171 offset:54272
	ds_read_b128 v[206:209], v171 offset:55296
	ds_read_b128 v[210:213], v171 offset:56320
	global_load_lds_dwordx4 v[164:165], off
	s_add_i32 m0, s42, 0x2000
	s_add_u32 s18, s18, 0x80080
	v_lshl_add_u64 v[164:165], v[214:215], 0, s[26:27]
	s_addc_u32 s19, s19, 0
	s_add_i32 s42, s71, s5
	global_load_lds_dwordx4 v[164:165], off
	v_lshl_add_u64 v[164:165], s[18:19], 0, v[138:139]
	s_mov_b32 m0, s42
	s_nop 0
	global_load_lds_dwordx4 v[164:165], off
	v_lshl_add_u64 v[164:165], s[18:19], 0, v[142:143]
	s_add_i32 m0, s42, 0x2000
	s_nop 0
	global_load_lds_dwordx4 v[164:165], off
	v_lshl_add_u64 v[164:165], v[216:217], 0, s[26:27]
	s_mov_b32 m0, s47
	s_nop 0
	global_load_lds_dwordx4 v[164:165], off
	v_lshl_add_u64 v[164:165], v[218:219], 0, s[26:27]
	s_mov_b32 m0, s56
	s_nop 0
	global_load_lds_dwordx4 v[164:165], off
	s_waitcnt vmcnt(8)
	s_waitcnt lgkmcnt(0)
	s_barrier
	s_setprio 1
	s_waitcnt lgkmcnt(0)
	v_mfma_f32_16x16x32_bf16 v[60:63], v[128:131], v[182:185], v[60:63]
	v_mfma_f32_16x16x32_bf16 v[56:59], v[148:151], v[182:185], v[56:59]
	v_mfma_f32_16x16x32_bf16 v[44:47], v[128:131], v[190:193], v[44:47]
	v_mfma_f32_16x16x32_bf16 v[40:43], v[148:151], v[190:193], v[40:43]
	v_mfma_f32_16x16x32_bf16 v[28:31], v[128:131], v[198:201], v[28:31]
	v_mfma_f32_16x16x32_bf16 v[24:27], v[148:151], v[198:201], v[24:27]
	v_mfma_f32_16x16x32_bf16 v[12:15], v[128:131], v[206:209], v[12:15]
	v_mfma_f32_16x16x32_bf16 v[8:11], v[148:151], v[206:209], v[8:11]
	v_mfma_f32_16x16x32_bf16 v[60:63], v[132:135], v[186:189], v[60:63]
	v_mfma_f32_16x16x32_bf16 v[56:59], v[152:155], v[186:189], v[56:59]
	v_mfma_f32_16x16x32_bf16 v[44:47], v[132:135], v[194:197], v[44:47]
	v_mfma_f32_16x16x32_bf16 v[40:43], v[152:155], v[194:197], v[40:43]
	v_mfma_f32_16x16x32_bf16 v[28:31], v[132:135], v[202:205], v[28:31]
	v_mfma_f32_16x16x32_bf16 v[24:27], v[152:155], v[202:205], v[24:27]
	v_mfma_f32_16x16x32_bf16 v[12:15], v[132:135], v[210:213], v[12:15]
	v_mfma_f32_16x16x32_bf16 v[8:11], v[152:155], v[210:213], v[8:11]
	v_mfma_f32_16x16x32_bf16 v[52:55], v[156:159], v[182:185], v[52:55]
	v_mfma_f32_16x16x32_bf16 v[48:51], v[174:177], v[182:185], v[48:51]
	v_mfma_f32_16x16x32_bf16 v[36:39], v[156:159], v[190:193], v[36:39]
	v_mfma_f32_16x16x32_bf16 v[32:35], v[174:177], v[190:193], v[32:35]
	v_mfma_f32_16x16x32_bf16 v[20:23], v[156:159], v[198:201], v[20:23]
	v_mfma_f32_16x16x32_bf16 v[16:19], v[174:177], v[198:201], v[16:19]
	v_mfma_f32_16x16x32_bf16 v[4:7], v[156:159], v[206:209], v[4:7]
	v_mfma_f32_16x16x32_bf16 v[0:3], v[174:177], v[206:209], v[0:3]
	v_mfma_f32_16x16x32_bf16 v[52:55], v[160:163], v[186:189], v[52:55]
	v_mfma_f32_16x16x32_bf16 v[48:51], v[178:181], v[186:189], v[48:51]
	v_mfma_f32_16x16x32_bf16 v[36:39], v[160:163], v[194:197], v[36:39]
	v_mfma_f32_16x16x32_bf16 v[32:35], v[178:181], v[194:197], v[32:35]
	v_mfma_f32_16x16x32_bf16 v[20:23], v[160:163], v[202:205], v[20:23]
	v_mfma_f32_16x16x32_bf16 v[16:19], v[178:181], v[202:205], v[16:19]
	v_mfma_f32_16x16x32_bf16 v[4:7], v[160:163], v[210:213], v[4:7]
	v_mfma_f32_16x16x32_bf16 v[0:3], v[178:181], v[210:213], v[0:3]
	s_setprio 0
	s_barrier
	s_add_i32 s69, s69, 2
	s_add_u32 s16, s16, 0x100
	s_addc_u32 s17, s17, 0
	s_add_u32 s67, s67, 0x100
	s_addc_u32 s68, s68, 0
	s_cmp_gt_u32 s69, 29
	s_cbranch_scc0 .LBB0_519
	s_and_b64 vcc, exec, s[28:29]
	s_cbranch_vccz .LBB0_522
	s_barrier

; template <class Epi, class Sched, bool ALIGN_EPI = false, bool SP2 = false>
; __device__ __forceinline__ void gemm_phase(PG8_LAS unsigned char* lds, const Gemm g, const Sched& S, const Epi& E) {
;     ...
;     const int aoff = lds_byte(wr * 64 + fr, fq * 8), boff = lds_byte(wc * 32 + fr, fq * 8);
;     ...
;     Unit cur, nxt; int ui = 0;
;     if (!S.next(0, cur)) return;
;     f32x4 acc[2][2][4][2];
; #pragma unroll
;     for (int a = 0; a < 2; ++a)
; #pragma unroll
;         for (int b = 0; b < 2; ++b)
; #pragma unroll
;             for (int m = 0; m < 4; ++m)
; #pragma unroll
;                 for (int n = 0; n < 2; ++n) acc[a][b][m][n] = (f32x4){0.f, 0.f, 0.f, 0.f};
;     bf16x8 At[4][2], B0[2][2], B1[2][2];
;     const char* cA = (const char*)g.A + (size_t)cur.pm * tstepA; const char* cB = (const char*)g.Bt + (size_t)cur.pn * tstepB;
;     S.a_ready(cur);
;     if constexpr (SP2) {
;         PG8_STAGE(PG8_SB(0, 0), cB, voffB); PG8_STAGE(PG8_SB(0, 1), cB + hstepB, voffB); PG8_STAGE(PG8_SA(0, 0), cA, voffA); PG8_STAGE(PG8_SA(0, 1), cA + hstepA, voffA);
;         if (wr == 1) PG8_BAR;
;         PG8_WAIT_V(2); PG8_BAR;
;         PG8_STAGE(PG8_SB(1, 0), cB + kstep, voffB); PG8_STAGE(PG8_SA(1, 0), cA + kstep, voffA); PG8_STAGE(PG8_SB(1, 1), cB + hstepB + kstep, voffB);
;         PG8_WAIT_V(6); PG8_BAR;
;     } else {
;         PG8_STAGE(PG8_SB(0, 0), cB, voffB); PG8_STAGE(PG8_SA(0, 0), cA, voffA); PG8_STAGE(PG8_SB(0, 1), cB + hstepB, voffB); PG8_STAGE(PG8_SA(0, 1), cA + hstepA, voffA);
;         if (wr == 1) PG8_BAR;
;         PG8_WAIT_V(4); PG8_BAR;
;         PG8_STAGE(PG8_SB(1, 0), cB + kstep, voffB); PG8_STAGE(PG8_SA(1, 0), cA + kstep, voffA); PG8_STAGE(PG8_SB(1, 1), cB + hstepB + kstep, voffB);
;         PG8_WAIT_V(6); PG8_BAR;
;     }
;     for (;;) {
;         const bool has_next = S.next(ui + 1, nxt);
;         const char* nA = has_next ? (const char*)g.A + (size_t)nxt.pm * tstepA : cA; const char* nB = has_next ? (const char*)g.Bt + (size_t)nxt.pn * tstepB : cB;
;         for (int t = 0; t < nt; t += 2) {
;             const bool last = (t == nt - 2);
;             if constexpr (Epi::HAS_MID) { if (t == E.mid_t) E.mid(acc, cur, wr, wc, fr, fq); }
;             const char* a1 = cA + (size_t)(t + 1) * kstep;
;             const char* a2 = last ? nA : cA + (size_t)(t + 2) * kstep; const char* b2 = last ? nB : cB + (size_t)(t + 2) * kstep;
.LBB0_697:
	s_lshl_b32 s37, s37, 5
	s_add_i32 s66, s43, s35
	s_and_b32 s37, s37, 0x60
	v_lshl_add_u64 v[16:17], v[0:1], 0, s[30:31]
	s_mov_b32 m0, s66
	s_add_i32 s68, s66, 0x2000
	s_lshl_b32 s71, s36, 13
	s_lshl_b32 s76, s37, 7
	s_waitcnt vmcnt(2)
	s_barrier
	global_load_lds_dwordx4 v[16:17], off
	v_lshl_add_u64 v[242:243], v[4:5], 0, s[30:31]
	s_mov_b32 m0, s68
	s_add_i32 s67, s34, 0x8000
	s_add_i32 s69, s34, 0xa000
	global_load_lds_dwordx4 v[242:243], off
	v_lshl_add_u64 v[14:15], v[18:19], 0, s[30:31]
	s_mov_b32 m0, s67
	s_add_u32 s74, s16, 0x8080
	global_load_lds_dwordx4 v[14:15], off
	v_lshl_add_u64 v[244:245], v[20:21], 0, s[30:31]
	s_mov_b32 m0, s69
	s_addc_u32 s75, s17, 0
	s_add_i32 s16, s46, s35
	global_load_lds_dwordx4 v[244:245], off
	v_lshl_add_u64 v[246:247], s[74:75], 0, v[140:141]
	s_mov_b32 m0, s16
	s_add_i32 s17, s16, 0x2000
	global_load_lds_dwordx4 v[246:247], off
	v_lshl_add_u64 v[248:249], s[74:75], 0, v[24:25]
	s_mov_b32 m0, s17
	v_and_b32_e32 v140, 15, v156
	global_load_lds_dwordx4 v[248:249], off
	v_and_b32_e32 v24, 48, v156
	v_lshlrev_b32_e32 v25, 2, v156
	v_lshl_or_b32 v24, v140, 6, v24
	v_and_b32_e32 v25, 32, v25
	v_bitop3_b32 v26, v24, s71, v25 bitop3:0xde
	v_bitop3_b32 v56, s76, v24, v25 bitop3:0xf6
	s_add_i32 s71, 0, 0x10000
	s_add_i32 s74, 0, 0x14000
	v_add_u32_e32 v36, s71, v56
	v_add_u32_e32 v52, s74, v56
	s_waitcnt vmcnt(6)
	s_barrier
	v_add_u32_e32 v157, 0, v26
	ds_read_b128 v[24:27], v36
	ds_read_b128 v[28:31], v36 offset:1024
	ds_read_b128 v[32:35], v36 offset:2048
	ds_read_b128 v[36:39], v36 offset:3072
	ds_read_b128 v[40:43], v52
	ds_read_b128 v[44:47], v52 offset:1024
	ds_read_b128 v[48:51], v52 offset:2048
	ds_read_b128 v[52:55], v52 offset:3072
	s_add_u32 s12, s12, 0x40080
	v_add_u32_e32 v206, s43, v56
	v_add_u32_e32 v222, s46, v56
	s_addc_u32 s13, s13, 0
	v_lshl_add_u64 v[8:9], s[12:13], 0, v[8:9]
	s_add_i32 m0, s34, 0xc000
	ds_read_b128 v[56:59], v157
	ds_read_b128 v[60:63], v157 offset:1024
	ds_read_b128 v[64:67], v157 offset:2048
	ds_read_b128 v[68:71], v157 offset:3072
	ds_read_b128 v[72:75], v157 offset:4096
	ds_read_b128 v[76:79], v157 offset:5120
	ds_read_b128 v[80:83], v157 offset:6144
	ds_read_b128 v[84:87], v157 offset:7168
	global_load_lds_dwordx4 v[8:9], off
	v_lshl_add_u64 v[8:9], s[12:13], 0, v[22:23]
	s_add_i32 m0, s34, 0xe000
	s_nop 0
	global_load_lds_dwordx4 v[8:9], off
	s_waitcnt vmcnt(8)
	s_waitcnt lgkmcnt(0)
	s_barrier
	s_setprio 1
	s_waitcnt lgkmcnt(0)
	v_mfma_f32_16x16x32_bf16 v[112:115], v[24:27], v[80:83], 0
	v_mfma_f32_16x16x32_bf16 v[88:91], v[24:27], v[56:59], 0
	v_mfma_f32_16x16x32_bf16 v[92:95], v[32:35], v[56:59], 0
	v_mfma_f32_16x16x32_bf16 v[96:99], v[24:27], v[64:67], 0
	v_mfma_f32_16x16x32_bf16 v[100:103], v[32:35], v[64:67], 0
	v_mfma_f32_16x16x32_bf16 v[116:119], v[28:31], v[84:87], v[112:115]
	v_mfma_f32_16x16x32_bf16 v[112:115], v[32:35], v[80:83], 0
	v_mfma_f32_16x16x32_bf16 v[88:91], v[28:31], v[60:63], v[88:91]
	v_mfma_f32_16x16x32_bf16 v[92:95], v[36:39], v[60:63], v[92:95]
	v_mfma_f32_16x16x32_bf16 v[96:99], v[28:31], v[68:71], v[96:99]
	v_mfma_f32_16x16x32_bf16 v[100:103], v[36:39], v[68:71], v[100:103]
	v_mfma_f32_16x16x32_bf16 v[104:107], v[24:27], v[72:75], 0
	v_mfma_f32_16x16x32_bf16 v[108:111], v[32:35], v[72:75], 0
	v_mfma_f32_16x16x32_bf16 v[124:127], v[36:39], v[84:87], v[112:115]
	v_mfma_f32_16x16x32_bf16 v[104:107], v[28:31], v[76:79], v[104:107]
	v_mfma_f32_16x16x32_bf16 v[108:111], v[36:39], v[76:79], v[108:111]
	v_mfma_f32_16x16x32_bf16 v[112:115], v[40:43], v[56:59], 0
	v_mfma_f32_16x16x32_bf16 v[56:59], v[48:51], v[56:59], 0
	v_mfma_f32_16x16x32_bf16 v[132:135], v[44:47], v[60:63], v[112:115]
	v_mfma_f32_16x16x32_bf16 v[56:59], v[52:55], v[60:63], v[56:59]
	v_mfma_f32_16x16x32_bf16 v[60:63], v[40:43], v[64:67], 0
	v_mfma_f32_16x16x32_bf16 v[64:67], v[48:51], v[64:67], 0
	v_mfma_f32_16x16x32_bf16 v[60:63], v[44:47], v[68:71], v[60:63]
	v_mfma_f32_16x16x32_bf16 v[68:71], v[52:55], v[68:71], v[64:67]
	v_mfma_f32_16x16x32_bf16 v[64:67], v[40:43], v[72:75], 0
	v_mfma_f32_16x16x32_bf16 v[136:139], v[44:47], v[76:79], v[64:67]
	v_mfma_f32_16x16x32_bf16 v[64:67], v[48:51], v[72:75], 0
	v_mfma_f32_16x16x32_bf16 v[76:79], v[52:55], v[76:79], v[64:67]
	v_mfma_f32_16x16x32_bf16 v[64:67], v[40:43], v[80:83], 0
	v_mfma_f32_16x16x32_bf16 v[142:145], v[44:47], v[84:87], v[64:67]
	v_mfma_f32_16x16x32_bf16 v[64:67], v[48:51], v[80:83], 0
	v_mfma_f32_16x16x32_bf16 v[146:149], v[52:55], v[84:87], v[64:67]
	s_setprio 0
	s_barrier
	s_add_i32 s12, s71, s35
	s_mov_b32 m0, s12
	s_nop 2
	ds_read_b128 v[64:67], v157 offset:16384
	ds_read_b128 v[72:75], v157 offset:17408
	ds_read_b128 v[80:83], v157 offset:18432
	ds_read_b128 v[84:87], v157 offset:19456
	ds_read_b128 v[112:115], v157 offset:20480
	ds_read_b128 v[120:123], v157 offset:21504
	ds_read_b128 v[128:131], v157 offset:22528
	ds_read_b128 v[158:161], v157 offset:23552
	global_load_lds_dwordx4 v[0:1], off
	s_add_i32 m0, s12, 0x2000
	s_add_i32 s12, s74, s35
	global_load_lds_dwordx4 v[4:5], off
	s_mov_b32 m0, s12
	s_nop 0
	global_load_lds_dwordx4 v[10:11], off
	s_add_i32 m0, s12, 0x2000
	s_nop 0
	global_load_lds_dwordx4 v[12:13], off
	s_mov_b32 m0, s34
	s_nop 0
	global_load_lds_dwordx4 v[18:19], off
	s_mov_b32 m0, s70
	s_nop 0
	global_load_lds_dwordx4 v[20:21], off
	s_waitcnt vmcnt(8)
	s_waitcnt lgkmcnt(0)
	s_barrier
; #define PG8_STAGE(bufoff, gbase, voff) do { _Pragma("unroll") for (int _i = 0; _i < 2; ++_i) \
;         __builtin_amdgcn_global_load_lds((const unsigned*)((const char*)(gbase) + (voff)[_i]), (PG8_LAS unsigned*)(lds + (bufoff) + ldsw + _i * 8192), 16, 0, 0); } while (0)
; #define PG8_LDA(dst, b, h) do { _Pragma("unroll") for (int m = 0; m < 4; ++m) _Pragma("unroll") for (int k = 0; k < 2; ++k) dst[m][k] = *(const PG8_LAS bf16x8*)(lds + PG8_SA(b, h) + aoff + m * 2048 + k * 1024); } while (0)
; #define PG8_LDB(dst, b, h) do { _Pragma("unroll") for (int n = 0; n < 2; ++n) _Pragma("unroll") for (int k = 0; k < 2; ++k) dst[n][k] = *(const PG8_LAS bf16x8*)(lds + PG8_SB(b, h) + boff + n * 2048 + k * 1024); } while (0)
; #define PG8_MMA(ai, bj, At, Bt) do { __builtin_amdgcn_s_setprio(1); _Pragma("unroll") for (int m = 0; m < 4; ++m) _Pragma("unroll") for (int n = 0; n < 2; ++n) _Pragma("unroll") for (int k = 0; k < 2; ++k) \
;         acc[ai][bj][m][n] = __builtin_amdgcn_mfma_f32_16x16x32_bf16(Bt[n][k], At[m][k], acc[ai][bj][m][n], 0, 0, 0); __builtin_amdgcn_s_setprio(0); } while (0)
; #define PG8_WAIT_V(n) asm volatile("s_waitcnt vmcnt(" #n ")" ::: "memory")
; #define PG8_WAIT_L(n) asm volatile("s_waitcnt lgkmcnt(" #n ")" ::: "memory")
; #define PG8_BAR __builtin_amdgcn_s_barrier()
; #define PG8_SCHED __builtin_amdgcn_sched_barrier(0)
; template <class Epi, class Sched, bool ALIGN_EPI = false, bool SP2 = false>
; __device__ __forceinline__ void gemm_phase(PG8_LAS unsigned char* lds, const Gemm g, const Sched& S, const Epi& E) {
;     ...
;             PG8_LDA(At, 0, 1); PG8_STAGE(PG8_SB(0, 0), b2, voffB); PG8_STAGE(PG8_SB(0, 1), b2 + hstepB, voffB); PG8_STAGE(PG8_SA(0, 0), a2, voffA);
;             PG8_WAIT_V(8); PG8_WAIT_L(0); PG8_BAR; PG8_MMA(1, 0, At, B0); PG8_MMA(1, 1, At, B1); PG8_BAR; PG8_SCHED;
;             PG8_LDB(B0, 1, 0); PG8_LDB(B1, 1, 1); PG8_SCHED; PG8_LDA(At, 1, 0); PG8_STAGE(PG8_SA(0, 1), a2 + hstepA, voffA);
;             PG8_WAIT_V(8); PG8_WAIT_L(0); PG8_BAR; PG8_MMA(0, 0, At, B0); PG8_MMA(0, 1, At, B1); PG8_BAR; PG8_SCHED;
;             PG8_LDA(At, 1, 1); PG8_STAGE(PG8_SB(1, 0), b3, voffB); PG8_STAGE(PG8_SB(1, 1), b3 + hstepB, voffB); PG8_STAGE(PG8_SA(1, 0), a3, voffA);
;             PG8_WAIT_V(8); PG8_WAIT_L(0); PG8_BAR; PG8_MMA(1, 0, At, B0); PG8_MMA(1, 1, At, B1); PG8_BAR; PG8_SCHED;
	s_setprio 1
	s_waitcnt lgkmcnt(0)
	v_mfma_f32_16x16x32_bf16 v[8:11], v[24:27], v[64:67], 0
	v_mfma_f32_16x16x32_bf16 v[162:165], v[24:27], v[80:83], 0
	v_mfma_f32_16x16x32_bf16 v[170:173], v[24:27], v[112:115], 0
	v_mfma_f32_16x16x32_bf16 v[22:25], v[24:27], v[128:131], 0
	v_mfma_f32_16x16x32_bf16 v[8:11], v[28:31], v[72:75], v[8:11]
	v_mfma_f32_16x16x32_bf16 v[18:21], v[32:35], v[64:67], 0
	v_mfma_f32_16x16x32_bf16 v[162:165], v[28:31], v[84:87], v[162:165]
	v_mfma_f32_16x16x32_bf16 v[166:169], v[32:35], v[80:83], 0
	v_mfma_f32_16x16x32_bf16 v[170:173], v[28:31], v[120:123], v[170:173]
	v_mfma_f32_16x16x32_bf16 v[174:177], v[32:35], v[112:115], 0
	v_mfma_f32_16x16x32_bf16 v[28:31], v[28:31], v[158:161], v[22:25]
	v_mfma_f32_16x16x32_bf16 v[22:25], v[32:35], v[128:131], 0
	v_mfma_f32_16x16x32_bf16 v[18:21], v[36:39], v[72:75], v[18:21]
	v_mfma_f32_16x16x32_bf16 v[166:169], v[36:39], v[84:87], v[166:169]
	v_mfma_f32_16x16x32_bf16 v[174:177], v[36:39], v[120:123], v[174:177]
	v_mfma_f32_16x16x32_bf16 v[36:39], v[36:39], v[158:161], v[22:25]
	v_mfma_f32_16x16x32_bf16 v[22:25], v[40:43], v[64:67], 0
	v_mfma_f32_16x16x32_bf16 v[178:181], v[44:47], v[72:75], v[22:25]
	v_mfma_f32_16x16x32_bf16 v[22:25], v[48:51], v[64:67], 0
	v_mfma_f32_16x16x32_bf16 v[182:185], v[52:55], v[72:75], v[22:25]
	v_mfma_f32_16x16x32_bf16 v[22:25], v[40:43], v[80:83], 0
	v_mfma_f32_16x16x32_bf16 v[186:189], v[44:47], v[84:87], v[22:25]
	v_mfma_f32_16x16x32_bf16 v[22:25], v[48:51], v[80:83], 0
	v_mfma_f32_16x16x32_bf16 v[190:193], v[52:55], v[84:87], v[22:25]
	v_mfma_f32_16x16x32_bf16 v[22:25], v[40:43], v[112:115], 0
	v_mfma_f32_16x16x32_bf16 v[194:197], v[44:47], v[120:123], v[22:25]
	v_mfma_f32_16x16x32_bf16 v[22:25], v[48:51], v[112:115], 0
	v_mfma_f32_16x16x32_bf16 v[198:201], v[52:55], v[120:123], v[22:25]
	v_mfma_f32_16x16x32_bf16 v[22:25], v[40:43], v[128:131], 0
	v_mfma_f32_16x16x32_bf16 v[202:205], v[44:47], v[158:161], v[22:25]
	v_mfma_f32_16x16x32_bf16 v[22:25], v[48:51], v[128:131], 0
	v_mfma_f32_16x16x32_bf16 v[158:161], v[52:55], v[158:161], v[22:25]
	s_setprio 0
	s_barrier
	ds_read_b128 v[32:35], v206
	ds_read_b128 v[44:47], v206 offset:1024
	ds_read_b128 v[52:55], v206 offset:2048
	ds_read_b128 v[206:209], v206 offset:3072
	ds_read_b128 v[210:213], v222
	ds_read_b128 v[214:217], v222 offset:1024
	ds_read_b128 v[218:221], v222 offset:2048
	ds_read_b128 v[222:225], v222 offset:3072
	s_mov_b32 m0, s39
	ds_read_b128 v[22:25], v157 offset:32768
	ds_read_b128 v[40:43], v157 offset:33792
	ds_read_b128 v[48:51], v157 offset:34816
	ds_read_b128 v[84:87], v157 offset:35840
	ds_read_b128 v[226:229], v157 offset:36864
	ds_read_b128 v[230:233], v157 offset:37888
	ds_read_b128 v[234:237], v157 offset:38912
	ds_read_b128 v[238:241], v157 offset:39936
	global_load_lds_dwordx4 v[2:3], off
	s_mov_b32 m0, s65
	s_nop 0
	global_load_lds_dwordx4 v[6:7], off
	s_waitcnt vmcnt(8)
	s_waitcnt lgkmcnt(0)
	s_barrier
	s_setprio 1
	s_waitcnt lgkmcnt(0)
	v_mfma_f32_16x16x32_bf16 v[0:3], v[32:35], v[22:25], v[88:91]
	v_mfma_f32_16x16x32_bf16 v[128:131], v[44:47], v[40:43], v[0:3]
	v_mfma_f32_16x16x32_bf16 v[0:3], v[52:55], v[22:25], v[92:95]
	v_mfma_f32_16x16x32_bf16 v[88:91], v[206:209], v[40:43], v[0:3]
	v_mfma_f32_16x16x32_bf16 v[0:3], v[32:35], v[48:51], v[96:99]
	v_mfma_f32_16x16x32_bf16 v[120:123], v[44:47], v[84:87], v[0:3]
	v_mfma_f32_16x16x32_bf16 v[0:3], v[52:55], v[48:51], v[100:103]
	v_mfma_f32_16x16x32_bf16 v[80:83], v[206:209], v[84:87], v[0:3]
	v_mfma_f32_16x16x32_bf16 v[0:3], v[32:35], v[226:229], v[104:107]
	v_mfma_f32_16x16x32_bf16 v[112:115], v[44:47], v[230:233], v[0:3]
	v_mfma_f32_16x16x32_bf16 v[0:3], v[52:55], v[226:229], v[108:111]
	v_mfma_f32_16x16x32_bf16 v[72:75], v[206:209], v[230:233], v[0:3]
	v_mfma_f32_16x16x32_bf16 v[0:3], v[32:35], v[234:237], v[116:119]
	v_mfma_f32_16x16x32_bf16 v[96:99], v[44:47], v[238:241], v[0:3]
	v_mfma_f32_16x16x32_bf16 v[0:3], v[52:55], v[234:237], v[124:127]
	v_mfma_f32_16x16x32_bf16 v[64:67], v[206:209], v[238:241], v[0:3]
	v_mfma_f32_16x16x32_bf16 v[0:3], v[210:213], v[22:25], v[132:135]
	v_mfma_f32_16x16x32_bf16 v[132:135], v[214:217], v[40:43], v[0:3]
	v_mfma_f32_16x16x32_bf16 v[0:3], v[218:221], v[22:25], v[56:59]
	v_mfma_f32_16x16x32_bf16 v[92:95], v[222:225], v[40:43], v[0:3]
	v_mfma_f32_16x16x32_bf16 v[0:3], v[210:213], v[48:51], v[60:63]
	v_mfma_f32_16x16x32_bf16 v[124:127], v[214:217], v[84:87], v[0:3]
	v_mfma_f32_16x16x32_bf16 v[0:3], v[218:221], v[48:51], v[68:71]
	v_mfma_f32_16x16x32_bf16 v[84:87], v[222:225], v[84:87], v[0:3]
	v_mfma_f32_16x16x32_bf16 v[0:3], v[210:213], v[226:229], v[136:139]
	v_mfma_f32_16x16x32_bf16 v[116:119], v[214:217], v[230:233], v[0:3]
	v_mfma_f32_16x16x32_bf16 v[0:3], v[218:221], v[226:229], v[76:79]
	v_mfma_f32_16x16x32_bf16 v[76:79], v[222:225], v[230:233], v[0:3]
	v_mfma_f32_16x16x32_bf16 v[0:3], v[210:213], v[234:237], v[142:145]
	v_mfma_f32_16x16x32_bf16 v[100:103], v[214:217], v[238:241], v[0:3]
	v_mfma_f32_16x16x32_bf16 v[0:3], v[218:221], v[234:237], v[146:149]
	v_mfma_f32_16x16x32_bf16 v[68:71], v[222:225], v[238:241], v[0:3]
	s_setprio 0
	s_barrier
; #define PG8_STAGE(bufoff, gbase, voff) do { _Pragma("unroll") for (int _i = 0; _i < 2; ++_i) \
;         __builtin_amdgcn_global_load_lds((const unsigned*)((const char*)(gbase) + (voff)[_i]), (PG8_LAS unsigned*)(lds + (bufoff) + ldsw + _i * 8192), 16, 0, 0); } while (0)
; #define PG8_LDA(dst, b, h) do { _Pragma("unroll") for (int m = 0; m < 4; ++m) _Pragma("unroll") for (int k = 0; k < 2; ++k) dst[m][k] = *(const PG8_LAS bf16x8*)(lds + PG8_SA(b, h) + aoff + m * 2048 + k * 1024); } while (0)
; #define PG8_LDB(dst, b, h) do { _Pragma("unroll") for (int n = 0; n < 2; ++n) _Pragma("unroll") for (int k = 0; k < 2; ++k) dst[n][k] = *(const PG8_LAS bf16x8*)(lds + PG8_SB(b, h) + boff + n * 2048 + k * 1024); } while (0)
; #define PG8_MMA(ai, bj, At, Bt) do { __builtin_amdgcn_s_setprio(1); _Pragma("unroll") for (int m = 0; m < 4; ++m) _Pragma("unroll") for (int n = 0; n < 2; ++n) _Pragma("unroll") for (int k = 0; k < 2; ++k) \
;         acc[ai][bj][m][n] = __builtin_amdgcn_mfma_f32_16x16x32_bf16(Bt[n][k], At[m][k], acc[ai][bj][m][n], 0, 0, 0); __builtin_amdgcn_s_setprio(0); } while (0)
; #define PG8_WAIT_V(n) asm volatile("s_waitcnt vmcnt(" #n ")" ::: "memory")
; #define PG8_WAIT_L(n) asm volatile("s_waitcnt lgkmcnt(" #n ")" ::: "memory")
; #define PG8_BAR __builtin_amdgcn_s_barrier()
; #define PG8_SCHED __builtin_amdgcn_sched_barrier(0)
; template <class Epi, class Sched, bool ALIGN_EPI = false, bool SP2 = false>
; __device__ __forceinline__ void gemm_phase(PG8_LAS unsigned char* lds, const Gemm g, const Sched& S, const Epi& E) {
;     ...
;             PG8_LDB(B0, 1, 0); PG8_LDB(B1, 1, 1); PG8_SCHED; PG8_LDA(At, 1, 0); PG8_STAGE(PG8_SA(0, 1), a2 + hstepA, voffA);
;             PG8_WAIT_V(8); PG8_WAIT_L(0); PG8_BAR; PG8_MMA(0, 0, At, B0); PG8_MMA(0, 1, At, B1); PG8_BAR; PG8_SCHED;
;             PG8_LDA(At, 1, 1); PG8_STAGE(PG8_SB(1, 0), b3, voffB); PG8_STAGE(PG8_SB(1, 1), b3 + hstepB, voffB); PG8_STAGE(PG8_SA(1, 0), a3, voffA);
;             PG8_WAIT_V(8); PG8_WAIT_L(0); PG8_BAR; PG8_MMA(1, 0, At, B0); PG8_MMA(1, 1, At, B1); PG8_BAR; PG8_SCHED;
;     ...
;     PG8_WAIT_V(0);
;     if constexpr (!ALIGN_EPI) { if (wr == 0) PG8_BAR; }
;     PG8_BAR;
	s_mov_b32 m0, s66
	ds_read_b128 v[4:7], v157 offset:49152
	ds_read_b128 v[104:107], v157 offset:50176
	ds_read_b128 v[108:111], v157 offset:51200
	ds_read_b128 v[136:139], v157 offset:52224
	ds_read_b128 v[142:145], v157 offset:53248
	ds_read_b128 v[146:149], v157 offset:54272
	ds_read_b128 v[226:229], v157 offset:55296
	ds_read_b128 v[230:233], v157 offset:56320
	global_load_lds_dwordx4 v[16:17], off
	s_mov_b32 m0, s68
	s_nop 0
	global_load_lds_dwordx4 v[242:243], off
	s_mov_b32 m0, s16
	s_nop 0
	global_load_lds_dwordx4 v[246:247], off
	s_mov_b32 m0, s17
	s_nop 0
	global_load_lds_dwordx4 v[248:249], off
	s_mov_b32 m0, s67
	s_nop 0
	global_load_lds_dwordx4 v[14:15], off
	s_mov_b32 m0, s69
	s_nop 0
	global_load_lds_dwordx4 v[244:245], off
	s_waitcnt vmcnt(8)
	s_waitcnt lgkmcnt(0)
	s_barrier
	s_setprio 1
	s_waitcnt lgkmcnt(0)
	v_mfma_f32_16x16x32_bf16 v[0:3], v[32:35], v[4:7], v[8:11]
	v_mfma_f32_16x16x32_bf16 v[56:59], v[44:47], v[104:107], v[0:3]
	v_mfma_f32_16x16x32_bf16 v[0:3], v[52:55], v[4:7], v[18:21]
	v_mfma_f32_16x16x32_bf16 v[24:27], v[206:209], v[104:107], v[0:3]
	v_mfma_f32_16x16x32_bf16 v[0:3], v[32:35], v[108:111], v[162:165]
	v_mfma_f32_16x16x32_bf16 v[48:51], v[44:47], v[136:139], v[0:3]
	v_mfma_f32_16x16x32_bf16 v[0:3], v[52:55], v[108:111], v[166:169]
	v_mfma_f32_16x16x32_bf16 v[16:19], v[206:209], v[136:139], v[0:3]
	v_mfma_f32_16x16x32_bf16 v[0:3], v[32:35], v[142:145], v[170:173]
	v_mfma_f32_16x16x32_bf16 v[40:43], v[44:47], v[146:149], v[0:3]
	v_mfma_f32_16x16x32_bf16 v[0:3], v[52:55], v[142:145], v[174:177]
	v_mfma_f32_16x16x32_bf16 v[8:11], v[206:209], v[146:149], v[0:3]
	v_mfma_f32_16x16x32_bf16 v[0:3], v[32:35], v[226:229], v[28:31]
	v_mfma_f32_16x16x32_bf16 v[32:35], v[44:47], v[230:233], v[0:3]
	v_mfma_f32_16x16x32_bf16 v[0:3], v[52:55], v[226:229], v[36:39]
	v_mfma_f32_16x16x32_bf16 v[0:3], v[206:209], v[230:233], v[0:3]
	v_mfma_f32_16x16x32_bf16 v[12:15], v[210:213], v[4:7], v[178:181]
	v_mfma_f32_16x16x32_bf16 v[4:7], v[218:221], v[4:7], v[182:185]
	v_mfma_f32_16x16x32_bf16 v[28:31], v[222:225], v[104:107], v[4:7]
	v_mfma_f32_16x16x32_bf16 v[4:7], v[210:213], v[108:111], v[186:189]
	v_mfma_f32_16x16x32_bf16 v[52:55], v[214:217], v[136:139], v[4:7]
	v_mfma_f32_16x16x32_bf16 v[4:7], v[218:221], v[108:111], v[190:193]
	v_mfma_f32_16x16x32_bf16 v[20:23], v[222:225], v[136:139], v[4:7]
	v_mfma_f32_16x16x32_bf16 v[4:7], v[210:213], v[142:145], v[194:197]
	v_mfma_f32_16x16x32_bf16 v[44:47], v[214:217], v[146:149], v[4:7]
	v_mfma_f32_16x16x32_bf16 v[4:7], v[218:221], v[142:145], v[198:201]
	v_mfma_f32_16x16x32_bf16 v[60:63], v[214:217], v[104:107], v[12:15]
	v_mfma_f32_16x16x32_bf16 v[12:15], v[222:225], v[146:149], v[4:7]
	v_mfma_f32_16x16x32_bf16 v[4:7], v[210:213], v[226:229], v[202:205]
	v_mfma_f32_16x16x32_bf16 v[36:39], v[214:217], v[230:233], v[4:7]
	v_mfma_f32_16x16x32_bf16 v[4:7], v[218:221], v[226:229], v[158:161]
	v_mfma_f32_16x16x32_bf16 v[4:7], v[222:225], v[230:233], v[4:7]
	s_setprio 0
	s_barrier
	s_waitcnt vmcnt(0)
	s_cmpk_gt_u32 s19, 0xff
	s_cbranch_scc1 .LBB0_699
	s_barrier

; #define PG8_STAGE(bufoff, gbase, voff) do { _Pragma("unroll") for (int _i = 0; _i < 2; ++_i) \
;         __builtin_amdgcn_global_load_lds((const unsigned*)((const char*)(gbase) + (voff)[_i]), (PG8_LAS unsigned*)(lds + (bufoff) + ldsw + _i * 8192), 16, 0, 0); } while (0)
; #define PG8_LDA(dst, b, h) do { _Pragma("unroll") for (int m = 0; m < 4; ++m) _Pragma("unroll") for (int k = 0; k < 2; ++k) dst[m][k] = *(const PG8_LAS bf16x8*)(lds + PG8_SA(b, h) + aoff + m * 2048 + k * 1024); } while (0)
; #define PG8_LDB(dst, b, h) do { _Pragma("unroll") for (int n = 0; n < 2; ++n) _Pragma("unroll") for (int k = 0; k < 2; ++k) dst[n][k] = *(const PG8_LAS bf16x8*)(lds + PG8_SB(b, h) + boff + n * 2048 + k * 1024); } while (0)
; #define PG8_WAIT_V(n) asm volatile("s_waitcnt vmcnt(" #n ")" ::: "memory")
; #define PG8_WAIT_L(n) asm volatile("s_waitcnt lgkmcnt(" #n ")" ::: "memory")
; #define PG8_BAR __builtin_amdgcn_s_barrier()
; #define PG8_SCHED __builtin_amdgcn_sched_barrier(0)
; template <class Epi, class Sched, bool ALIGN_EPI = false, bool SP2 = false>
; __device__ __forceinline__ void gemm_phase(PG8_LAS unsigned char* lds, const Gemm g, const Sched& S, const Epi& E) {
;     ...
;         const char* nA = has_next ? (const char*)g.A + (size_t)nxt.pm * tstepA : cA; const char* nB = has_next ? (const char*)g.Bt + (size_t)nxt.pn * tstepB : cB;
;         for (int t = 0; t < nt; t += 2) {
;             const bool last = (t == nt - 2);
;             if constexpr (Epi::HAS_MID) { if (t == E.mid_t) E.mid(acc, cur, wr, wc, fr, fq); }
;             const char* a1 = cA + (size_t)(t + 1) * kstep;
;             const char* a2 = last ? nA : cA + (size_t)(t + 2) * kstep; const char* b2 = last ? nB : cB + (size_t)(t + 2) * kstep;
;             const char* a3 = a2 + kstep; const char* b3 = b2 + kstep;
;             if (last && has_next) S.a_ready(nxt);
;             if constexpr (SP2) {
;             PG8_LDB(B0, 0, 0); PG8_LDB(B1, 0, 1); PG8_SCHED; PG8_LDA(At, 0, 0); PG8_STAGE(PG8_SA(1, 1), a1 + hstepA, voffA);
;             PG8_WAIT_V(8); PG8_WAIT_L(0); PG8_BAR; PG8_MMA(0, 0, At, B0); PG8_MMA(0, 1, At, B1); PG8_BAR; PG8_SCHED;
;             PG8_LDA(At, 0, 1); PG8_STAGE(PG8_SB(0, 0), b2, voffB); PG8_STAGE(PG8_SB(0, 1), b2 + hstepB, voffB); PG8_STAGE(PG8_SA(0, 0), a2, voffA);
;             PG8_WAIT_V(8); PG8_WAIT_L(0); PG8_BAR; PG8_MMA(1, 0, At, B0); PG8_MMA(1, 1, At, B1); PG8_BAR; PG8_SCHED;
.LBB0_1217:
	v_add_u32_e32 v1, s57, v154
	ds_read_b128 v[158:161], v1
	ds_read_b128 v[162:165], v1 offset:1024
	ds_read_b128 v[166:169], v1 offset:2048
	ds_read_b128 v[170:173], v1 offset:3072
	v_add_u32_e32 v1, s58, v154
	s_add_u32 s42, s78, s18
	ds_read_b128 v[174:177], v1
	ds_read_b128 v[178:181], v1 offset:1024
	ds_read_b128 v[182:185], v1 offset:2048
	ds_read_b128 v[186:189], v1 offset:3072
	s_addc_u32 s43, s79, s19
	s_add_u32 s42, s42, 0x100
	s_addc_u32 s43, s43, 0
	s_add_u32 s69, s66, s18
	s_addc_u32 s70, s67, s19
	s_cmpk_eq_i32 s18, 0xf00
	s_cselect_b32 s43, s62, s43
	s_cselect_b32 s42, s63, s42
	s_cselect_b32 vcc_hi, s51, s70
	s_cselect_b32 vcc_lo, s65, s69
	v_lshl_add_u64 v[2:3], v[148:149], 0, s[18:19]
	s_add_i32 m0, s5, 0xc000
	ds_read_b128 v[190:193], v156
	ds_read_b128 v[194:197], v156 offset:1024
	ds_read_b128 v[198:201], v156 offset:2048
	ds_read_b128 v[202:205], v156 offset:3072
	ds_read_b128 v[206:209], v156 offset:4096
	ds_read_b128 v[210:213], v156 offset:5120
	ds_read_b128 v[214:217], v156 offset:6144
	ds_read_b128 v[218:221], v156 offset:7168
	s_add_u32 s98, s78, s18
	s_addc_u32 s99, s79, s19
	s_add_u32 s98, s98, 0x80
	s_addc_u32 s99, s99, 0
	s_mov_b32 m0, s47
	s_nop 0
	global_load_lds_dwordx4 v132, s[98:99]
	s_mov_b32 m0, s56
	s_nop 0
	global_load_lds_dwordx4 v136, s[98:99]
	s_add_i32 m0, s5, 0xc000
	s_nop 0
	global_load_lds_dwordx4 v[2:3], off
	v_lshl_add_u64 v[2:3], v[150:151], 0, s[18:19]
	s_add_i32 m0, s5, 0xe000
	s_nop 0
	global_load_lds_dwordx4 v[2:3], off
	s_waitcnt vmcnt(8)
	s_waitcnt lgkmcnt(0)
	s_barrier
	s_setprio 1
	v_mfma_f32_16x16x32_bf16 v[128:131], v[158:161], v[190:193], v[128:131]
	v_mfma_f32_16x16x32_bf16 v[124:127], v[166:169], v[190:193], v[124:127]
	v_mfma_f32_16x16x32_bf16 v[112:115], v[158:161], v[198:201], v[112:115]
	v_mfma_f32_16x16x32_bf16 v[108:111], v[166:169], v[198:201], v[108:111]
	v_mfma_f32_16x16x32_bf16 v[96:99], v[158:161], v[206:209], v[96:99]
	v_mfma_f32_16x16x32_bf16 v[92:95], v[166:169], v[206:209], v[92:95]
	v_mfma_f32_16x16x32_bf16 v[80:83], v[158:161], v[214:217], v[80:83]
	v_mfma_f32_16x16x32_bf16 v[76:79], v[166:169], v[214:217], v[76:79]
	v_mfma_f32_16x16x32_bf16 v[128:131], v[162:165], v[194:197], v[128:131]
	v_mfma_f32_16x16x32_bf16 v[124:127], v[170:173], v[194:197], v[124:127]
	v_mfma_f32_16x16x32_bf16 v[112:115], v[162:165], v[202:205], v[112:115]
	v_mfma_f32_16x16x32_bf16 v[108:111], v[170:173], v[202:205], v[108:111]
	v_mfma_f32_16x16x32_bf16 v[96:99], v[162:165], v[210:213], v[96:99]
	v_mfma_f32_16x16x32_bf16 v[92:95], v[170:173], v[210:213], v[92:95]
	v_mfma_f32_16x16x32_bf16 v[80:83], v[162:165], v[218:221], v[80:83]
	v_mfma_f32_16x16x32_bf16 v[76:79], v[170:173], v[218:221], v[76:79]
	v_mfma_f32_16x16x32_bf16 v[120:123], v[174:177], v[190:193], v[120:123]
	v_mfma_f32_16x16x32_bf16 v[116:119], v[182:185], v[190:193], v[116:119]
	v_mfma_f32_16x16x32_bf16 v[104:107], v[174:177], v[198:201], v[104:107]
	v_mfma_f32_16x16x32_bf16 v[100:103], v[182:185], v[198:201], v[100:103]
	v_mfma_f32_16x16x32_bf16 v[88:91], v[174:177], v[206:209], v[88:91]
	v_mfma_f32_16x16x32_bf16 v[84:87], v[182:185], v[206:209], v[84:87]
	v_mfma_f32_16x16x32_bf16 v[72:75], v[174:177], v[214:217], v[72:75]
	v_mfma_f32_16x16x32_bf16 v[68:71], v[182:185], v[214:217], v[68:71]
	v_mfma_f32_16x16x32_bf16 v[120:123], v[178:181], v[194:197], v[120:123]
	v_mfma_f32_16x16x32_bf16 v[116:119], v[186:189], v[194:197], v[116:119]
	v_mfma_f32_16x16x32_bf16 v[104:107], v[178:181], v[202:205], v[104:107]
	v_mfma_f32_16x16x32_bf16 v[100:103], v[186:189], v[202:205], v[100:103]
	v_mfma_f32_16x16x32_bf16 v[88:91], v[178:181], v[210:213], v[88:91]
	v_mfma_f32_16x16x32_bf16 v[84:87], v[186:189], v[210:213], v[84:87]
	v_mfma_f32_16x16x32_bf16 v[72:75], v[178:181], v[218:221], v[72:75]
	v_mfma_f32_16x16x32_bf16 v[68:71], v[186:189], v[218:221], v[68:71]
	s_setprio 0
	s_barrier
	s_add_i32 s69, s57, s4
	s_mov_b32 m0, s69
	ds_read_b128 v[190:193], v156 offset:16384
	ds_read_b128 v[194:197], v156 offset:17408
	ds_read_b128 v[198:201], v156 offset:18432
	ds_read_b128 v[202:205], v156 offset:19456
	ds_read_b128 v[206:209], v156 offset:20480
	ds_read_b128 v[210:213], v156 offset:21504
	ds_read_b128 v[214:217], v156 offset:22528
	ds_read_b128 v[218:221], v156 offset:23552
	global_load_lds_dwordx4 v134, vcc
	s_add_i32 m0, s69, 0x2000
	s_add_u32 s70, vcc_lo, 0x80000
	s_addc_u32 s71, vcc_hi, 0
	s_add_i32 s69, s58, s4
	global_load_lds_dwordx4 v138, vcc
	s_mov_b32 m0, s69
	s_nop 0
	global_load_lds_dwordx4 v134, s[70:71]
	s_add_i32 m0, s69, 0x2000
	s_nop 0
	global_load_lds_dwordx4 v138, s[70:71]
	s_waitcnt vmcnt(6)
	s_waitcnt lgkmcnt(0)
	s_barrier
; #define PG8_STAGE(bufoff, gbase, voff) do { _Pragma("unroll") for (int _i = 0; _i < 2; ++_i) \
;         __builtin_amdgcn_global_load_lds((const unsigned*)((const char*)(gbase) + (voff)[_i]), (PG8_LAS unsigned*)(lds + (bufoff) + ldsw + _i * 8192), 16, 0, 0); } while (0)
; #define PG8_LDA(dst, b, h) do { _Pragma("unroll") for (int m = 0; m < 4; ++m) _Pragma("unroll") for (int k = 0; k < 2; ++k) dst[m][k] = *(const PG8_LAS bf16x8*)(lds + PG8_SA(b, h) + aoff + m * 2048 + k * 1024); } while (0)
; #define PG8_LDB(dst, b, h) do { _Pragma("unroll") for (int n = 0; n < 2; ++n) _Pragma("unroll") for (int k = 0; k < 2; ++k) dst[n][k] = *(const PG8_LAS bf16x8*)(lds + PG8_SB(b, h) + boff + n * 2048 + k * 1024); } while (0)
; #define PG8_MMA(ai, bj, At, Bt) do { __builtin_amdgcn_s_setprio(1); _Pragma("unroll") for (int m = 0; m < 4; ++m) _Pragma("unroll") for (int n = 0; n < 2; ++n) _Pragma("unroll") for (int k = 0; k < 2; ++k) \
;         acc[ai][bj][m][n] = __builtin_amdgcn_mfma_f32_16x16x32_bf16(Bt[n][k], At[m][k], acc[ai][bj][m][n], 0, 0, 0); __builtin_amdgcn_s_setprio(0); } while (0)
; #define PG8_WAIT_V(n) asm volatile("s_waitcnt vmcnt(" #n ")" ::: "memory")
; #define PG8_WAIT_L(n) asm volatile("s_waitcnt lgkmcnt(" #n ")" ::: "memory")
; #define PG8_BAR __builtin_amdgcn_s_barrier()
; #define PG8_SCHED __builtin_amdgcn_sched_barrier(0)
; template <class Epi, class Sched, bool ALIGN_EPI = false, bool SP2 = false>
; __device__ __forceinline__ void gemm_phase(PG8_LAS unsigned char* lds, const Gemm g, const Sched& S, const Epi& E) {
;     ...
;             PG8_WAIT_V(8); PG8_WAIT_L(0); PG8_BAR; PG8_MMA(0, 0, At, B0); PG8_MMA(0, 1, At, B1); PG8_BAR; PG8_SCHED;
;             PG8_LDA(At, 0, 1); PG8_STAGE(PG8_SB(0, 0), b2, voffB); PG8_STAGE(PG8_SB(0, 1), b2 + hstepB, voffB); PG8_STAGE(PG8_SA(0, 0), a2, voffA);
;             PG8_WAIT_V(8); PG8_WAIT_L(0); PG8_BAR; PG8_MMA(1, 0, At, B0); PG8_MMA(1, 1, At, B1); PG8_BAR; PG8_SCHED;
;             PG8_LDB(B0, 1, 0); PG8_LDB(B1, 1, 1); PG8_SCHED; PG8_LDA(At, 1, 0); PG8_STAGE(PG8_SA(0, 1), a2 + hstepA, voffA);
;             PG8_WAIT_V(8); PG8_WAIT_L(0); PG8_BAR; PG8_MMA(0, 0, At, B0); PG8_MMA(0, 1, At, B1); PG8_BAR; PG8_SCHED;
	s_setprio 1
	v_mfma_f32_16x16x32_bf16 v[64:67], v[158:161], v[190:193], v[64:67]
	v_mfma_f32_16x16x32_bf16 v[60:63], v[166:169], v[190:193], v[60:63]
	v_mfma_f32_16x16x32_bf16 v[48:51], v[158:161], v[198:201], v[48:51]
	v_mfma_f32_16x16x32_bf16 v[44:47], v[166:169], v[198:201], v[44:47]
	v_mfma_f32_16x16x32_bf16 v[32:35], v[158:161], v[206:209], v[32:35]
	v_mfma_f32_16x16x32_bf16 v[28:31], v[166:169], v[206:209], v[28:31]
	v_mfma_f32_16x16x32_bf16 v[16:19], v[158:161], v[214:217], v[16:19]
	v_mfma_f32_16x16x32_bf16 v[12:15], v[166:169], v[214:217], v[12:15]
	v_mfma_f32_16x16x32_bf16 v[64:67], v[162:165], v[194:197], v[64:67]
	v_mfma_f32_16x16x32_bf16 v[60:63], v[170:173], v[194:197], v[60:63]
	v_mfma_f32_16x16x32_bf16 v[48:51], v[162:165], v[202:205], v[48:51]
	v_mfma_f32_16x16x32_bf16 v[44:47], v[170:173], v[202:205], v[44:47]
	v_mfma_f32_16x16x32_bf16 v[32:35], v[162:165], v[210:213], v[32:35]
	v_mfma_f32_16x16x32_bf16 v[28:31], v[170:173], v[210:213], v[28:31]
	v_mfma_f32_16x16x32_bf16 v[16:19], v[162:165], v[218:221], v[16:19]
	v_mfma_f32_16x16x32_bf16 v[12:15], v[170:173], v[218:221], v[12:15]
	v_mfma_f32_16x16x32_bf16 v[56:59], v[174:177], v[190:193], v[56:59]
	v_mfma_f32_16x16x32_bf16 v[52:55], v[182:185], v[190:193], v[52:55]
	v_mfma_f32_16x16x32_bf16 v[40:43], v[174:177], v[198:201], v[40:43]
	v_mfma_f32_16x16x32_bf16 v[36:39], v[182:185], v[198:201], v[36:39]
	v_mfma_f32_16x16x32_bf16 v[24:27], v[174:177], v[206:209], v[24:27]
	v_mfma_f32_16x16x32_bf16 v[20:23], v[182:185], v[206:209], v[20:23]
	v_mfma_f32_16x16x32_bf16 v[8:11], v[174:177], v[214:217], v[8:11]
	v_mfma_f32_16x16x32_bf16 v[2:5], v[182:185], v[214:217], v[4:7]
	v_mfma_f32_16x16x32_bf16 v[56:59], v[178:181], v[194:197], v[56:59]
	v_mfma_f32_16x16x32_bf16 v[52:55], v[186:189], v[194:197], v[52:55]
	v_mfma_f32_16x16x32_bf16 v[40:43], v[178:181], v[202:205], v[40:43]
	v_mfma_f32_16x16x32_bf16 v[36:39], v[186:189], v[202:205], v[36:39]
	v_mfma_f32_16x16x32_bf16 v[24:27], v[178:181], v[210:213], v[24:27]
	v_mfma_f32_16x16x32_bf16 v[20:23], v[186:189], v[210:213], v[20:23]
	v_mfma_f32_16x16x32_bf16 v[8:11], v[178:181], v[218:221], v[8:11]
	v_mfma_f32_16x16x32_bf16 v[2:5], v[186:189], v[218:221], v[2:5]
	s_setprio 0
	s_barrier
	s_add_i32 s69, 0, 0x18000
	v_add_u32_e32 v1, s69, v154
	s_add_i32 s70, 0, 0x1c000
	ds_read_b128 v[158:161], v1
	ds_read_b128 v[162:165], v1 offset:1024
	ds_read_b128 v[166:169], v1 offset:2048
	ds_read_b128 v[170:173], v1 offset:3072
	v_add_u32_e32 v1, s70, v154
	ds_read_b128 v[174:177], v1
	ds_read_b128 v[178:181], v1 offset:1024
	ds_read_b128 v[182:185], v1 offset:2048
	ds_read_b128 v[186:189], v1 offset:3072
	s_mov_b64 s[100:101], s[42:43]
	s_add_u32 s42, s42, 0x80000
	s_addc_u32 s43, s43, 0
	s_mov_b32 m0, s7
	ds_read_b128 v[190:193], v156 offset:32768
	ds_read_b128 v[194:197], v156 offset:33792
	ds_read_b128 v[198:201], v156 offset:34816
	ds_read_b128 v[202:205], v156 offset:35840
	ds_read_b128 v[206:209], v156 offset:36864
	ds_read_b128 v[210:213], v156 offset:37888
	ds_read_b128 v[214:217], v156 offset:38912
	ds_read_b128 v[218:221], v156 offset:39936
	s_mov_b32 m0, s5
	s_nop 0
	global_load_lds_dwordx4 v132, s[100:101]
	s_mov_b32 m0, s6
	s_nop 0
	global_load_lds_dwordx4 v136, s[100:101]
	s_mov_b32 m0, s7
	s_nop 0
	global_load_lds_dwordx4 v132, s[42:43]
	s_mov_b32 m0, s33
	s_nop 0
	global_load_lds_dwordx4 v136, s[42:43]
	s_waitcnt vmcnt(8)
	s_waitcnt lgkmcnt(0)
	s_barrier
; #define PG8_STAGE(bufoff, gbase, voff) do { _Pragma("unroll") for (int _i = 0; _i < 2; ++_i) \
;         __builtin_amdgcn_global_load_lds((const unsigned*)((const char*)(gbase) + (voff)[_i]), (PG8_LAS unsigned*)(lds + (bufoff) + ldsw + _i * 8192), 16, 0, 0); } while (0)
; #define PG8_LDA(dst, b, h) do { _Pragma("unroll") for (int m = 0; m < 4; ++m) _Pragma("unroll") for (int k = 0; k < 2; ++k) dst[m][k] = *(const PG8_LAS bf16x8*)(lds + PG8_SA(b, h) + aoff + m * 2048 + k * 1024); } while (0)
; #define PG8_MMA(ai, bj, At, Bt) do { __builtin_amdgcn_s_setprio(1); _Pragma("unroll") for (int m = 0; m < 4; ++m) _Pragma("unroll") for (int n = 0; n < 2; ++n) _Pragma("unroll") for (int k = 0; k < 2; ++k) \
;         acc[ai][bj][m][n] = __builtin_amdgcn_mfma_f32_16x16x32_bf16(Bt[n][k], At[m][k], acc[ai][bj][m][n], 0, 0, 0); __builtin_amdgcn_s_setprio(0); } while (0)
; #define PG8_WAIT_V(n) asm volatile("s_waitcnt vmcnt(" #n ")" ::: "memory")
; #define PG8_WAIT_L(n) asm volatile("s_waitcnt lgkmcnt(" #n ")" ::: "memory")
; #define PG8_BAR __builtin_amdgcn_s_barrier()
; #define PG8_SCHED __builtin_amdgcn_sched_barrier(0)
; template <class Epi, class Sched, bool ALIGN_EPI = false, bool SP2 = false>
; __device__ __forceinline__ void gemm_phase(PG8_LAS unsigned char* lds, const Gemm g, const Sched& S, const Epi& E) {
;     ...
;             PG8_WAIT_V(8); PG8_WAIT_L(0); PG8_BAR; PG8_MMA(0, 0, At, B0); PG8_MMA(0, 1, At, B1); PG8_BAR; PG8_SCHED;
;             PG8_LDA(At, 1, 1); PG8_STAGE(PG8_SB(1, 0), b3, voffB); PG8_STAGE(PG8_SB(1, 1), b3 + hstepB, voffB); PG8_STAGE(PG8_SA(1, 0), a3, voffA);
;             PG8_WAIT_V(8); PG8_WAIT_L(0); PG8_BAR; PG8_MMA(1, 0, At, B0); PG8_MMA(1, 1, At, B1); PG8_BAR; PG8_SCHED;
	s_setprio 1
	v_mfma_f32_16x16x32_bf16 v[128:131], v[158:161], v[190:193], v[128:131]
	v_mfma_f32_16x16x32_bf16 v[124:127], v[166:169], v[190:193], v[124:127]
	v_mfma_f32_16x16x32_bf16 v[112:115], v[158:161], v[198:201], v[112:115]
	v_mfma_f32_16x16x32_bf16 v[108:111], v[166:169], v[198:201], v[108:111]
	v_mfma_f32_16x16x32_bf16 v[96:99], v[158:161], v[206:209], v[96:99]
	v_mfma_f32_16x16x32_bf16 v[92:95], v[166:169], v[206:209], v[92:95]
	v_mfma_f32_16x16x32_bf16 v[80:83], v[158:161], v[214:217], v[80:83]
	v_mfma_f32_16x16x32_bf16 v[76:79], v[166:169], v[214:217], v[76:79]
	v_mfma_f32_16x16x32_bf16 v[128:131], v[162:165], v[194:197], v[128:131]
	v_mfma_f32_16x16x32_bf16 v[124:127], v[170:173], v[194:197], v[124:127]
	v_mfma_f32_16x16x32_bf16 v[112:115], v[162:165], v[202:205], v[112:115]
	v_mfma_f32_16x16x32_bf16 v[108:111], v[170:173], v[202:205], v[108:111]
	v_mfma_f32_16x16x32_bf16 v[96:99], v[162:165], v[210:213], v[96:99]
	v_mfma_f32_16x16x32_bf16 v[92:95], v[170:173], v[210:213], v[92:95]
	v_mfma_f32_16x16x32_bf16 v[80:83], v[162:165], v[218:221], v[80:83]
	v_mfma_f32_16x16x32_bf16 v[76:79], v[170:173], v[218:221], v[76:79]
	v_mfma_f32_16x16x32_bf16 v[120:123], v[174:177], v[190:193], v[120:123]
	v_mfma_f32_16x16x32_bf16 v[116:119], v[182:185], v[190:193], v[116:119]
	v_mfma_f32_16x16x32_bf16 v[104:107], v[174:177], v[198:201], v[104:107]
	v_mfma_f32_16x16x32_bf16 v[100:103], v[182:185], v[198:201], v[100:103]
	v_mfma_f32_16x16x32_bf16 v[88:91], v[174:177], v[206:209], v[88:91]
	v_mfma_f32_16x16x32_bf16 v[84:87], v[182:185], v[206:209], v[84:87]
	v_mfma_f32_16x16x32_bf16 v[72:75], v[174:177], v[214:217], v[72:75]
	v_mfma_f32_16x16x32_bf16 v[68:71], v[182:185], v[214:217], v[68:71]
	v_mfma_f32_16x16x32_bf16 v[120:123], v[178:181], v[194:197], v[120:123]
	v_mfma_f32_16x16x32_bf16 v[116:119], v[186:189], v[194:197], v[116:119]
	v_mfma_f32_16x16x32_bf16 v[104:107], v[178:181], v[202:205], v[104:107]
	v_mfma_f32_16x16x32_bf16 v[100:103], v[186:189], v[202:205], v[100:103]
	v_mfma_f32_16x16x32_bf16 v[88:91], v[178:181], v[210:213], v[88:91]
	v_mfma_f32_16x16x32_bf16 v[84:87], v[186:189], v[210:213], v[84:87]
	v_mfma_f32_16x16x32_bf16 v[72:75], v[178:181], v[218:221], v[72:75]
	v_mfma_f32_16x16x32_bf16 v[68:71], v[186:189], v[218:221], v[68:71]
	s_setprio 0
	s_barrier
	s_add_i32 s42, s69, s4
	s_add_u32 s98, vcc_lo, 0x80
	s_addc_u32 s99, vcc_hi, 0
	s_mov_b32 m0, s42
	ds_read_b128 v[190:193], v156 offset:49152
	ds_read_b128 v[194:197], v156 offset:50176
	ds_read_b128 v[198:201], v156 offset:51200
	ds_read_b128 v[202:205], v156 offset:52224
	ds_read_b128 v[206:209], v156 offset:53248
	ds_read_b128 v[210:213], v156 offset:54272
	ds_read_b128 v[214:217], v156 offset:55296
	ds_read_b128 v[218:221], v156 offset:56320
	global_load_lds_dwordx4 v134, s[98:99]
	s_add_i32 m0, s42, 0x2000
	s_add_u32 s42, vcc_lo, 0x80080
	s_addc_u32 s43, vcc_hi, 0
	s_add_i32 s69, s70, s4
	global_load_lds_dwordx4 v138, s[98:99]
	s_mov_b32 m0, s69
	s_nop 0
	global_load_lds_dwordx4 v134, s[42:43]
	s_add_i32 m0, s69, 0x2000
	s_nop 0
	global_load_lds_dwordx4 v138, s[42:43]
	s_waitcnt vmcnt(6)
	s_waitcnt lgkmcnt(0)
	s_barrier
	s_setprio 1
	v_mfma_f32_16x16x32_bf16 v[64:67], v[158:161], v[190:193], v[64:67]
	v_mfma_f32_16x16x32_bf16 v[60:63], v[166:169], v[190:193], v[60:63]
	v_mfma_f32_16x16x32_bf16 v[48:51], v[158:161], v[198:201], v[48:51]
	v_mfma_f32_16x16x32_bf16 v[44:47], v[166:169], v[198:201], v[44:47]
	v_mfma_f32_16x16x32_bf16 v[32:35], v[158:161], v[206:209], v[32:35]
	v_mfma_f32_16x16x32_bf16 v[28:31], v[166:169], v[206:209], v[28:31]
	v_mfma_f32_16x16x32_bf16 v[16:19], v[158:161], v[214:217], v[16:19]
	v_mfma_f32_16x16x32_bf16 v[12:15], v[166:169], v[214:217], v[12:15]
	v_mfma_f32_16x16x32_bf16 v[64:67], v[162:165], v[194:197], v[64:67]
	v_mfma_f32_16x16x32_bf16 v[60:63], v[170:173], v[194:197], v[60:63]
	v_mfma_f32_16x16x32_bf16 v[48:51], v[162:165], v[202:205], v[48:51]
	v_mfma_f32_16x16x32_bf16 v[44:47], v[170:173], v[202:205], v[44:47]
	v_mfma_f32_16x16x32_bf16 v[32:35], v[162:165], v[210:213], v[32:35]
	v_mfma_f32_16x16x32_bf16 v[28:31], v[170:173], v[210:213], v[28:31]
	v_mfma_f32_16x16x32_bf16 v[16:19], v[162:165], v[218:221], v[16:19]
	v_mfma_f32_16x16x32_bf16 v[12:15], v[170:173], v[218:221], v[12:15]
	v_mfma_f32_16x16x32_bf16 v[56:59], v[174:177], v[190:193], v[56:59]
	v_mfma_f32_16x16x32_bf16 v[52:55], v[182:185], v[190:193], v[52:55]
	v_mfma_f32_16x16x32_bf16 v[40:43], v[174:177], v[198:201], v[40:43]
	v_mfma_f32_16x16x32_bf16 v[36:39], v[182:185], v[198:201], v[36:39]
	v_mfma_f32_16x16x32_bf16 v[24:27], v[174:177], v[206:209], v[24:27]
	v_mfma_f32_16x16x32_bf16 v[20:23], v[182:185], v[206:209], v[20:23]
	v_mfma_f32_16x16x32_bf16 v[6:9], v[174:177], v[214:217], v[8:11]
	v_mfma_f32_16x16x32_bf16 v[2:5], v[182:185], v[214:217], v[2:5]
	v_mfma_f32_16x16x32_bf16 v[56:59], v[178:181], v[194:197], v[56:59]
	v_mfma_f32_16x16x32_bf16 v[52:55], v[186:189], v[194:197], v[52:55]
	v_mfma_f32_16x16x32_bf16 v[40:43], v[178:181], v[202:205], v[40:43]
	v_mfma_f32_16x16x32_bf16 v[36:39], v[186:189], v[202:205], v[36:39]
	v_mfma_f32_16x16x32_bf16 v[24:27], v[178:181], v[210:213], v[24:27]
	v_mfma_f32_16x16x32_bf16 v[20:23], v[186:189], v[210:213], v[20:23]
	v_mfma_f32_16x16x32_bf16 v[8:11], v[178:181], v[218:221], v[6:9]
	v_mfma_f32_16x16x32_bf16 v[4:7], v[186:189], v[218:221], v[2:5]
	s_setprio 0
	s_barrier
	s_add_i32 s68, s68, 2
	s_add_u32 s18, s18, 0x100
	s_addc_u32 s19, s19, 0
	s_cmp_gt_u32 s68, 29
	s_cbranch_scc1 .LBB0_1220

; #define PG8_STAGE(bufoff, gbase, voff) do { _Pragma("unroll") for (int _i = 0; _i < 2; ++_i) \
;         __builtin_amdgcn_global_load_lds((const unsigned*)((const char*)(gbase) + (voff)[_i]), (PG8_LAS unsigned*)(lds + (bufoff) + ldsw + _i * 8192), 16, 0, 0); } while (0)
; #define PG8_LDA(dst, b, h) do { _Pragma("unroll") for (int m = 0; m < 4; ++m) _Pragma("unroll") for (int k = 0; k < 2; ++k) dst[m][k] = *(const PG8_LAS bf16x8*)(lds + PG8_SA(b, h) + aoff + m * 2048 + k * 1024); } while (0)
; #define PG8_LDB(dst, b, h) do { _Pragma("unroll") for (int n = 0; n < 2; ++n) _Pragma("unroll") for (int k = 0; k < 2; ++k) dst[n][k] = *(const PG8_LAS bf16x8*)(lds + PG8_SB(b, h) + boff + n * 2048 + k * 1024); } while (0)
; #define PG8_WAIT_V(n) asm volatile("s_waitcnt vmcnt(" #n ")" ::: "memory")
; #define PG8_WAIT_L(n) asm volatile("s_waitcnt lgkmcnt(" #n ")" ::: "memory")
; #define PG8_BAR __builtin_amdgcn_s_barrier()
; #define PG8_SCHED __builtin_amdgcn_sched_barrier(0)
; template <class Epi, class Sched, bool ALIGN_EPI = false, bool SP2 = false>
; __device__ __forceinline__ void gemm_phase(PG8_LAS unsigned char* lds, const Gemm g, const Sched& S, const Epi& E) {
;     ...
;         const char* nA = has_next ? (const char*)g.A + (size_t)nxt.pm * tstepA : cA; const char* nB = has_next ? (const char*)g.Bt + (size_t)nxt.pn * tstepB : cB;
;         for (int t = 0; t < nt; t += 2) {
;             const bool last = (t == nt - 2);
;             if constexpr (Epi::HAS_MID) { if (t == E.mid_t) E.mid(acc, cur, wr, wc, fr, fq); }
;             const char* a1 = cA + (size_t)(t + 1) * kstep;
;             const char* a2 = last ? nA : cA + (size_t)(t + 2) * kstep; const char* b2 = last ? nB : cB + (size_t)(t + 2) * kstep;
;             const char* a3 = a2 + kstep; const char* b3 = b2 + kstep;
;             if (last && has_next) S.a_ready(nxt);
;             if constexpr (SP2) {
;             PG8_LDB(B0, 0, 0); PG8_LDB(B1, 0, 1); PG8_SCHED; PG8_LDA(At, 0, 0); PG8_STAGE(PG8_SA(1, 1), a1 + hstepA, voffA);
;             PG8_WAIT_V(8); PG8_WAIT_L(0); PG8_BAR; PG8_MMA(0, 0, At, B0); PG8_MMA(0, 1, At, B1); PG8_BAR; PG8_SCHED;
;             PG8_LDA(At, 0, 1); PG8_STAGE(PG8_SB(0, 0), b2, voffB); PG8_STAGE(PG8_SB(0, 1), b2 + hstepB, voffB); PG8_STAGE(PG8_SA(0, 0), a2, voffA);
;             PG8_WAIT_V(8); PG8_WAIT_L(0); PG8_BAR; PG8_MMA(1, 0, At, B0); PG8_MMA(1, 1, At, B1); PG8_BAR; PG8_SCHED;
.LBB0_1309:
	ds_read_b128 v[128:131], v161
	ds_read_b128 v[132:135], v161 offset:1024
	ds_read_b128 v[148:151], v161 offset:2048
	ds_read_b128 v[152:155], v161 offset:3072
	ds_read_b128 v[166:169], v162
	ds_read_b128 v[170:173], v162 offset:1024
	ds_read_b128 v[174:177], v162 offset:2048
	ds_read_b128 v[178:181], v162 offset:3072
	s_add_u32 s16, s12, 0xfff80080
	s_addc_u32 s17, s13, -1
	s_cmp_eq_u32 s65, 28
	s_cselect_b32 s19, s39, s17
	s_cselect_b32 s18, s59, s16
	s_cselect_b32 s17, s37, s63
	s_cselect_b32 s16, s61, s62
	s_add_i32 m0, s5, 0xc000
	ds_read_b128 v[182:185], v163
	ds_read_b128 v[186:189], v163 offset:1024
	ds_read_b128 v[190:193], v163 offset:2048
	ds_read_b128 v[194:197], v163 offset:3072
	ds_read_b128 v[198:201], v163 offset:4096
	ds_read_b128 v[202:205], v163 offset:5120
	ds_read_b128 v[206:209], v163 offset:6144
	ds_read_b128 v[210:213], v163 offset:7168
	s_add_u32 s98, s12, 0xfff80000
	s_addc_u32 s99, s13, -1
	s_mov_b32 m0, s33
	s_nop 0
	global_load_lds_dwordx4 v136, s[98:99]
	s_mov_b32 m0, s34
	s_nop 0
	global_load_lds_dwordx4 v140, s[98:99]
	s_add_i32 m0, s5, 0xc000
	s_nop 0
	global_load_lds_dwordx4 v144, s[12:13]
	s_add_i32 m0, s5, 0xe000
	s_nop 0
	global_load_lds_dwordx4 v146, s[12:13]
	s_waitcnt vmcnt(8)
	s_waitcnt lgkmcnt(0)
	s_barrier
	s_setprio 1
	v_mfma_f32_16x16x32_bf16 v[124:127], v[128:131], v[182:185], v[124:127]
	v_mfma_f32_16x16x32_bf16 v[120:123], v[148:151], v[182:185], v[120:123]
	v_mfma_f32_16x16x32_bf16 v[108:111], v[128:131], v[190:193], v[108:111]
	v_mfma_f32_16x16x32_bf16 v[104:107], v[148:151], v[190:193], v[104:107]
	v_mfma_f32_16x16x32_bf16 v[92:95], v[128:131], v[198:201], v[92:95]
	v_mfma_f32_16x16x32_bf16 v[88:91], v[148:151], v[198:201], v[88:91]
	v_mfma_f32_16x16x32_bf16 v[76:79], v[128:131], v[206:209], v[76:79]
	v_mfma_f32_16x16x32_bf16 v[72:75], v[148:151], v[206:209], v[72:75]
	v_mfma_f32_16x16x32_bf16 v[124:127], v[132:135], v[186:189], v[124:127]
	v_mfma_f32_16x16x32_bf16 v[120:123], v[152:155], v[186:189], v[120:123]
	v_mfma_f32_16x16x32_bf16 v[108:111], v[132:135], v[194:197], v[108:111]
	v_mfma_f32_16x16x32_bf16 v[104:107], v[152:155], v[194:197], v[104:107]
	v_mfma_f32_16x16x32_bf16 v[92:95], v[132:135], v[202:205], v[92:95]
	v_mfma_f32_16x16x32_bf16 v[88:91], v[152:155], v[202:205], v[88:91]
	v_mfma_f32_16x16x32_bf16 v[76:79], v[132:135], v[210:213], v[76:79]
	v_mfma_f32_16x16x32_bf16 v[72:75], v[152:155], v[210:213], v[72:75]
	v_mfma_f32_16x16x32_bf16 v[116:119], v[166:169], v[182:185], v[116:119]
	v_mfma_f32_16x16x32_bf16 v[112:115], v[174:177], v[182:185], v[112:115]
	v_mfma_f32_16x16x32_bf16 v[100:103], v[166:169], v[190:193], v[100:103]
	v_mfma_f32_16x16x32_bf16 v[96:99], v[174:177], v[190:193], v[96:99]
	v_mfma_f32_16x16x32_bf16 v[84:87], v[166:169], v[198:201], v[84:87]
	v_mfma_f32_16x16x32_bf16 v[80:83], v[174:177], v[198:201], v[80:83]
	v_mfma_f32_16x16x32_bf16 v[68:71], v[166:169], v[206:209], v[68:71]
	v_mfma_f32_16x16x32_bf16 v[64:67], v[174:177], v[206:209], v[64:67]
	v_mfma_f32_16x16x32_bf16 v[116:119], v[170:173], v[186:189], v[116:119]
	v_mfma_f32_16x16x32_bf16 v[112:115], v[178:181], v[186:189], v[112:115]
	v_mfma_f32_16x16x32_bf16 v[100:103], v[170:173], v[194:197], v[100:103]
	v_mfma_f32_16x16x32_bf16 v[96:99], v[178:181], v[194:197], v[96:99]
	v_mfma_f32_16x16x32_bf16 v[84:87], v[170:173], v[202:205], v[84:87]
	v_mfma_f32_16x16x32_bf16 v[80:83], v[178:181], v[202:205], v[80:83]
	v_mfma_f32_16x16x32_bf16 v[68:71], v[170:173], v[210:213], v[68:71]
	v_mfma_f32_16x16x32_bf16 v[64:67], v[178:181], v[210:213], v[64:67]
	s_setprio 0
	s_barrier
	s_add_i32 s66, s56, s4
	s_mov_b32 m0, s66
	ds_read_b128 v[182:185], v163 offset:16384
	ds_read_b128 v[186:189], v163 offset:17408
	ds_read_b128 v[190:193], v163 offset:18432
	ds_read_b128 v[194:197], v163 offset:19456
	ds_read_b128 v[198:201], v163 offset:20480
	ds_read_b128 v[202:205], v163 offset:21504
	ds_read_b128 v[206:209], v163 offset:22528
	ds_read_b128 v[210:213], v163 offset:23552
	global_load_lds_dwordx4 v138, s[16:17]
	s_add_i32 m0, s66, 0x2000
	s_add_u32 s66, s16, 0x80000
	s_addc_u32 s67, s17, 0
	s_add_i32 s68, s57, s4
	global_load_lds_dwordx4 v142, s[16:17]
	s_mov_b32 m0, s68
	s_nop 0
	global_load_lds_dwordx4 v138, s[66:67]
	s_add_i32 m0, s68, 0x2000
	s_nop 0
	global_load_lds_dwordx4 v142, s[66:67]
	s_waitcnt vmcnt(6)
	s_waitcnt lgkmcnt(0)
	s_barrier
	s_setprio 1
	v_mfma_f32_16x16x32_bf16 v[60:63], v[128:131], v[182:185], v[60:63]
	v_mfma_f32_16x16x32_bf16 v[56:59], v[148:151], v[182:185], v[56:59]
	v_mfma_f32_16x16x32_bf16 v[44:47], v[128:131], v[190:193], v[44:47]
	v_mfma_f32_16x16x32_bf16 v[40:43], v[148:151], v[190:193], v[40:43]
	v_mfma_f32_16x16x32_bf16 v[28:31], v[128:131], v[198:201], v[28:31]
	v_mfma_f32_16x16x32_bf16 v[24:27], v[148:151], v[198:201], v[24:27]
	v_mfma_f32_16x16x32_bf16 v[12:15], v[128:131], v[206:209], v[12:15]
	v_mfma_f32_16x16x32_bf16 v[8:11], v[148:151], v[206:209], v[8:11]
	v_mfma_f32_16x16x32_bf16 v[60:63], v[132:135], v[186:189], v[60:63]
	v_mfma_f32_16x16x32_bf16 v[56:59], v[152:155], v[186:189], v[56:59]
	v_mfma_f32_16x16x32_bf16 v[44:47], v[132:135], v[194:197], v[44:47]
	v_mfma_f32_16x16x32_bf16 v[40:43], v[152:155], v[194:197], v[40:43]
	v_mfma_f32_16x16x32_bf16 v[28:31], v[132:135], v[202:205], v[28:31]
	v_mfma_f32_16x16x32_bf16 v[24:27], v[152:155], v[202:205], v[24:27]
	v_mfma_f32_16x16x32_bf16 v[12:15], v[132:135], v[210:213], v[12:15]
	v_mfma_f32_16x16x32_bf16 v[8:11], v[152:155], v[210:213], v[8:11]
	v_mfma_f32_16x16x32_bf16 v[52:55], v[166:169], v[182:185], v[52:55]
	v_mfma_f32_16x16x32_bf16 v[48:51], v[174:177], v[182:185], v[48:51]
	v_mfma_f32_16x16x32_bf16 v[36:39], v[166:169], v[190:193], v[36:39]
	v_mfma_f32_16x16x32_bf16 v[32:35], v[174:177], v[190:193], v[32:35]
	v_mfma_f32_16x16x32_bf16 v[20:23], v[166:169], v[198:201], v[20:23]
	v_mfma_f32_16x16x32_bf16 v[16:19], v[174:177], v[198:201], v[16:19]
	v_mfma_f32_16x16x32_bf16 v[4:7], v[166:169], v[206:209], v[4:7]
	v_mfma_f32_16x16x32_bf16 v[0:3], v[174:177], v[206:209], v[0:3]
	v_mfma_f32_16x16x32_bf16 v[52:55], v[170:173], v[186:189], v[52:55]
	v_mfma_f32_16x16x32_bf16 v[48:51], v[178:181], v[186:189], v[48:51]
	v_mfma_f32_16x16x32_bf16 v[36:39], v[170:173], v[194:197], v[36:39]
	v_mfma_f32_16x16x32_bf16 v[32:35], v[178:181], v[194:197], v[32:35]
	v_mfma_f32_16x16x32_bf16 v[20:23], v[170:173], v[202:205], v[20:23]
	v_mfma_f32_16x16x32_bf16 v[16:19], v[178:181], v[202:205], v[16:19]
	v_mfma_f32_16x16x32_bf16 v[4:7], v[170:173], v[210:213], v[4:7]
	v_mfma_f32_16x16x32_bf16 v[0:3], v[178:181], v[210:213], v[0:3]
	s_setprio 0
	s_barrier
; #define PG8_STAGE(bufoff, gbase, voff) do { _Pragma("unroll") for (int _i = 0; _i < 2; ++_i) \
;         __builtin_amdgcn_global_load_lds((const unsigned*)((const char*)(gbase) + (voff)[_i]), (PG8_LAS unsigned*)(lds + (bufoff) + ldsw + _i * 8192), 16, 0, 0); } while (0)
; #define PG8_LDA(dst, b, h) do { _Pragma("unroll") for (int m = 0; m < 4; ++m) _Pragma("unroll") for (int k = 0; k < 2; ++k) dst[m][k] = *(const PG8_LAS bf16x8*)(lds + PG8_SA(b, h) + aoff + m * 2048 + k * 1024); } while (0)
; #define PG8_WAIT_V(n) asm volatile("s_waitcnt vmcnt(" #n ")" ::: "memory")
; #define PG8_BAR __builtin_amdgcn_s_barrier()
; template <class Epi, class Sched, bool ALIGN_EPI = false, bool SP2 = false>
; __device__ __forceinline__ void gemm_phase(PG8_LAS unsigned char* lds, const Gemm g, const Sched& S, const Epi& E) {
;     ...
;         for (int t = 0; t < nt; t += 2) {
;             const bool last = (t == nt - 2);
;             if constexpr (Epi::HAS_MID) { if (t == E.mid_t) E.mid(acc, cur, wr, wc, fr, fq); }
;             const char* a1 = cA + (size_t)(t + 1) * kstep;
;             const char* a2 = last ? nA : cA + (size_t)(t + 2) * kstep; const char* b2 = last ? nB : cB + (size_t)(t + 2) * kstep;
;             const char* a3 = a2 + kstep; const char* b3 = b2 + kstep;
;             if (last && has_next) S.a_ready(nxt);
;             if constexpr (SP2) {
;             PG8_LDB(B0, 0, 0); PG8_LDB(B1, 0, 1); PG8_SCHED; PG8_LDA(At, 0, 0); PG8_STAGE(PG8_SA(1, 1), a1 + hstepA, voffA);
;             PG8_WAIT_V(8); PG8_WAIT_L(0); PG8_BAR; PG8_MMA(0, 0, At, B0); PG8_MMA(0, 1, At, B1); PG8_BAR; PG8_SCHED;
;             PG8_LDA(At, 0, 1); PG8_STAGE(PG8_SB(0, 0), b2, voffB); PG8_STAGE(PG8_SB(0, 1), b2 + hstepB, voffB); PG8_STAGE(PG8_SA(0, 0), a2, voffA);
;             PG8_WAIT_V(8); PG8_WAIT_L(0); PG8_BAR; PG8_MMA(1, 0, At, B0); PG8_MMA(1, 1, At, B1); PG8_BAR; PG8_SCHED;
;             PG8_LDB(B0, 1, 0); PG8_LDB(B1, 1, 1); PG8_SCHED; PG8_LDA(At, 1, 0); PG8_STAGE(PG8_SA(0, 1), a2 + hstepA, voffA);
;             PG8_WAIT_V(8); PG8_WAIT_L(0); PG8_BAR; PG8_MMA(0, 0, At, B0); PG8_MMA(0, 1, At, B1); PG8_BAR; PG8_SCHED;
;             PG8_LDA(At, 1, 1); PG8_STAGE(PG8_SB(1, 0), b3, voffB); PG8_STAGE(PG8_SB(1, 1), b3 + hstepB, voffB); PG8_STAGE(PG8_SA(1, 0), a3, voffA);
;             PG8_WAIT_V(8); PG8_WAIT_L(0); PG8_BAR; PG8_MMA(1, 0, At, B0); PG8_MMA(1, 1, At, B1); PG8_BAR; PG8_SCHED;
	s_add_i32 s66, 0, 0x18000
	s_add_i32 s67, 0, 0x1c000
	v_add_u32_e32 v152, s66, v160
	v_add_u32_e32 v165, s67, v160
	ds_read_b128 v[128:131], v152
	ds_read_b128 v[132:135], v152 offset:1024
	ds_read_b128 v[148:151], v152 offset:2048
	ds_read_b128 v[152:155], v152 offset:3072
	ds_read_b128 v[166:169], v165
	ds_read_b128 v[170:173], v165 offset:1024
	ds_read_b128 v[174:177], v165 offset:2048
	ds_read_b128 v[178:181], v165 offset:3072
	s_mov_b64 s[100:101], s[18:19]
	s_add_u32 s18, s18, 0x80000
	s_addc_u32 s19, s19, 0
	s_mov_b32 m0, s7
	ds_read_b128 v[182:185], v163 offset:32768
	ds_read_b128 v[186:189], v163 offset:33792
	ds_read_b128 v[190:193], v163 offset:34816
	ds_read_b128 v[194:197], v163 offset:35840
	ds_read_b128 v[198:201], v163 offset:36864
	ds_read_b128 v[202:205], v163 offset:37888
	ds_read_b128 v[206:209], v163 offset:38912
	ds_read_b128 v[210:213], v163 offset:39936
	s_mov_b32 m0, s5
	s_nop 0
	global_load_lds_dwordx4 v136, s[100:101]
	s_mov_b32 m0, s6
	s_nop 0
	global_load_lds_dwordx4 v140, s[100:101]
	s_mov_b32 m0, s7
	s_nop 0
	global_load_lds_dwordx4 v136, s[18:19]
	s_mov_b32 m0, s20
	s_nop 0
	global_load_lds_dwordx4 v140, s[18:19]
	s_waitcnt vmcnt(8)
	s_waitcnt lgkmcnt(0)
	s_barrier
	s_setprio 1
	v_mfma_f32_16x16x32_bf16 v[124:127], v[128:131], v[182:185], v[124:127]
	v_mfma_f32_16x16x32_bf16 v[120:123], v[148:151], v[182:185], v[120:123]
	v_mfma_f32_16x16x32_bf16 v[108:111], v[128:131], v[190:193], v[108:111]
	v_mfma_f32_16x16x32_bf16 v[104:107], v[148:151], v[190:193], v[104:107]
	v_mfma_f32_16x16x32_bf16 v[92:95], v[128:131], v[198:201], v[92:95]
	v_mfma_f32_16x16x32_bf16 v[88:91], v[148:151], v[198:201], v[88:91]
	v_mfma_f32_16x16x32_bf16 v[76:79], v[128:131], v[206:209], v[76:79]
	v_mfma_f32_16x16x32_bf16 v[72:75], v[148:151], v[206:209], v[72:75]
	v_mfma_f32_16x16x32_bf16 v[124:127], v[132:135], v[186:189], v[124:127]
	v_mfma_f32_16x16x32_bf16 v[120:123], v[152:155], v[186:189], v[120:123]
	v_mfma_f32_16x16x32_bf16 v[108:111], v[132:135], v[194:197], v[108:111]
	v_mfma_f32_16x16x32_bf16 v[104:107], v[152:155], v[194:197], v[104:107]
	v_mfma_f32_16x16x32_bf16 v[92:95], v[132:135], v[202:205], v[92:95]
	v_mfma_f32_16x16x32_bf16 v[88:91], v[152:155], v[202:205], v[88:91]
	v_mfma_f32_16x16x32_bf16 v[76:79], v[132:135], v[210:213], v[76:79]
	v_mfma_f32_16x16x32_bf16 v[72:75], v[152:155], v[210:213], v[72:75]
	v_mfma_f32_16x16x32_bf16 v[116:119], v[166:169], v[182:185], v[116:119]
	v_mfma_f32_16x16x32_bf16 v[112:115], v[174:177], v[182:185], v[112:115]
	v_mfma_f32_16x16x32_bf16 v[100:103], v[166:169], v[190:193], v[100:103]
	v_mfma_f32_16x16x32_bf16 v[96:99], v[174:177], v[190:193], v[96:99]
	v_mfma_f32_16x16x32_bf16 v[84:87], v[166:169], v[198:201], v[84:87]
	v_mfma_f32_16x16x32_bf16 v[80:83], v[174:177], v[198:201], v[80:83]
	v_mfma_f32_16x16x32_bf16 v[68:71], v[166:169], v[206:209], v[68:71]
	v_mfma_f32_16x16x32_bf16 v[64:67], v[174:177], v[206:209], v[64:67]
	v_mfma_f32_16x16x32_bf16 v[116:119], v[170:173], v[186:189], v[116:119]
	v_mfma_f32_16x16x32_bf16 v[112:115], v[178:181], v[186:189], v[112:115]
	v_mfma_f32_16x16x32_bf16 v[100:103], v[170:173], v[194:197], v[100:103]
	v_mfma_f32_16x16x32_bf16 v[96:99], v[178:181], v[194:197], v[96:99]
	v_mfma_f32_16x16x32_bf16 v[84:87], v[170:173], v[202:205], v[84:87]
	v_mfma_f32_16x16x32_bf16 v[80:83], v[178:181], v[202:205], v[80:83]
	v_mfma_f32_16x16x32_bf16 v[68:71], v[170:173], v[210:213], v[68:71]
	v_mfma_f32_16x16x32_bf16 v[64:67], v[178:181], v[210:213], v[64:67]
	s_setprio 0
	s_barrier
	s_add_i32 s18, s66, s4
	s_add_u32 s98, s16, 0x80
	s_addc_u32 s99, s17, 0
	s_mov_b32 m0, s18
	ds_read_b128 v[182:185], v163 offset:49152
	ds_read_b128 v[186:189], v163 offset:50176
	ds_read_b128 v[190:193], v163 offset:51200
	ds_read_b128 v[194:197], v163 offset:52224
	ds_read_b128 v[198:201], v163 offset:53248
	ds_read_b128 v[202:205], v163 offset:54272
	ds_read_b128 v[206:209], v163 offset:55296
	ds_read_b128 v[210:213], v163 offset:56320
	global_load_lds_dwordx4 v138, s[98:99]
	s_add_i32 m0, s18, 0x2000
	s_add_u32 s16, s16, 0x80080
	s_addc_u32 s17, s17, 0
	s_add_i32 s18, s67, s4
	global_load_lds_dwordx4 v142, s[98:99]
	s_mov_b32 m0, s18
	s_nop 0
	global_load_lds_dwordx4 v138, s[16:17]
	s_add_i32 m0, s18, 0x2000
	s_nop 0
	global_load_lds_dwordx4 v142, s[16:17]
	s_waitcnt vmcnt(6)
	s_waitcnt lgkmcnt(0)
	s_barrier
	s_setprio 1
	v_mfma_f32_16x16x32_bf16 v[60:63], v[128:131], v[182:185], v[60:63]
	v_mfma_f32_16x16x32_bf16 v[56:59], v[148:151], v[182:185], v[56:59]
	v_mfma_f32_16x16x32_bf16 v[44:47], v[128:131], v[190:193], v[44:47]
	v_mfma_f32_16x16x32_bf16 v[40:43], v[148:151], v[190:193], v[40:43]
	v_mfma_f32_16x16x32_bf16 v[28:31], v[128:131], v[198:201], v[28:31]
	v_mfma_f32_16x16x32_bf16 v[24:27], v[148:151], v[198:201], v[24:27]
	v_mfma_f32_16x16x32_bf16 v[12:15], v[128:131], v[206:209], v[12:15]
	v_mfma_f32_16x16x32_bf16 v[8:11], v[148:151], v[206:209], v[8:11]
	v_mfma_f32_16x16x32_bf16 v[60:63], v[132:135], v[186:189], v[60:63]
	v_mfma_f32_16x16x32_bf16 v[56:59], v[152:155], v[186:189], v[56:59]
	v_mfma_f32_16x16x32_bf16 v[44:47], v[132:135], v[194:197], v[44:47]
	v_mfma_f32_16x16x32_bf16 v[40:43], v[152:155], v[194:197], v[40:43]
	v_mfma_f32_16x16x32_bf16 v[28:31], v[132:135], v[202:205], v[28:31]
	v_mfma_f32_16x16x32_bf16 v[24:27], v[152:155], v[202:205], v[24:27]
	v_mfma_f32_16x16x32_bf16 v[12:15], v[132:135], v[210:213], v[12:15]
	v_mfma_f32_16x16x32_bf16 v[8:11], v[152:155], v[210:213], v[8:11]
	v_mfma_f32_16x16x32_bf16 v[52:55], v[166:169], v[182:185], v[52:55]
	v_mfma_f32_16x16x32_bf16 v[48:51], v[174:177], v[182:185], v[48:51]
	v_mfma_f32_16x16x32_bf16 v[36:39], v[166:169], v[190:193], v[36:39]
	v_mfma_f32_16x16x32_bf16 v[32:35], v[174:177], v[190:193], v[32:35]
	v_mfma_f32_16x16x32_bf16 v[20:23], v[166:169], v[198:201], v[20:23]
	v_mfma_f32_16x16x32_bf16 v[16:19], v[174:177], v[198:201], v[16:19]
	v_mfma_f32_16x16x32_bf16 v[4:7], v[166:169], v[206:209], v[4:7]
	v_mfma_f32_16x16x32_bf16 v[0:3], v[174:177], v[206:209], v[0:3]
	v_mfma_f32_16x16x32_bf16 v[52:55], v[170:173], v[186:189], v[52:55]
	v_mfma_f32_16x16x32_bf16 v[48:51], v[178:181], v[186:189], v[48:51]
	v_mfma_f32_16x16x32_bf16 v[36:39], v[170:173], v[194:197], v[36:39]
	v_mfma_f32_16x16x32_bf16 v[32:35], v[178:181], v[194:197], v[32:35]
	v_mfma_f32_16x16x32_bf16 v[20:23], v[170:173], v[202:205], v[20:23]
	v_mfma_f32_16x16x32_bf16 v[16:19], v[178:181], v[202:205], v[16:19]
	v_mfma_f32_16x16x32_bf16 v[4:7], v[170:173], v[210:213], v[4:7]
	v_mfma_f32_16x16x32_bf16 v[0:3], v[178:181], v[210:213], v[0:3]
	s_setprio 0
	s_barrier
	s_add_i32 s65, s65, 2
	s_add_u32 s12, s12, 0x100
	s_addc_u32 s13, s13, 0
	s_add_u32 s62, s62, 0x100
	s_addc_u32 s63, s63, 0
	s_cmp_gt_u32 s65, 29
	s_cbranch_scc0 .LBB0_1309
	s_and_b64 vcc, exec, s[26:27]
	s_cbranch_vccz .LBB0_1312
	s_barrier

; #define PG8_STAGE(bufoff, gbase, voff) do { _Pragma("unroll") for (int _i = 0; _i < 2; ++_i) \
;         __builtin_amdgcn_global_load_lds((const unsigned*)((const char*)(gbase) + (voff)[_i]), (PG8_LAS unsigned*)(lds + (bufoff) + ldsw + _i * 8192), 16, 0, 0); } while (0)
; #define PG8_LDA(dst, b, h) do { _Pragma("unroll") for (int m = 0; m < 4; ++m) _Pragma("unroll") for (int k = 0; k < 2; ++k) dst[m][k] = *(const PG8_LAS bf16x8*)(lds + PG8_SA(b, h) + aoff + m * 2048 + k * 1024); } while (0)
; #define PG8_LDB(dst, b, h) do { _Pragma("unroll") for (int n = 0; n < 2; ++n) _Pragma("unroll") for (int k = 0; k < 2; ++k) dst[n][k] = *(const PG8_LAS bf16x8*)(lds + PG8_SB(b, h) + boff + n * 2048 + k * 1024); } while (0)
; #define PG8_WAIT_V(n) asm volatile("s_waitcnt vmcnt(" #n ")" ::: "memory")
; #define PG8_WAIT_L(n) asm volatile("s_waitcnt lgkmcnt(" #n ")" ::: "memory")
; #define PG8_BAR __builtin_amdgcn_s_barrier()
; #define PG8_SCHED __builtin_amdgcn_sched_barrier(0)
; template <class Epi, class Sched, bool ALIGN_EPI = false, bool SP2 = false>
; __device__ __forceinline__ void gemm_phase(PG8_LAS unsigned char* lds, const Gemm g, const Sched& S, const Epi& E) {
;     ...
;         const char* nA = has_next ? (const char*)g.A + (size_t)nxt.pm * tstepA : cA; const char* nB = has_next ? (const char*)g.Bt + (size_t)nxt.pn * tstepB : cB;
;         for (int t = 0; t < nt; t += 2) {
;             const bool last = (t == nt - 2);
;             if constexpr (Epi::HAS_MID) { if (t == E.mid_t) E.mid(acc, cur, wr, wc, fr, fq); }
;             const char* a1 = cA + (size_t)(t + 1) * kstep;
;             const char* a2 = last ? nA : cA + (size_t)(t + 2) * kstep; const char* b2 = last ? nB : cB + (size_t)(t + 2) * kstep;
;             const char* a3 = a2 + kstep; const char* b3 = b2 + kstep;
;             if (last && has_next) S.a_ready(nxt);
;             if constexpr (SP2) {
;             PG8_LDB(B0, 0, 0); PG8_LDB(B1, 0, 1); PG8_SCHED; PG8_LDA(At, 0, 0); PG8_STAGE(PG8_SA(1, 1), a1 + hstepA, voffA);
;             PG8_WAIT_V(8); PG8_WAIT_L(0); PG8_BAR; PG8_MMA(0, 0, At, B0); PG8_MMA(0, 1, At, B1); PG8_BAR; PG8_SCHED;
;             PG8_LDA(At, 0, 1); PG8_STAGE(PG8_SB(0, 0), b2, voffB); PG8_STAGE(PG8_SB(0, 1), b2 + hstepB, voffB); PG8_STAGE(PG8_SA(0, 0), a2, voffA);
;             PG8_WAIT_V(8); PG8_WAIT_L(0); PG8_BAR; PG8_MMA(1, 0, At, B0); PG8_MMA(1, 1, At, B1); PG8_BAR; PG8_SCHED;
.LBB0_1363:
	ds_read_b128 v[128:131], v169
	ds_read_b128 v[132:135], v169 offset:1024
	ds_read_b128 v[148:151], v169 offset:2048
	ds_read_b128 v[152:155], v169 offset:3072
	ds_read_b128 v[156:159], v170
	ds_read_b128 v[160:163], v170 offset:1024
	ds_read_b128 v[174:177], v170 offset:2048
	ds_read_b128 v[178:181], v170 offset:3072
	s_add_u32 s20, s16, 0xfff80080
	s_addc_u32 s21, s17, -1
	s_cmp_eq_u32 s63, 28
	s_cselect_b32 s35, s13, s21
	s_cselect_b32 s34, s19, s20
	s_cselect_b32 s21, s29, s62
	s_cselect_b32 s20, s31, s61
	v_lshl_add_u64 v[164:165], s[16:17], 0, v[144:145]
	s_add_i32 m0, s6, 0xc000
	ds_read_b128 v[182:185], v171
	ds_read_b128 v[186:189], v171 offset:1024
	ds_read_b128 v[190:193], v171 offset:2048
	ds_read_b128 v[194:197], v171 offset:3072
	ds_read_b128 v[198:201], v171 offset:4096
	ds_read_b128 v[202:205], v171 offset:5120
	ds_read_b128 v[206:209], v171 offset:6144
	ds_read_b128 v[210:213], v171 offset:7168
	global_load_lds_dwordx4 v[164:165], off
	v_lshl_add_u64 v[164:165], s[16:17], 0, v[146:147]
	s_add_i32 m0, s6, 0xe000
	s_nop 0
	global_load_lds_dwordx4 v[164:165], off
	s_waitcnt vmcnt(8)
	s_waitcnt lgkmcnt(0)
	s_barrier
	s_setprio 1
	v_mfma_f32_16x16x32_bf16 v[124:127], v[128:131], v[182:185], v[124:127]
	v_mfma_f32_16x16x32_bf16 v[120:123], v[148:151], v[182:185], v[120:123]
	v_mfma_f32_16x16x32_bf16 v[108:111], v[128:131], v[190:193], v[108:111]
	v_mfma_f32_16x16x32_bf16 v[104:107], v[148:151], v[190:193], v[104:107]
	v_mfma_f32_16x16x32_bf16 v[92:95], v[128:131], v[198:201], v[92:95]
	v_mfma_f32_16x16x32_bf16 v[88:91], v[148:151], v[198:201], v[88:91]
	v_mfma_f32_16x16x32_bf16 v[76:79], v[128:131], v[206:209], v[76:79]
	v_mfma_f32_16x16x32_bf16 v[72:75], v[148:151], v[206:209], v[72:75]
	v_mfma_f32_16x16x32_bf16 v[124:127], v[132:135], v[186:189], v[124:127]
	v_mfma_f32_16x16x32_bf16 v[120:123], v[152:155], v[186:189], v[120:123]
	v_mfma_f32_16x16x32_bf16 v[108:111], v[132:135], v[194:197], v[108:111]
	v_mfma_f32_16x16x32_bf16 v[104:107], v[152:155], v[194:197], v[104:107]
	v_mfma_f32_16x16x32_bf16 v[92:95], v[132:135], v[202:205], v[92:95]
	v_mfma_f32_16x16x32_bf16 v[88:91], v[152:155], v[202:205], v[88:91]
	v_mfma_f32_16x16x32_bf16 v[76:79], v[132:135], v[210:213], v[76:79]
	v_mfma_f32_16x16x32_bf16 v[72:75], v[152:155], v[210:213], v[72:75]
	v_mfma_f32_16x16x32_bf16 v[116:119], v[156:159], v[182:185], v[116:119]
	v_mfma_f32_16x16x32_bf16 v[112:115], v[174:177], v[182:185], v[112:115]
	v_mfma_f32_16x16x32_bf16 v[100:103], v[156:159], v[190:193], v[100:103]
	v_mfma_f32_16x16x32_bf16 v[96:99], v[174:177], v[190:193], v[96:99]
	v_mfma_f32_16x16x32_bf16 v[84:87], v[156:159], v[198:201], v[84:87]
	v_mfma_f32_16x16x32_bf16 v[80:83], v[174:177], v[198:201], v[80:83]
	v_mfma_f32_16x16x32_bf16 v[68:71], v[156:159], v[206:209], v[68:71]
	v_mfma_f32_16x16x32_bf16 v[64:67], v[174:177], v[206:209], v[64:67]
	v_mfma_f32_16x16x32_bf16 v[116:119], v[160:163], v[186:189], v[116:119]
	v_mfma_f32_16x16x32_bf16 v[112:115], v[178:181], v[186:189], v[112:115]
	v_mfma_f32_16x16x32_bf16 v[100:103], v[160:163], v[194:197], v[100:103]
	v_mfma_f32_16x16x32_bf16 v[96:99], v[178:181], v[194:197], v[96:99]
	v_mfma_f32_16x16x32_bf16 v[84:87], v[160:163], v[202:205], v[84:87]
	v_mfma_f32_16x16x32_bf16 v[80:83], v[178:181], v[202:205], v[80:83]
	v_mfma_f32_16x16x32_bf16 v[68:71], v[160:163], v[210:213], v[68:71]
	v_mfma_f32_16x16x32_bf16 v[64:67], v[178:181], v[210:213], v[64:67]
	s_setprio 0
	s_barrier
	s_add_i32 s64, s59, s5
	v_lshl_add_u64 v[164:165], s[20:21], 0, v[138:139]
	s_mov_b32 m0, s64
	ds_read_b128 v[182:185], v171 offset:16384
	ds_read_b128 v[186:189], v171 offset:17408
	ds_read_b128 v[190:193], v171 offset:18432
	ds_read_b128 v[194:197], v171 offset:19456
	ds_read_b128 v[198:201], v171 offset:20480
	ds_read_b128 v[202:205], v171 offset:21504
	ds_read_b128 v[206:209], v171 offset:22528
	ds_read_b128 v[210:213], v171 offset:23552
	global_load_lds_dwordx4 v[164:165], off
	s_add_i32 m0, s64, 0x2000
	s_add_u32 s64, s20, 0x80000
	v_lshl_add_u64 v[214:215], s[20:21], 0, v[142:143]
	s_addc_u32 s65, s21, 0
	s_add_i32 s66, s60, s5
	global_load_lds_dwordx4 v[214:215], off
	v_lshl_add_u64 v[216:217], s[64:65], 0, v[138:139]
	s_mov_b32 m0, s66
	v_lshl_add_u64 v[218:219], s[34:35], 0, v[140:141]
	global_load_lds_dwordx4 v[216:217], off
	v_lshl_add_u64 v[216:217], s[64:65], 0, v[142:143]
	s_add_i32 m0, s66, 0x2000
	s_nop 0
	global_load_lds_dwordx4 v[216:217], off
	v_lshl_add_u64 v[216:217], s[34:35], 0, v[136:137]
	s_mov_b32 m0, s6
	s_nop 0
	global_load_lds_dwordx4 v[216:217], off
	s_mov_b32 m0, s7
	s_nop 0
	global_load_lds_dwordx4 v[218:219], off
	s_waitcnt vmcnt(8)
	s_waitcnt lgkmcnt(0)
	s_barrier
; #define PG8_STAGE(bufoff, gbase, voff) do { _Pragma("unroll") for (int _i = 0; _i < 2; ++_i) \
;         __builtin_amdgcn_global_load_lds((const unsigned*)((const char*)(gbase) + (voff)[_i]), (PG8_LAS unsigned*)(lds + (bufoff) + ldsw + _i * 8192), 16, 0, 0); } while (0)
; #define PG8_LDA(dst, b, h) do { _Pragma("unroll") for (int m = 0; m < 4; ++m) _Pragma("unroll") for (int k = 0; k < 2; ++k) dst[m][k] = *(const PG8_LAS bf16x8*)(lds + PG8_SA(b, h) + aoff + m * 2048 + k * 1024); } while (0)
; #define PG8_LDB(dst, b, h) do { _Pragma("unroll") for (int n = 0; n < 2; ++n) _Pragma("unroll") for (int k = 0; k < 2; ++k) dst[n][k] = *(const PG8_LAS bf16x8*)(lds + PG8_SB(b, h) + boff + n * 2048 + k * 1024); } while (0)
; #define PG8_MMA(ai, bj, At, Bt) do { __builtin_amdgcn_s_setprio(1); _Pragma("unroll") for (int m = 0; m < 4; ++m) _Pragma("unroll") for (int n = 0; n < 2; ++n) _Pragma("unroll") for (int k = 0; k < 2; ++k) \
;         acc[ai][bj][m][n] = __builtin_amdgcn_mfma_f32_16x16x32_bf16(Bt[n][k], At[m][k], acc[ai][bj][m][n], 0, 0, 0); __builtin_amdgcn_s_setprio(0); } while (0)
; #define PG8_WAIT_V(n) asm volatile("s_waitcnt vmcnt(" #n ")" ::: "memory")
; #define PG8_WAIT_L(n) asm volatile("s_waitcnt lgkmcnt(" #n ")" ::: "memory")
; #define PG8_BAR __builtin_amdgcn_s_barrier()
; template <class Epi, class Sched, bool ALIGN_EPI = false, bool SP2 = false>
; __device__ __forceinline__ void gemm_phase(PG8_LAS unsigned char* lds, const Gemm g, const Sched& S, const Epi& E) {
;     ...
;             PG8_WAIT_V(8); PG8_WAIT_L(0); PG8_BAR; PG8_MMA(0, 0, At, B0); PG8_MMA(0, 1, At, B1); PG8_BAR; PG8_SCHED;
;             PG8_LDA(At, 0, 1); PG8_STAGE(PG8_SB(0, 0), b2, voffB); PG8_STAGE(PG8_SB(0, 1), b2 + hstepB, voffB); PG8_STAGE(PG8_SA(0, 0), a2, voffA);
;             PG8_WAIT_V(8); PG8_WAIT_L(0); PG8_BAR; PG8_MMA(1, 0, At, B0); PG8_MMA(1, 1, At, B1); PG8_BAR; PG8_SCHED;
;             PG8_LDB(B0, 1, 0); PG8_LDB(B1, 1, 1); PG8_SCHED; PG8_LDA(At, 1, 0); PG8_STAGE(PG8_SA(0, 1), a2 + hstepA, voffA);
;             PG8_WAIT_V(8); PG8_WAIT_L(0); PG8_BAR; PG8_MMA(0, 0, At, B0); PG8_MMA(0, 1, At, B1); PG8_BAR; PG8_SCHED;
;             PG8_LDA(At, 1, 1); PG8_STAGE(PG8_SB(1, 0), b3, voffB); PG8_STAGE(PG8_SB(1, 1), b3 + hstepB, voffB); PG8_STAGE(PG8_SA(1, 0), a3, voffA);
;             PG8_WAIT_V(8); PG8_WAIT_L(0); PG8_BAR; PG8_MMA(1, 0, At, B0); PG8_MMA(1, 1, At, B1); PG8_BAR; PG8_SCHED;
	s_setprio 1
	v_mfma_f32_16x16x32_bf16 v[60:63], v[128:131], v[182:185], v[60:63]
	v_mfma_f32_16x16x32_bf16 v[56:59], v[148:151], v[182:185], v[56:59]
	v_mfma_f32_16x16x32_bf16 v[44:47], v[128:131], v[190:193], v[44:47]
	v_mfma_f32_16x16x32_bf16 v[40:43], v[148:151], v[190:193], v[40:43]
	v_mfma_f32_16x16x32_bf16 v[28:31], v[128:131], v[198:201], v[28:31]
	v_mfma_f32_16x16x32_bf16 v[24:27], v[148:151], v[198:201], v[24:27]
	v_mfma_f32_16x16x32_bf16 v[12:15], v[128:131], v[206:209], v[12:15]
	v_mfma_f32_16x16x32_bf16 v[8:11], v[148:151], v[206:209], v[8:11]
	v_mfma_f32_16x16x32_bf16 v[60:63], v[132:135], v[186:189], v[60:63]
	v_mfma_f32_16x16x32_bf16 v[56:59], v[152:155], v[186:189], v[56:59]
	v_mfma_f32_16x16x32_bf16 v[44:47], v[132:135], v[194:197], v[44:47]
	v_mfma_f32_16x16x32_bf16 v[40:43], v[152:155], v[194:197], v[40:43]
	v_mfma_f32_16x16x32_bf16 v[28:31], v[132:135], v[202:205], v[28:31]
	v_mfma_f32_16x16x32_bf16 v[24:27], v[152:155], v[202:205], v[24:27]
	v_mfma_f32_16x16x32_bf16 v[12:15], v[132:135], v[210:213], v[12:15]
	v_mfma_f32_16x16x32_bf16 v[8:11], v[152:155], v[210:213], v[8:11]
	v_mfma_f32_16x16x32_bf16 v[52:55], v[156:159], v[182:185], v[52:55]
	v_mfma_f32_16x16x32_bf16 v[48:51], v[174:177], v[182:185], v[48:51]
	v_mfma_f32_16x16x32_bf16 v[36:39], v[156:159], v[190:193], v[36:39]
	v_mfma_f32_16x16x32_bf16 v[32:35], v[174:177], v[190:193], v[32:35]
	v_mfma_f32_16x16x32_bf16 v[20:23], v[156:159], v[198:201], v[20:23]
	v_mfma_f32_16x16x32_bf16 v[16:19], v[174:177], v[198:201], v[16:19]
	v_mfma_f32_16x16x32_bf16 v[4:7], v[156:159], v[206:209], v[4:7]
	v_mfma_f32_16x16x32_bf16 v[0:3], v[174:177], v[206:209], v[0:3]
	v_mfma_f32_16x16x32_bf16 v[52:55], v[160:163], v[186:189], v[52:55]
	v_mfma_f32_16x16x32_bf16 v[48:51], v[178:181], v[186:189], v[48:51]
	v_mfma_f32_16x16x32_bf16 v[36:39], v[160:163], v[194:197], v[36:39]
	v_mfma_f32_16x16x32_bf16 v[32:35], v[178:181], v[194:197], v[32:35]
	v_mfma_f32_16x16x32_bf16 v[20:23], v[160:163], v[202:205], v[20:23]
	v_mfma_f32_16x16x32_bf16 v[16:19], v[178:181], v[202:205], v[16:19]
	v_mfma_f32_16x16x32_bf16 v[4:7], v[160:163], v[210:213], v[4:7]
	v_mfma_f32_16x16x32_bf16 v[0:3], v[178:181], v[210:213], v[0:3]
	s_setprio 0
	s_barrier
	s_add_i32 s64, 0, 0x18000
	s_add_i32 s65, 0, 0x1c000
	v_add_u32_e32 v152, s64, v168
	v_add_u32_e32 v173, s65, v168
	ds_read_b128 v[128:131], v152
	ds_read_b128 v[132:135], v152 offset:1024
	ds_read_b128 v[148:151], v152 offset:2048
	ds_read_b128 v[152:155], v152 offset:3072
	ds_read_b128 v[156:159], v173
	ds_read_b128 v[160:163], v173 offset:1024
	ds_read_b128 v[174:177], v173 offset:2048
	ds_read_b128 v[178:181], v173 offset:3072
	s_add_u32 s34, s34, 0x80000
	s_addc_u32 s35, s35, 0
	s_mov_b32 m0, s33
	v_lshl_add_u64 v[220:221], s[34:35], 0, v[136:137]
	ds_read_b128 v[182:185], v171 offset:32768
	ds_read_b128 v[186:189], v171 offset:33792
	ds_read_b128 v[190:193], v171 offset:34816
	ds_read_b128 v[194:197], v171 offset:35840
	ds_read_b128 v[198:201], v171 offset:36864
	ds_read_b128 v[202:205], v171 offset:37888
	ds_read_b128 v[206:209], v171 offset:38912
	ds_read_b128 v[210:213], v171 offset:39936
	global_load_lds_dwordx4 v[220:221], off
	v_lshl_add_u64 v[220:221], s[34:35], 0, v[140:141]
	s_mov_b32 m0, s46
	s_nop 0
	global_load_lds_dwordx4 v[220:221], off
	s_waitcnt vmcnt(8)
	s_waitcnt lgkmcnt(0)
	s_barrier
	s_setprio 1
	v_mfma_f32_16x16x32_bf16 v[124:127], v[128:131], v[182:185], v[124:127]
	v_mfma_f32_16x16x32_bf16 v[120:123], v[148:151], v[182:185], v[120:123]
	v_mfma_f32_16x16x32_bf16 v[108:111], v[128:131], v[190:193], v[108:111]
	v_mfma_f32_16x16x32_bf16 v[104:107], v[148:151], v[190:193], v[104:107]
	v_mfma_f32_16x16x32_bf16 v[92:95], v[128:131], v[198:201], v[92:95]
	v_mfma_f32_16x16x32_bf16 v[88:91], v[148:151], v[198:201], v[88:91]
	v_mfma_f32_16x16x32_bf16 v[76:79], v[128:131], v[206:209], v[76:79]
	v_mfma_f32_16x16x32_bf16 v[72:75], v[148:151], v[206:209], v[72:75]
	v_mfma_f32_16x16x32_bf16 v[124:127], v[132:135], v[186:189], v[124:127]
	v_mfma_f32_16x16x32_bf16 v[120:123], v[152:155], v[186:189], v[120:123]
	v_mfma_f32_16x16x32_bf16 v[108:111], v[132:135], v[194:197], v[108:111]
	v_mfma_f32_16x16x32_bf16 v[104:107], v[152:155], v[194:197], v[104:107]
	v_mfma_f32_16x16x32_bf16 v[92:95], v[132:135], v[202:205], v[92:95]
	v_mfma_f32_16x16x32_bf16 v[88:91], v[152:155], v[202:205], v[88:91]
	v_mfma_f32_16x16x32_bf16 v[76:79], v[132:135], v[210:213], v[76:79]
	v_mfma_f32_16x16x32_bf16 v[72:75], v[152:155], v[210:213], v[72:75]
	v_mfma_f32_16x16x32_bf16 v[116:119], v[156:159], v[182:185], v[116:119]
	v_mfma_f32_16x16x32_bf16 v[112:115], v[174:177], v[182:185], v[112:115]
	v_mfma_f32_16x16x32_bf16 v[100:103], v[156:159], v[190:193], v[100:103]
	v_mfma_f32_16x16x32_bf16 v[96:99], v[174:177], v[190:193], v[96:99]
	v_mfma_f32_16x16x32_bf16 v[84:87], v[156:159], v[198:201], v[84:87]
	v_mfma_f32_16x16x32_bf16 v[80:83], v[174:177], v[198:201], v[80:83]
	v_mfma_f32_16x16x32_bf16 v[68:71], v[156:159], v[206:209], v[68:71]
	v_mfma_f32_16x16x32_bf16 v[64:67], v[174:177], v[206:209], v[64:67]
	v_mfma_f32_16x16x32_bf16 v[116:119], v[160:163], v[186:189], v[116:119]
	v_mfma_f32_16x16x32_bf16 v[112:115], v[178:181], v[186:189], v[112:115]
	v_mfma_f32_16x16x32_bf16 v[100:103], v[160:163], v[194:197], v[100:103]
	v_mfma_f32_16x16x32_bf16 v[96:99], v[178:181], v[194:197], v[96:99]
	v_mfma_f32_16x16x32_bf16 v[84:87], v[160:163], v[202:205], v[84:87]
	v_mfma_f32_16x16x32_bf16 v[80:83], v[178:181], v[202:205], v[80:83]
	v_mfma_f32_16x16x32_bf16 v[68:71], v[160:163], v[210:213], v[68:71]
	v_mfma_f32_16x16x32_bf16 v[64:67], v[178:181], v[210:213], v[64:67]
	s_setprio 0
	s_barrier
; #define PG8_STAGE(bufoff, gbase, voff) do { _Pragma("unroll") for (int _i = 0; _i < 2; ++_i) \
;         __builtin_amdgcn_global_load_lds((const unsigned*)((const char*)(gbase) + (voff)[_i]), (PG8_LAS unsigned*)(lds + (bufoff) + ldsw + _i * 8192), 16, 0, 0); } while (0)
; #define PG8_LDA(dst, b, h) do { _Pragma("unroll") for (int m = 0; m < 4; ++m) _Pragma("unroll") for (int k = 0; k < 2; ++k) dst[m][k] = *(const PG8_LAS bf16x8*)(lds + PG8_SA(b, h) + aoff + m * 2048 + k * 1024); } while (0)
; #define PG8_LDB(dst, b, h) do { _Pragma("unroll") for (int n = 0; n < 2; ++n) _Pragma("unroll") for (int k = 0; k < 2; ++k) dst[n][k] = *(const PG8_LAS bf16x8*)(lds + PG8_SB(b, h) + boff + n * 2048 + k * 1024); } while (0)
; #define PG8_MMA(ai, bj, At, Bt) do { __builtin_amdgcn_s_setprio(1); _Pragma("unroll") for (int m = 0; m < 4; ++m) _Pragma("unroll") for (int n = 0; n < 2; ++n) _Pragma("unroll") for (int k = 0; k < 2; ++k) \
;         acc[ai][bj][m][n] = __builtin_amdgcn_mfma_f32_16x16x32_bf16(Bt[n][k], At[m][k], acc[ai][bj][m][n], 0, 0, 0); __builtin_amdgcn_s_setprio(0); } while (0)
; #define PG8_WAIT_V(n) asm volatile("s_waitcnt vmcnt(" #n ")" ::: "memory")
; #define PG8_WAIT_L(n) asm volatile("s_waitcnt lgkmcnt(" #n ")" ::: "memory")
; #define PG8_BAR __builtin_amdgcn_s_barrier()
; #define PG8_SCHED __builtin_amdgcn_sched_barrier(0)
; template <class Epi, class Sched, bool ALIGN_EPI = false, bool SP2 = false>
; __device__ __forceinline__ void gemm_phase(PG8_LAS unsigned char* lds, const Gemm g, const Sched& S, const Epi& E) {
;     ...
;             PG8_LDB(B0, 1, 0); PG8_LDB(B1, 1, 1); PG8_SCHED; PG8_LDA(At, 1, 0); PG8_STAGE(PG8_SA(0, 1), a2 + hstepA, voffA);
;             PG8_WAIT_V(8); PG8_WAIT_L(0); PG8_BAR; PG8_MMA(0, 0, At, B0); PG8_MMA(0, 1, At, B1); PG8_BAR; PG8_SCHED;
;             PG8_LDA(At, 1, 1); PG8_STAGE(PG8_SB(1, 0), b3, voffB); PG8_STAGE(PG8_SB(1, 1), b3 + hstepB, voffB); PG8_STAGE(PG8_SA(1, 0), a3, voffA);
;             PG8_WAIT_V(8); PG8_WAIT_L(0); PG8_BAR; PG8_MMA(1, 0, At, B0); PG8_MMA(1, 1, At, B1); PG8_BAR; PG8_SCHED;
	s_add_i32 s34, s64, s5
	v_lshl_add_u64 v[164:165], v[164:165], 0, s[22:23]
	s_mov_b32 m0, s34
	ds_read_b128 v[182:185], v171 offset:49152
	ds_read_b128 v[186:189], v171 offset:50176
	ds_read_b128 v[190:193], v171 offset:51200
	ds_read_b128 v[194:197], v171 offset:52224
	ds_read_b128 v[198:201], v171 offset:53248
	ds_read_b128 v[202:205], v171 offset:54272
	ds_read_b128 v[206:209], v171 offset:55296
	ds_read_b128 v[210:213], v171 offset:56320
	global_load_lds_dwordx4 v[164:165], off
	s_add_i32 m0, s34, 0x2000
	s_add_u32 s20, s20, 0x80080
	v_lshl_add_u64 v[164:165], v[214:215], 0, s[22:23]
	s_addc_u32 s21, s21, 0
	s_add_i32 s34, s65, s5
	global_load_lds_dwordx4 v[164:165], off
	v_lshl_add_u64 v[164:165], s[20:21], 0, v[138:139]
	s_mov_b32 m0, s34
	s_nop 0
	global_load_lds_dwordx4 v[164:165], off
	v_lshl_add_u64 v[164:165], s[20:21], 0, v[142:143]
	s_add_i32 m0, s34, 0x2000
	s_nop 0
	global_load_lds_dwordx4 v[164:165], off
	v_lshl_add_u64 v[164:165], v[216:217], 0, s[22:23]
	s_mov_b32 m0, s56
	s_nop 0
	global_load_lds_dwordx4 v[164:165], off
	v_lshl_add_u64 v[164:165], v[218:219], 0, s[22:23]
	s_mov_b32 m0, s57
	s_nop 0
	global_load_lds_dwordx4 v[164:165], off
	s_waitcnt vmcnt(8)
	s_waitcnt lgkmcnt(0)
	s_barrier
	s_setprio 1
	v_mfma_f32_16x16x32_bf16 v[60:63], v[128:131], v[182:185], v[60:63]
	v_mfma_f32_16x16x32_bf16 v[56:59], v[148:151], v[182:185], v[56:59]
	v_mfma_f32_16x16x32_bf16 v[44:47], v[128:131], v[190:193], v[44:47]
	v_mfma_f32_16x16x32_bf16 v[40:43], v[148:151], v[190:193], v[40:43]
	v_mfma_f32_16x16x32_bf16 v[28:31], v[128:131], v[198:201], v[28:31]
	v_mfma_f32_16x16x32_bf16 v[24:27], v[148:151], v[198:201], v[24:27]
	v_mfma_f32_16x16x32_bf16 v[12:15], v[128:131], v[206:209], v[12:15]
	v_mfma_f32_16x16x32_bf16 v[8:11], v[148:151], v[206:209], v[8:11]
	v_mfma_f32_16x16x32_bf16 v[60:63], v[132:135], v[186:189], v[60:63]
	v_mfma_f32_16x16x32_bf16 v[56:59], v[152:155], v[186:189], v[56:59]
	v_mfma_f32_16x16x32_bf16 v[44:47], v[132:135], v[194:197], v[44:47]
	v_mfma_f32_16x16x32_bf16 v[40:43], v[152:155], v[194:197], v[40:43]
	v_mfma_f32_16x16x32_bf16 v[28:31], v[132:135], v[202:205], v[28:31]
	v_mfma_f32_16x16x32_bf16 v[24:27], v[152:155], v[202:205], v[24:27]
	v_mfma_f32_16x16x32_bf16 v[12:15], v[132:135], v[210:213], v[12:15]
	v_mfma_f32_16x16x32_bf16 v[8:11], v[152:155], v[210:213], v[8:11]
	v_mfma_f32_16x16x32_bf16 v[52:55], v[156:159], v[182:185], v[52:55]
	v_mfma_f32_16x16x32_bf16 v[48:51], v[174:177], v[182:185], v[48:51]
	v_mfma_f32_16x16x32_bf16 v[36:39], v[156:159], v[190:193], v[36:39]
	v_mfma_f32_16x16x32_bf16 v[32:35], v[174:177], v[190:193], v[32:35]
	v_mfma_f32_16x16x32_bf16 v[20:23], v[156:159], v[198:201], v[20:23]
	v_mfma_f32_16x16x32_bf16 v[16:19], v[174:177], v[198:201], v[16:19]
	v_mfma_f32_16x16x32_bf16 v[4:7], v[156:159], v[206:209], v[4:7]
	v_mfma_f32_16x16x32_bf16 v[0:3], v[174:177], v[206:209], v[0:3]
	v_mfma_f32_16x16x32_bf16 v[52:55], v[160:163], v[186:189], v[52:55]
	v_mfma_f32_16x16x32_bf16 v[48:51], v[178:181], v[186:189], v[48:51]
	v_mfma_f32_16x16x32_bf16 v[36:39], v[160:163], v[194:197], v[36:39]
	v_mfma_f32_16x16x32_bf16 v[32:35], v[178:181], v[194:197], v[32:35]
	v_mfma_f32_16x16x32_bf16 v[20:23], v[160:163], v[202:205], v[20:23]
	v_mfma_f32_16x16x32_bf16 v[16:19], v[178:181], v[202:205], v[16:19]
	v_mfma_f32_16x16x32_bf16 v[4:7], v[160:163], v[210:213], v[4:7]
	v_mfma_f32_16x16x32_bf16 v[0:3], v[178:181], v[210:213], v[0:3]
	s_setprio 0
	s_barrier
	s_add_i32 s63, s63, 2
	s_add_u32 s16, s16, 0x100
	s_addc_u32 s17, s17, 0
	s_add_u32 s61, s61, 0x100
	s_addc_u32 s62, s62, 0
	s_cmp_gt_u32 s63, 29
	s_cbranch_scc0 .LBB0_1363
	s_and_b64 vcc, exec, s[24:25]
	s_cbranch_vccz .LBB0_1366
	s_barrier

; #define PG8_STAGE(bufoff, gbase, voff) do { _Pragma("unroll") for (int _i = 0; _i < 2; ++_i) \
;         __builtin_amdgcn_global_load_lds((const unsigned*)((const char*)(gbase) + (voff)[_i]), (PG8_LAS unsigned*)(lds + (bufoff) + ldsw + _i * 8192), 16, 0, 0); } while (0)
; #define PG8_LDA(dst, b, h) do { _Pragma("unroll") for (int m = 0; m < 4; ++m) _Pragma("unroll") for (int k = 0; k < 2; ++k) dst[m][k] = *(const PG8_LAS bf16x8*)(lds + PG8_SA(b, h) + aoff + m * 2048 + k * 1024); } while (0)
; #define PG8_LDB(dst, b, h) do { _Pragma("unroll") for (int n = 0; n < 2; ++n) _Pragma("unroll") for (int k = 0; k < 2; ++k) dst[n][k] = *(const PG8_LAS bf16x8*)(lds + PG8_SB(b, h) + boff + n * 2048 + k * 1024); } while (0)
; #define PG8_WAIT_V(n) asm volatile("s_waitcnt vmcnt(" #n ")" ::: "memory")
; #define PG8_WAIT_L(n) asm volatile("s_waitcnt lgkmcnt(" #n ")" ::: "memory")
; #define PG8_BAR __builtin_amdgcn_s_barrier()
; #define PG8_SCHED __builtin_amdgcn_sched_barrier(0)
; template <class Epi, class Sched, bool ALIGN_EPI = false, bool SP2 = false>
; __device__ __forceinline__ void gemm_phase(PG8_LAS unsigned char* lds, const Gemm g, const Sched& S, const Epi& E) {
;     ...
;         const char* nA = has_next ? (const char*)g.A + (size_t)nxt.pm * tstepA : cA; const char* nB = has_next ? (const char*)g.Bt + (size_t)nxt.pn * tstepB : cB;
;         for (int t = 0; t < nt; t += 2) {
;             const bool last = (t == nt - 2);
;             if constexpr (Epi::HAS_MID) { if (t == E.mid_t) E.mid(acc, cur, wr, wc, fr, fq); }
;             const char* a1 = cA + (size_t)(t + 1) * kstep;
;             const char* a2 = last ? nA : cA + (size_t)(t + 2) * kstep; const char* b2 = last ? nB : cB + (size_t)(t + 2) * kstep;
;             const char* a3 = a2 + kstep; const char* b3 = b2 + kstep;
;             if (last && has_next) S.a_ready(nxt);
;             if constexpr (SP2) {
;             PG8_LDB(B0, 0, 0); PG8_LDB(B1, 0, 1); PG8_SCHED; PG8_LDA(At, 0, 0); PG8_STAGE(PG8_SA(1, 1), a1 + hstepA, voffA);
;             PG8_WAIT_V(8); PG8_WAIT_L(0); PG8_BAR; PG8_MMA(0, 0, At, B0); PG8_MMA(0, 1, At, B1); PG8_BAR; PG8_SCHED;
;             PG8_LDA(At, 0, 1); PG8_STAGE(PG8_SB(0, 0), b2, voffB); PG8_STAGE(PG8_SB(0, 1), b2 + hstepB, voffB); PG8_STAGE(PG8_SA(0, 0), a2, voffA);
;             PG8_WAIT_V(8); PG8_WAIT_L(0); PG8_BAR; PG8_MMA(1, 0, At, B0); PG8_MMA(1, 1, At, B1); PG8_BAR; PG8_SCHED;
.LBB0_1738:
	ds_read_b128 v[144:147], v151
	ds_read_b128 v[154:157], v151 offset:1024
	ds_read_b128 v[158:161], v151 offset:2048
	ds_read_b128 v[162:165], v151 offset:3072
	ds_read_b128 v[166:169], v152
	ds_read_b128 v[170:173], v152 offset:1024
	ds_read_b128 v[174:177], v152 offset:2048
	ds_read_b128 v[178:181], v152 offset:3072
	s_add_u32 s34, s20, 0xfffe0080
	s_addc_u32 s35, s21, -1
	s_cmp_eq_u32 s57, 4
	s_cselect_b32 s39, s13, s35
	s_cselect_b32 s38, s27, s34
	s_cselect_b32 s35, s25, s56
	s_cselect_b32 s34, s52, s53
	s_add_i32 m0, s5, 0xc000
	ds_read_b128 v[182:185], v153
	ds_read_b128 v[186:189], v153 offset:1024
	ds_read_b128 v[190:193], v153 offset:2048
	ds_read_b128 v[194:197], v153 offset:3072
	ds_read_b128 v[198:201], v153 offset:4096
	ds_read_b128 v[202:205], v153 offset:5120
	ds_read_b128 v[206:209], v153 offset:6144
	ds_read_b128 v[210:213], v153 offset:7168
	s_add_u32 s98, s20, 0xfffe0000
	s_addc_u32 s99, s21, -1
	s_mov_b32 m0, s42
	s_nop 0
	global_load_lds_dwordx4 v128, s[98:99]
	s_mov_b32 m0, s43
	s_nop 0
	global_load_lds_dwordx4 v132, s[98:99]
	s_add_i32 m0, s5, 0xc000
	s_nop 0
	global_load_lds_dwordx4 v136, s[20:21]
	s_add_i32 m0, s5, 0xe000
	s_nop 0
	global_load_lds_dwordx4 v138, s[20:21]
	s_waitcnt vmcnt(8)
	s_waitcnt lgkmcnt(0)
	s_barrier
	s_setprio 1
	v_mfma_f32_16x16x32_bf16 v[124:127], v[144:147], v[182:185], v[124:127]
	v_mfma_f32_16x16x32_bf16 v[120:123], v[158:161], v[182:185], v[120:123]
	v_mfma_f32_16x16x32_bf16 v[108:111], v[144:147], v[190:193], v[108:111]
	v_mfma_f32_16x16x32_bf16 v[104:107], v[158:161], v[190:193], v[104:107]
	v_mfma_f32_16x16x32_bf16 v[92:95], v[144:147], v[198:201], v[92:95]
	v_mfma_f32_16x16x32_bf16 v[88:91], v[158:161], v[198:201], v[88:91]
	v_mfma_f32_16x16x32_bf16 v[76:79], v[144:147], v[206:209], v[76:79]
	v_mfma_f32_16x16x32_bf16 v[72:75], v[158:161], v[206:209], v[72:75]
	v_mfma_f32_16x16x32_bf16 v[124:127], v[154:157], v[186:189], v[124:127]
	v_mfma_f32_16x16x32_bf16 v[120:123], v[162:165], v[186:189], v[120:123]
	v_mfma_f32_16x16x32_bf16 v[108:111], v[154:157], v[194:197], v[108:111]
	v_mfma_f32_16x16x32_bf16 v[104:107], v[162:165], v[194:197], v[104:107]
	v_mfma_f32_16x16x32_bf16 v[92:95], v[154:157], v[202:205], v[92:95]
	v_mfma_f32_16x16x32_bf16 v[88:91], v[162:165], v[202:205], v[88:91]
	v_mfma_f32_16x16x32_bf16 v[76:79], v[154:157], v[210:213], v[76:79]
	v_mfma_f32_16x16x32_bf16 v[72:75], v[162:165], v[210:213], v[72:75]
	v_mfma_f32_16x16x32_bf16 v[116:119], v[166:169], v[182:185], v[116:119]
	v_mfma_f32_16x16x32_bf16 v[112:115], v[174:177], v[182:185], v[112:115]
	v_mfma_f32_16x16x32_bf16 v[100:103], v[166:169], v[190:193], v[100:103]
	v_mfma_f32_16x16x32_bf16 v[96:99], v[174:177], v[190:193], v[96:99]
	v_mfma_f32_16x16x32_bf16 v[84:87], v[166:169], v[198:201], v[84:87]
	v_mfma_f32_16x16x32_bf16 v[80:83], v[174:177], v[198:201], v[80:83]
	v_mfma_f32_16x16x32_bf16 v[68:71], v[166:169], v[206:209], v[68:71]
	v_mfma_f32_16x16x32_bf16 v[64:67], v[174:177], v[206:209], v[64:67]
	v_mfma_f32_16x16x32_bf16 v[116:119], v[170:173], v[186:189], v[116:119]
	v_mfma_f32_16x16x32_bf16 v[112:115], v[178:181], v[186:189], v[112:115]
	v_mfma_f32_16x16x32_bf16 v[100:103], v[170:173], v[194:197], v[100:103]
	v_mfma_f32_16x16x32_bf16 v[96:99], v[178:181], v[194:197], v[96:99]
	v_mfma_f32_16x16x32_bf16 v[84:87], v[170:173], v[202:205], v[84:87]
	v_mfma_f32_16x16x32_bf16 v[80:83], v[178:181], v[202:205], v[80:83]
	v_mfma_f32_16x16x32_bf16 v[68:71], v[170:173], v[210:213], v[68:71]
	v_mfma_f32_16x16x32_bf16 v[64:67], v[178:181], v[210:213], v[64:67]
	s_setprio 0
	s_barrier
	s_add_i32 s58, s47, s4
	s_mov_b32 m0, s58
	ds_read_b128 v[182:185], v153 offset:16384
	ds_read_b128 v[186:189], v153 offset:17408
	ds_read_b128 v[190:193], v153 offset:18432
	ds_read_b128 v[194:197], v153 offset:19456
	ds_read_b128 v[198:201], v153 offset:20480
	ds_read_b128 v[202:205], v153 offset:21504
	ds_read_b128 v[206:209], v153 offset:22528
	ds_read_b128 v[210:213], v153 offset:23552
	global_load_lds_dwordx4 v130, s[34:35]
	s_add_i32 m0, s58, 0x2000
	s_add_u32 s58, s34, 0x20000
	s_addc_u32 s59, s35, 0
	s_add_i32 s60, s50, s4
	global_load_lds_dwordx4 v134, s[34:35]
	s_mov_b32 m0, s60
	s_nop 0
	global_load_lds_dwordx4 v130, s[58:59]
	s_add_i32 m0, s60, 0x2000
	s_nop 0
	global_load_lds_dwordx4 v134, s[58:59]
	s_waitcnt vmcnt(6)
	s_waitcnt lgkmcnt(0)
	s_barrier
	s_setprio 1
	v_mfma_f32_16x16x32_bf16 v[60:63], v[144:147], v[182:185], v[60:63]
	v_mfma_f32_16x16x32_bf16 v[56:59], v[158:161], v[182:185], v[56:59]
	v_mfma_f32_16x16x32_bf16 v[44:47], v[144:147], v[190:193], v[44:47]
	v_mfma_f32_16x16x32_bf16 v[40:43], v[158:161], v[190:193], v[40:43]
	v_mfma_f32_16x16x32_bf16 v[28:31], v[144:147], v[198:201], v[28:31]
	v_mfma_f32_16x16x32_bf16 v[24:27], v[158:161], v[198:201], v[24:27]
	v_mfma_f32_16x16x32_bf16 v[12:15], v[144:147], v[206:209], v[12:15]
	v_mfma_f32_16x16x32_bf16 v[8:11], v[158:161], v[206:209], v[8:11]
	v_mfma_f32_16x16x32_bf16 v[60:63], v[154:157], v[186:189], v[60:63]
	v_mfma_f32_16x16x32_bf16 v[56:59], v[162:165], v[186:189], v[56:59]
	v_mfma_f32_16x16x32_bf16 v[44:47], v[154:157], v[194:197], v[44:47]
	v_mfma_f32_16x16x32_bf16 v[40:43], v[162:165], v[194:197], v[40:43]
	v_mfma_f32_16x16x32_bf16 v[28:31], v[154:157], v[202:205], v[28:31]
	v_mfma_f32_16x16x32_bf16 v[24:27], v[162:165], v[202:205], v[24:27]
	v_mfma_f32_16x16x32_bf16 v[12:15], v[154:157], v[210:213], v[12:15]
	v_mfma_f32_16x16x32_bf16 v[8:11], v[162:165], v[210:213], v[8:11]
	v_mfma_f32_16x16x32_bf16 v[52:55], v[166:169], v[182:185], v[52:55]
	v_mfma_f32_16x16x32_bf16 v[48:51], v[174:177], v[182:185], v[48:51]
	v_mfma_f32_16x16x32_bf16 v[36:39], v[166:169], v[190:193], v[36:39]
	v_mfma_f32_16x16x32_bf16 v[32:35], v[174:177], v[190:193], v[32:35]
	v_mfma_f32_16x16x32_bf16 v[20:23], v[166:169], v[198:201], v[20:23]
	v_mfma_f32_16x16x32_bf16 v[16:19], v[174:177], v[198:201], v[16:19]
	v_mfma_f32_16x16x32_bf16 v[4:7], v[166:169], v[206:209], v[4:7]
	v_mfma_f32_16x16x32_bf16 v[0:3], v[174:177], v[206:209], v[0:3]
	v_mfma_f32_16x16x32_bf16 v[52:55], v[170:173], v[186:189], v[52:55]
	v_mfma_f32_16x16x32_bf16 v[48:51], v[178:181], v[186:189], v[48:51]
	v_mfma_f32_16x16x32_bf16 v[36:39], v[170:173], v[194:197], v[36:39]
	v_mfma_f32_16x16x32_bf16 v[32:35], v[178:181], v[194:197], v[32:35]
	v_mfma_f32_16x16x32_bf16 v[20:23], v[170:173], v[202:205], v[20:23]
	v_mfma_f32_16x16x32_bf16 v[16:19], v[178:181], v[202:205], v[16:19]
	v_mfma_f32_16x16x32_bf16 v[4:7], v[170:173], v[210:213], v[4:7]
	v_mfma_f32_16x16x32_bf16 v[0:3], v[178:181], v[210:213], v[0:3]
	s_setprio 0
	s_barrier
; #define PG8_STAGE(bufoff, gbase, voff) do { _Pragma("unroll") for (int _i = 0; _i < 2; ++_i) \
;         __builtin_amdgcn_global_load_lds((const unsigned*)((const char*)(gbase) + (voff)[_i]), (PG8_LAS unsigned*)(lds + (bufoff) + ldsw + _i * 8192), 16, 0, 0); } while (0)
; #define PG8_LDA(dst, b, h) do { _Pragma("unroll") for (int m = 0; m < 4; ++m) _Pragma("unroll") for (int k = 0; k < 2; ++k) dst[m][k] = *(const PG8_LAS bf16x8*)(lds + PG8_SA(b, h) + aoff + m * 2048 + k * 1024); } while (0)
; #define PG8_WAIT_V(n) asm volatile("s_waitcnt vmcnt(" #n ")" ::: "memory")
; #define PG8_BAR __builtin_amdgcn_s_barrier()
; template <class Epi, class Sched, bool ALIGN_EPI = false, bool SP2 = false>
; __device__ __forceinline__ void gemm_phase(PG8_LAS unsigned char* lds, const Gemm g, const Sched& S, const Epi& E) {
;     ...
;         for (int t = 0; t < nt; t += 2) {
;             const bool last = (t == nt - 2);
;             if constexpr (Epi::HAS_MID) { if (t == E.mid_t) E.mid(acc, cur, wr, wc, fr, fq); }
;             const char* a1 = cA + (size_t)(t + 1) * kstep;
;             const char* a2 = last ? nA : cA + (size_t)(t + 2) * kstep; const char* b2 = last ? nB : cB + (size_t)(t + 2) * kstep;
;             const char* a3 = a2 + kstep; const char* b3 = b2 + kstep;
;             if (last && has_next) S.a_ready(nxt);
;             if constexpr (SP2) {
;             PG8_LDB(B0, 0, 0); PG8_LDB(B1, 0, 1); PG8_SCHED; PG8_LDA(At, 0, 0); PG8_STAGE(PG8_SA(1, 1), a1 + hstepA, voffA);
;             PG8_WAIT_V(8); PG8_WAIT_L(0); PG8_BAR; PG8_MMA(0, 0, At, B0); PG8_MMA(0, 1, At, B1); PG8_BAR; PG8_SCHED;
;             PG8_LDA(At, 0, 1); PG8_STAGE(PG8_SB(0, 0), b2, voffB); PG8_STAGE(PG8_SB(0, 1), b2 + hstepB, voffB); PG8_STAGE(PG8_SA(0, 0), a2, voffA);
;             PG8_WAIT_V(8); PG8_WAIT_L(0); PG8_BAR; PG8_MMA(1, 0, At, B0); PG8_MMA(1, 1, At, B1); PG8_BAR; PG8_SCHED;
;             PG8_LDB(B0, 1, 0); PG8_LDB(B1, 1, 1); PG8_SCHED; PG8_LDA(At, 1, 0); PG8_STAGE(PG8_SA(0, 1), a2 + hstepA, voffA);
;             PG8_WAIT_V(8); PG8_WAIT_L(0); PG8_BAR; PG8_MMA(0, 0, At, B0); PG8_MMA(0, 1, At, B1); PG8_BAR; PG8_SCHED;
;             PG8_LDA(At, 1, 1); PG8_STAGE(PG8_SB(1, 0), b3, voffB); PG8_STAGE(PG8_SB(1, 1), b3 + hstepB, voffB); PG8_STAGE(PG8_SA(1, 0), a3, voffA);
;             PG8_WAIT_V(8); PG8_WAIT_L(0); PG8_BAR; PG8_MMA(1, 0, At, B0); PG8_MMA(1, 1, At, B1); PG8_BAR; PG8_SCHED;
	s_add_i32 s58, 0, 0x18000
	s_add_i32 s59, 0, 0x1c000
	v_add_u32_e32 v162, s58, v150
	v_add_u32_e32 v178, s59, v150
	ds_read_b128 v[144:147], v162
	ds_read_b128 v[154:157], v162 offset:1024
	ds_read_b128 v[158:161], v162 offset:2048
	ds_read_b128 v[162:165], v162 offset:3072
	ds_read_b128 v[166:169], v178
	ds_read_b128 v[170:173], v178 offset:1024
	ds_read_b128 v[174:177], v178 offset:2048
	ds_read_b128 v[178:181], v178 offset:3072
	s_mov_b64 s[100:101], s[38:39]
	s_add_u32 s38, s38, 0x20000
	s_addc_u32 s39, s39, 0
	s_mov_b32 m0, s7
	ds_read_b128 v[182:185], v153 offset:32768
	ds_read_b128 v[186:189], v153 offset:33792
	ds_read_b128 v[190:193], v153 offset:34816
	ds_read_b128 v[194:197], v153 offset:35840
	ds_read_b128 v[198:201], v153 offset:36864
	ds_read_b128 v[202:205], v153 offset:37888
	ds_read_b128 v[206:209], v153 offset:38912
	ds_read_b128 v[210:213], v153 offset:39936
	s_mov_b32 m0, s5
	s_nop 0
	global_load_lds_dwordx4 v128, s[100:101]
	s_mov_b32 m0, s6
	s_nop 0
	global_load_lds_dwordx4 v132, s[100:101]
	s_mov_b32 m0, s7
	s_nop 0
	global_load_lds_dwordx4 v128, s[38:39]
	s_mov_b32 m0, s33
	s_nop 0
	global_load_lds_dwordx4 v132, s[38:39]
	s_waitcnt vmcnt(8)
	s_waitcnt lgkmcnt(0)
	s_barrier
	s_setprio 1
	v_mfma_f32_16x16x32_bf16 v[124:127], v[144:147], v[182:185], v[124:127]
	v_mfma_f32_16x16x32_bf16 v[120:123], v[158:161], v[182:185], v[120:123]
	v_mfma_f32_16x16x32_bf16 v[108:111], v[144:147], v[190:193], v[108:111]
	v_mfma_f32_16x16x32_bf16 v[104:107], v[158:161], v[190:193], v[104:107]
	v_mfma_f32_16x16x32_bf16 v[92:95], v[144:147], v[198:201], v[92:95]
	v_mfma_f32_16x16x32_bf16 v[88:91], v[158:161], v[198:201], v[88:91]
	v_mfma_f32_16x16x32_bf16 v[76:79], v[144:147], v[206:209], v[76:79]
	v_mfma_f32_16x16x32_bf16 v[72:75], v[158:161], v[206:209], v[72:75]
	v_mfma_f32_16x16x32_bf16 v[124:127], v[154:157], v[186:189], v[124:127]
	v_mfma_f32_16x16x32_bf16 v[120:123], v[162:165], v[186:189], v[120:123]
	v_mfma_f32_16x16x32_bf16 v[108:111], v[154:157], v[194:197], v[108:111]
	v_mfma_f32_16x16x32_bf16 v[104:107], v[162:165], v[194:197], v[104:107]
	v_mfma_f32_16x16x32_bf16 v[92:95], v[154:157], v[202:205], v[92:95]
	v_mfma_f32_16x16x32_bf16 v[88:91], v[162:165], v[202:205], v[88:91]
	v_mfma_f32_16x16x32_bf16 v[76:79], v[154:157], v[210:213], v[76:79]
	v_mfma_f32_16x16x32_bf16 v[72:75], v[162:165], v[210:213], v[72:75]
	v_mfma_f32_16x16x32_bf16 v[116:119], v[166:169], v[182:185], v[116:119]
	v_mfma_f32_16x16x32_bf16 v[112:115], v[174:177], v[182:185], v[112:115]
	v_mfma_f32_16x16x32_bf16 v[100:103], v[166:169], v[190:193], v[100:103]
	v_mfma_f32_16x16x32_bf16 v[96:99], v[174:177], v[190:193], v[96:99]
	v_mfma_f32_16x16x32_bf16 v[84:87], v[166:169], v[198:201], v[84:87]
	v_mfma_f32_16x16x32_bf16 v[80:83], v[174:177], v[198:201], v[80:83]
	v_mfma_f32_16x16x32_bf16 v[68:71], v[166:169], v[206:209], v[68:71]
	v_mfma_f32_16x16x32_bf16 v[64:67], v[174:177], v[206:209], v[64:67]
	v_mfma_f32_16x16x32_bf16 v[116:119], v[170:173], v[186:189], v[116:119]
	v_mfma_f32_16x16x32_bf16 v[112:115], v[178:181], v[186:189], v[112:115]
	v_mfma_f32_16x16x32_bf16 v[100:103], v[170:173], v[194:197], v[100:103]
	v_mfma_f32_16x16x32_bf16 v[96:99], v[178:181], v[194:197], v[96:99]
	v_mfma_f32_16x16x32_bf16 v[84:87], v[170:173], v[202:205], v[84:87]
	v_mfma_f32_16x16x32_bf16 v[80:83], v[178:181], v[202:205], v[80:83]
	v_mfma_f32_16x16x32_bf16 v[68:71], v[170:173], v[210:213], v[68:71]
	v_mfma_f32_16x16x32_bf16 v[64:67], v[178:181], v[210:213], v[64:67]
	s_setprio 0
	s_barrier
	s_add_i32 s38, s58, s4
	s_add_u32 s98, s34, 0x80
	s_addc_u32 s99, s35, 0
	s_mov_b32 m0, s38
	ds_read_b128 v[182:185], v153 offset:49152
	ds_read_b128 v[186:189], v153 offset:50176
	ds_read_b128 v[190:193], v153 offset:51200
	ds_read_b128 v[194:197], v153 offset:52224
	ds_read_b128 v[198:201], v153 offset:53248
	ds_read_b128 v[202:205], v153 offset:54272
	ds_read_b128 v[206:209], v153 offset:55296
	ds_read_b128 v[210:213], v153 offset:56320
	global_load_lds_dwordx4 v130, s[98:99]
	s_add_i32 m0, s38, 0x2000
	s_add_u32 s34, s34, 0x20080
	s_addc_u32 s35, s35, 0
	s_add_i32 s38, s59, s4
	global_load_lds_dwordx4 v134, s[98:99]
	s_mov_b32 m0, s38
	s_nop 0
	global_load_lds_dwordx4 v130, s[34:35]
	s_add_i32 m0, s38, 0x2000
	s_nop 0
	global_load_lds_dwordx4 v134, s[34:35]
	s_waitcnt vmcnt(6)
	s_waitcnt lgkmcnt(0)
	s_barrier
	s_setprio 1
	v_mfma_f32_16x16x32_bf16 v[60:63], v[144:147], v[182:185], v[60:63]
	v_mfma_f32_16x16x32_bf16 v[56:59], v[158:161], v[182:185], v[56:59]
	v_mfma_f32_16x16x32_bf16 v[44:47], v[144:147], v[190:193], v[44:47]
	v_mfma_f32_16x16x32_bf16 v[40:43], v[158:161], v[190:193], v[40:43]
	v_mfma_f32_16x16x32_bf16 v[28:31], v[144:147], v[198:201], v[28:31]
	v_mfma_f32_16x16x32_bf16 v[24:27], v[158:161], v[198:201], v[24:27]
	v_mfma_f32_16x16x32_bf16 v[12:15], v[144:147], v[206:209], v[12:15]
	v_mfma_f32_16x16x32_bf16 v[8:11], v[158:161], v[206:209], v[8:11]
	v_mfma_f32_16x16x32_bf16 v[60:63], v[154:157], v[186:189], v[60:63]
	v_mfma_f32_16x16x32_bf16 v[56:59], v[162:165], v[186:189], v[56:59]
	v_mfma_f32_16x16x32_bf16 v[44:47], v[154:157], v[194:197], v[44:47]
	v_mfma_f32_16x16x32_bf16 v[40:43], v[162:165], v[194:197], v[40:43]
	v_mfma_f32_16x16x32_bf16 v[28:31], v[154:157], v[202:205], v[28:31]
	v_mfma_f32_16x16x32_bf16 v[24:27], v[162:165], v[202:205], v[24:27]
	v_mfma_f32_16x16x32_bf16 v[12:15], v[154:157], v[210:213], v[12:15]
	v_mfma_f32_16x16x32_bf16 v[8:11], v[162:165], v[210:213], v[8:11]
	v_mfma_f32_16x16x32_bf16 v[52:55], v[166:169], v[182:185], v[52:55]
	v_mfma_f32_16x16x32_bf16 v[48:51], v[174:177], v[182:185], v[48:51]
	v_mfma_f32_16x16x32_bf16 v[36:39], v[166:169], v[190:193], v[36:39]
	v_mfma_f32_16x16x32_bf16 v[32:35], v[174:177], v[190:193], v[32:35]
	v_mfma_f32_16x16x32_bf16 v[20:23], v[166:169], v[198:201], v[20:23]
	v_mfma_f32_16x16x32_bf16 v[16:19], v[174:177], v[198:201], v[16:19]
	v_mfma_f32_16x16x32_bf16 v[4:7], v[166:169], v[206:209], v[4:7]
	v_mfma_f32_16x16x32_bf16 v[0:3], v[174:177], v[206:209], v[0:3]
	v_mfma_f32_16x16x32_bf16 v[52:55], v[170:173], v[186:189], v[52:55]
	v_mfma_f32_16x16x32_bf16 v[48:51], v[178:181], v[186:189], v[48:51]
	v_mfma_f32_16x16x32_bf16 v[36:39], v[170:173], v[194:197], v[36:39]
	v_mfma_f32_16x16x32_bf16 v[32:35], v[178:181], v[194:197], v[32:35]
	v_mfma_f32_16x16x32_bf16 v[20:23], v[170:173], v[202:205], v[20:23]
	v_mfma_f32_16x16x32_bf16 v[16:19], v[178:181], v[202:205], v[16:19]
	v_mfma_f32_16x16x32_bf16 v[4:7], v[170:173], v[210:213], v[4:7]
	v_mfma_f32_16x16x32_bf16 v[0:3], v[178:181], v[210:213], v[0:3]
	s_setprio 0
	s_barrier
	s_add_i32 s57, s57, 2
	s_add_u32 s20, s20, 0x100
	s_addc_u32 s21, s21, 0
	s_add_u32 s53, s53, 0x100
	s_addc_u32 s56, s56, 0
	s_cmp_gt_u32 s57, 5
	s_cbranch_scc0 .LBB0_1738
	s_and_b64 vcc, exec, s[22:23]
	s_cbranch_vccz .LBB0_1741
	s_barrier

; #define PG8_STAGE(bufoff, gbase, voff) do { _Pragma("unroll") for (int _i = 0; _i < 2; ++_i) \
;         __builtin_amdgcn_global_load_lds((const unsigned*)((const char*)(gbase) + (voff)[_i]), (PG8_LAS unsigned*)(lds + (bufoff) + ldsw + _i * 8192), 16, 0, 0); } while (0)
; #define PG8_LDA(dst, b, h) do { _Pragma("unroll") for (int m = 0; m < 4; ++m) _Pragma("unroll") for (int k = 0; k < 2; ++k) dst[m][k] = *(const PG8_LAS bf16x8*)(lds + PG8_SA(b, h) + aoff + m * 2048 + k * 1024); } while (0)
; #define PG8_LDB(dst, b, h) do { _Pragma("unroll") for (int n = 0; n < 2; ++n) _Pragma("unroll") for (int k = 0; k < 2; ++k) dst[n][k] = *(const PG8_LAS bf16x8*)(lds + PG8_SB(b, h) + boff + n * 2048 + k * 1024); } while (0)
; #define PG8_WAIT_V(n) asm volatile("s_waitcnt vmcnt(" #n ")" ::: "memory")
; #define PG8_WAIT_L(n) asm volatile("s_waitcnt lgkmcnt(" #n ")" ::: "memory")
; #define PG8_BAR __builtin_amdgcn_s_barrier()
; #define PG8_SCHED __builtin_amdgcn_sched_barrier(0)
; template <class Epi, class Sched, bool ALIGN_EPI = false, bool SP2 = false>
; __device__ __forceinline__ void gemm_phase(PG8_LAS unsigned char* lds, const Gemm g, const Sched& S, const Epi& E) {
;     ...
;         const char* nA = has_next ? (const char*)g.A + (size_t)nxt.pm * tstepA : cA; const char* nB = has_next ? (const char*)g.Bt + (size_t)nxt.pn * tstepB : cB;
;         for (int t = 0; t < nt; t += 2) {
;             const bool last = (t == nt - 2);
;             if constexpr (Epi::HAS_MID) { if (t == E.mid_t) E.mid(acc, cur, wr, wc, fr, fq); }
;             const char* a1 = cA + (size_t)(t + 1) * kstep;
;             const char* a2 = last ? nA : cA + (size_t)(t + 2) * kstep; const char* b2 = last ? nB : cB + (size_t)(t + 2) * kstep;
;             const char* a3 = a2 + kstep; const char* b3 = b2 + kstep;
;             if (last && has_next) S.a_ready(nxt);
;             if constexpr (SP2) {
;             PG8_LDB(B0, 0, 0); PG8_LDB(B1, 0, 1); PG8_SCHED; PG8_LDA(At, 0, 0); PG8_STAGE(PG8_SA(1, 1), a1 + hstepA, voffA);
;             PG8_WAIT_V(8); PG8_WAIT_L(0); PG8_BAR; PG8_MMA(0, 0, At, B0); PG8_MMA(0, 1, At, B1); PG8_BAR; PG8_SCHED;
;             PG8_LDA(At, 0, 1); PG8_STAGE(PG8_SB(0, 0), b2, voffB); PG8_STAGE(PG8_SB(0, 1), b2 + hstepB, voffB); PG8_STAGE(PG8_SA(0, 0), a2, voffA);
;             PG8_WAIT_V(8); PG8_WAIT_L(0); PG8_BAR; PG8_MMA(1, 0, At, B0); PG8_MMA(1, 1, At, B1); PG8_BAR; PG8_SCHED;
.Lp7_full_loop:
.LBB0_1824:
	ds_read_b128 v[144:147], v151
	ds_read_b128 v[156:159], v151 offset:1024
	ds_read_b128 v[160:163], v151 offset:2048
	ds_read_b128 v[164:167], v151 offset:3072
	ds_read_b128 v[168:171], v152
	ds_read_b128 v[172:175], v152 offset:1024
	ds_read_b128 v[176:179], v152 offset:2048
	ds_read_b128 v[180:183], v152 offset:3072
	s_add_u32 s34, s30, 0xfff80080
	s_addc_u32 s35, s31, -1
	s_cmp_eq_u32 s62, 28
	s_cselect_b32 s39, s21, s35
	s_cselect_b32 s38, s25, s34
	s_cselect_b32 s35, s23, s61
	s_cselect_b32 s34, s59, s60
	ds_read_b128 v[184:187], v153
	ds_read_b128 v[188:191], v153 offset:1024
	ds_read_b128 v[192:195], v153 offset:2048
	ds_read_b128 v[196:199], v153 offset:3072
	ds_read_b128 v[200:203], v153 offset:4096
	ds_read_b128 v[204:207], v153 offset:5120
	ds_read_b128 v[208:211], v153 offset:6144
	ds_read_b128 v[212:215], v153 offset:7168
	s_add_u32 s98, s30, 0xfff80000
	s_addc_u32 s99, s31, -1
	s_mov_b32 m0, s46
	s_nop 0
	global_load_lds_dwordx4 v134, s[98:99]
	s_mov_b32 m0, s47
	s_nop 0
	global_load_lds_dwordx4 v130, s[98:99]
	s_add_i32 m0, s6, 0xc000
	s_nop 0
	global_load_lds_dwordx4 v136, s[30:31]
	s_add_i32 m0, s6, 0xe000
	s_nop 0
	global_load_lds_dwordx4 v138, s[30:31]
	s_waitcnt vmcnt(8)
	s_waitcnt lgkmcnt(0)
	s_barrier
	s_setprio 1
	v_mfma_f32_16x16x32_bf16 v[124:127], v[144:147], v[184:187], v[124:127]
	v_mfma_f32_16x16x32_bf16 v[116:119], v[160:163], v[184:187], v[116:119]
	v_mfma_f32_16x16x32_bf16 v[108:111], v[144:147], v[192:195], v[108:111]
	v_mfma_f32_16x16x32_bf16 v[100:103], v[160:163], v[192:195], v[100:103]
	v_mfma_f32_16x16x32_bf16 v[92:95], v[144:147], v[200:203], v[92:95]
	v_mfma_f32_16x16x32_bf16 v[84:87], v[160:163], v[200:203], v[84:87]
	v_mfma_f32_16x16x32_bf16 v[76:79], v[144:147], v[208:211], v[76:79]
	v_mfma_f32_16x16x32_bf16 v[68:71], v[160:163], v[208:211], v[68:71]
	v_mfma_f32_16x16x32_bf16 v[124:127], v[156:159], v[188:191], v[124:127]
	v_mfma_f32_16x16x32_bf16 v[116:119], v[164:167], v[188:191], v[116:119]
	v_mfma_f32_16x16x32_bf16 v[108:111], v[156:159], v[196:199], v[108:111]
	v_mfma_f32_16x16x32_bf16 v[100:103], v[164:167], v[196:199], v[100:103]
	v_mfma_f32_16x16x32_bf16 v[92:95], v[156:159], v[204:207], v[92:95]
	v_mfma_f32_16x16x32_bf16 v[84:87], v[164:167], v[204:207], v[84:87]
	v_mfma_f32_16x16x32_bf16 v[76:79], v[156:159], v[212:215], v[76:79]
	v_mfma_f32_16x16x32_bf16 v[68:71], v[164:167], v[212:215], v[68:71]
	v_mfma_f32_16x16x32_bf16 v[120:123], v[168:171], v[184:187], v[120:123]
	v_mfma_f32_16x16x32_bf16 v[112:115], v[176:179], v[184:187], v[112:115]
	v_mfma_f32_16x16x32_bf16 v[104:107], v[168:171], v[192:195], v[104:107]
	v_mfma_f32_16x16x32_bf16 v[96:99], v[176:179], v[192:195], v[96:99]
	v_mfma_f32_16x16x32_bf16 v[88:91], v[168:171], v[200:203], v[88:91]
	v_mfma_f32_16x16x32_bf16 v[80:83], v[176:179], v[200:203], v[80:83]
	v_mfma_f32_16x16x32_bf16 v[72:75], v[168:171], v[208:211], v[72:75]
	v_mfma_f32_16x16x32_bf16 v[64:67], v[176:179], v[208:211], v[64:67]
	v_mfma_f32_16x16x32_bf16 v[120:123], v[172:175], v[188:191], v[120:123]
	v_mfma_f32_16x16x32_bf16 v[112:115], v[180:183], v[188:191], v[112:115]
	v_mfma_f32_16x16x32_bf16 v[104:107], v[172:175], v[196:199], v[104:107]
	v_mfma_f32_16x16x32_bf16 v[96:99], v[180:183], v[196:199], v[96:99]
	v_mfma_f32_16x16x32_bf16 v[88:91], v[172:175], v[204:207], v[88:91]
	v_mfma_f32_16x16x32_bf16 v[80:83], v[180:183], v[204:207], v[80:83]
	v_mfma_f32_16x16x32_bf16 v[72:75], v[172:175], v[212:215], v[72:75]
	v_mfma_f32_16x16x32_bf16 v[64:67], v[180:183], v[212:215], v[64:67]
	s_setprio 0
	s_barrier
	s_add_i32 s63, s53, s4
	s_mov_b32 m0, s63
	ds_read_b128 v[184:187], v153 offset:16384
	ds_read_b128 v[188:191], v153 offset:17408
	ds_read_b128 v[192:195], v153 offset:18432
	ds_read_b128 v[196:199], v153 offset:19456
	ds_read_b128 v[200:203], v153 offset:20480
	ds_read_b128 v[204:207], v153 offset:21504
	ds_read_b128 v[208:211], v153 offset:22528
	ds_read_b128 v[212:215], v153 offset:23552
	global_load_lds_dwordx4 v132, s[34:35]
	s_add_i32 m0, s63, 0x2000
	s_add_u32 s64, s34, 0x80000
	s_addc_u32 s65, s35, 0
	s_add_i32 s63, s54, s4
	global_load_lds_dwordx4 v128, s[34:35]
	s_mov_b32 m0, s63
	s_nop 0
	global_load_lds_dwordx4 v132, s[64:65]
	s_add_i32 m0, s63, 0x2000
	s_nop 0
	global_load_lds_dwordx4 v128, s[64:65]
	s_waitcnt vmcnt(6)
	s_waitcnt lgkmcnt(0)
	s_barrier
	s_setprio 1
	v_mfma_f32_16x16x32_bf16 v[60:63], v[144:147], v[184:187], v[60:63]
	v_mfma_f32_16x16x32_bf16 v[52:55], v[160:163], v[184:187], v[52:55]
	v_mfma_f32_16x16x32_bf16 v[44:47], v[144:147], v[192:195], v[44:47]
	v_mfma_f32_16x16x32_bf16 v[36:39], v[160:163], v[192:195], v[36:39]
	v_mfma_f32_16x16x32_bf16 v[28:31], v[144:147], v[200:203], v[28:31]
	v_mfma_f32_16x16x32_bf16 v[20:23], v[160:163], v[200:203], v[20:23]
	v_mfma_f32_16x16x32_bf16 v[12:15], v[144:147], v[208:211], v[12:15]
	v_mfma_f32_16x16x32_bf16 v[4:7], v[160:163], v[208:211], v[4:7]
	v_mfma_f32_16x16x32_bf16 v[60:63], v[156:159], v[188:191], v[60:63]
	v_mfma_f32_16x16x32_bf16 v[52:55], v[164:167], v[188:191], v[52:55]
	v_mfma_f32_16x16x32_bf16 v[44:47], v[156:159], v[196:199], v[44:47]
	v_mfma_f32_16x16x32_bf16 v[36:39], v[164:167], v[196:199], v[36:39]
	v_mfma_f32_16x16x32_bf16 v[28:31], v[156:159], v[204:207], v[28:31]
	v_mfma_f32_16x16x32_bf16 v[20:23], v[164:167], v[204:207], v[20:23]
	v_mfma_f32_16x16x32_bf16 v[12:15], v[156:159], v[212:215], v[12:15]
	v_mfma_f32_16x16x32_bf16 v[4:7], v[164:167], v[212:215], v[4:7]
	v_mfma_f32_16x16x32_bf16 v[56:59], v[168:171], v[184:187], v[56:59]
	v_mfma_f32_16x16x32_bf16 v[48:51], v[176:179], v[184:187], v[48:51]
	v_mfma_f32_16x16x32_bf16 v[40:43], v[168:171], v[192:195], v[40:43]
	v_mfma_f32_16x16x32_bf16 v[32:35], v[176:179], v[192:195], v[32:35]
	v_mfma_f32_16x16x32_bf16 v[24:27], v[168:171], v[200:203], v[24:27]
	v_mfma_f32_16x16x32_bf16 v[16:19], v[176:179], v[200:203], v[16:19]
	v_mfma_f32_16x16x32_bf16 v[8:11], v[168:171], v[208:211], v[8:11]
	v_mfma_f32_16x16x32_bf16 v[0:3], v[176:179], v[208:211], v[0:3]
	v_mfma_f32_16x16x32_bf16 v[56:59], v[172:175], v[188:191], v[56:59]
	v_mfma_f32_16x16x32_bf16 v[48:51], v[180:183], v[188:191], v[48:51]
	v_mfma_f32_16x16x32_bf16 v[40:43], v[172:175], v[196:199], v[40:43]
	v_mfma_f32_16x16x32_bf16 v[32:35], v[180:183], v[196:199], v[32:35]
	v_mfma_f32_16x16x32_bf16 v[24:27], v[172:175], v[204:207], v[24:27]
	v_mfma_f32_16x16x32_bf16 v[16:19], v[180:183], v[204:207], v[16:19]
	v_mfma_f32_16x16x32_bf16 v[8:11], v[172:175], v[212:215], v[8:11]
	v_mfma_f32_16x16x32_bf16 v[0:3], v[180:183], v[212:215], v[0:3]
	s_setprio 0
	s_barrier
; #define PG8_STAGE(bufoff, gbase, voff) do { _Pragma("unroll") for (int _i = 0; _i < 2; ++_i) \
;         __builtin_amdgcn_global_load_lds((const unsigned*)((const char*)(gbase) + (voff)[_i]), (PG8_LAS unsigned*)(lds + (bufoff) + ldsw + _i * 8192), 16, 0, 0); } while (0)
; #define PG8_LDA(dst, b, h) do { _Pragma("unroll") for (int m = 0; m < 4; ++m) _Pragma("unroll") for (int k = 0; k < 2; ++k) dst[m][k] = *(const PG8_LAS bf16x8*)(lds + PG8_SA(b, h) + aoff + m * 2048 + k * 1024); } while (0)
; #define PG8_LDB(dst, b, h) do { _Pragma("unroll") for (int n = 0; n < 2; ++n) _Pragma("unroll") for (int k = 0; k < 2; ++k) dst[n][k] = *(const PG8_LAS bf16x8*)(lds + PG8_SB(b, h) + boff + n * 2048 + k * 1024); } while (0)
; #define PG8_WAIT_V(n) asm volatile("s_waitcnt vmcnt(" #n ")" ::: "memory")
; template <class Epi, class Sched, bool ALIGN_EPI = false, bool SP2 = false>
; __device__ __forceinline__ void gemm_phase(PG8_LAS unsigned char* lds, const Gemm g, const Sched& S, const Epi& E) {
;     ...
;             const char* a1 = cA + (size_t)(t + 1) * kstep;
;             const char* a2 = last ? nA : cA + (size_t)(t + 2) * kstep; const char* b2 = last ? nB : cB + (size_t)(t + 2) * kstep;
;             const char* a3 = a2 + kstep; const char* b3 = b2 + kstep;
;             if (last && has_next) S.a_ready(nxt);
;             if constexpr (SP2) {
;             PG8_LDB(B0, 0, 0); PG8_LDB(B1, 0, 1); PG8_SCHED; PG8_LDA(At, 0, 0); PG8_STAGE(PG8_SA(1, 1), a1 + hstepA, voffA);
;             PG8_WAIT_V(8); PG8_WAIT_L(0); PG8_BAR; PG8_MMA(0, 0, At, B0); PG8_MMA(0, 1, At, B1); PG8_BAR; PG8_SCHED;
;             PG8_LDA(At, 0, 1); PG8_STAGE(PG8_SB(0, 0), b2, voffB); PG8_STAGE(PG8_SB(0, 1), b2 + hstepB, voffB); PG8_STAGE(PG8_SA(0, 0), a2, voffA);
;             PG8_WAIT_V(8); PG8_WAIT_L(0); PG8_BAR; PG8_MMA(1, 0, At, B0); PG8_MMA(1, 1, At, B1); PG8_BAR; PG8_SCHED;
;             PG8_LDB(B0, 1, 0); PG8_LDB(B1, 1, 1); PG8_SCHED; PG8_LDA(At, 1, 0); PG8_STAGE(PG8_SA(0, 1), a2 + hstepA, voffA);
;             PG8_WAIT_V(8); PG8_WAIT_L(0); PG8_BAR; PG8_MMA(0, 0, At, B0); PG8_MMA(0, 1, At, B1); PG8_BAR; PG8_SCHED;
;             PG8_LDA(At, 1, 1); PG8_STAGE(PG8_SB(1, 0), b3, voffB); PG8_STAGE(PG8_SB(1, 1), b3 + hstepB, voffB); PG8_STAGE(PG8_SA(1, 0), a3, voffA);
;             PG8_WAIT_V(8); PG8_WAIT_L(0); PG8_BAR; PG8_MMA(1, 0, At, B0); PG8_MMA(1, 1, At, B1); PG8_BAR; PG8_SCHED;
	s_add_i32 s63, 0, 0x18000
	v_add_u32_e32 v155, s63, v150
	s_add_i32 s64, 0, 0x1c000
	ds_read_b128 v[144:147], v155
	ds_read_b128 v[156:159], v155 offset:1024
	ds_read_b128 v[160:163], v155 offset:2048
	ds_read_b128 v[164:167], v155 offset:3072
	v_add_u32_e32 v155, s64, v150
	ds_read_b128 v[168:171], v155
	ds_read_b128 v[172:175], v155 offset:1024
	ds_read_b128 v[176:179], v155 offset:2048
	ds_read_b128 v[180:183], v155 offset:3072
	s_mov_b64 s[100:101], s[38:39]
	s_add_u32 s38, s38, 0x80000
	s_addc_u32 s39, s39, 0
	ds_read_b128 v[184:187], v153 offset:32768
	ds_read_b128 v[188:191], v153 offset:33792
	ds_read_b128 v[192:195], v153 offset:34816
	ds_read_b128 v[196:199], v153 offset:35840
	ds_read_b128 v[200:203], v153 offset:36864
	ds_read_b128 v[204:207], v153 offset:37888
	ds_read_b128 v[208:211], v153 offset:38912
	ds_read_b128 v[212:215], v153 offset:39936
	s_mov_b32 m0, s6
	s_nop 0
	global_load_lds_dwordx4 v134, s[100:101]
	s_mov_b32 m0, s7
	s_nop 0
	global_load_lds_dwordx4 v130, s[100:101]
	s_mov_b32 m0, s41
	s_nop 0
	global_load_lds_dwordx4 v134, s[38:39]
	s_mov_b32 m0, s42
	s_nop 0
	global_load_lds_dwordx4 v130, s[38:39]
	s_waitcnt vmcnt(8)
	s_waitcnt lgkmcnt(0)
	s_barrier
	s_setprio 1
	v_mfma_f32_16x16x32_bf16 v[124:127], v[144:147], v[184:187], v[124:127]
	v_mfma_f32_16x16x32_bf16 v[116:119], v[160:163], v[184:187], v[116:119]
	v_mfma_f32_16x16x32_bf16 v[108:111], v[144:147], v[192:195], v[108:111]
	v_mfma_f32_16x16x32_bf16 v[100:103], v[160:163], v[192:195], v[100:103]
	v_mfma_f32_16x16x32_bf16 v[92:95], v[144:147], v[200:203], v[92:95]
	v_mfma_f32_16x16x32_bf16 v[84:87], v[160:163], v[200:203], v[84:87]
	v_mfma_f32_16x16x32_bf16 v[76:79], v[144:147], v[208:211], v[76:79]
	v_mfma_f32_16x16x32_bf16 v[68:71], v[160:163], v[208:211], v[68:71]
	v_mfma_f32_16x16x32_bf16 v[124:127], v[156:159], v[188:191], v[124:127]
	v_mfma_f32_16x16x32_bf16 v[116:119], v[164:167], v[188:191], v[116:119]
	v_mfma_f32_16x16x32_bf16 v[108:111], v[156:159], v[196:199], v[108:111]
	v_mfma_f32_16x16x32_bf16 v[100:103], v[164:167], v[196:199], v[100:103]
	v_mfma_f32_16x16x32_bf16 v[92:95], v[156:159], v[204:207], v[92:95]
	v_mfma_f32_16x16x32_bf16 v[84:87], v[164:167], v[204:207], v[84:87]
	v_mfma_f32_16x16x32_bf16 v[76:79], v[156:159], v[212:215], v[76:79]
	v_mfma_f32_16x16x32_bf16 v[68:71], v[164:167], v[212:215], v[68:71]
	v_mfma_f32_16x16x32_bf16 v[120:123], v[168:171], v[184:187], v[120:123]
	v_mfma_f32_16x16x32_bf16 v[112:115], v[176:179], v[184:187], v[112:115]
	v_mfma_f32_16x16x32_bf16 v[104:107], v[168:171], v[192:195], v[104:107]
	v_mfma_f32_16x16x32_bf16 v[96:99], v[176:179], v[192:195], v[96:99]
	v_mfma_f32_16x16x32_bf16 v[88:91], v[168:171], v[200:203], v[88:91]
	v_mfma_f32_16x16x32_bf16 v[80:83], v[176:179], v[200:203], v[80:83]
	v_mfma_f32_16x16x32_bf16 v[72:75], v[168:171], v[208:211], v[72:75]
	v_mfma_f32_16x16x32_bf16 v[64:67], v[176:179], v[208:211], v[64:67]
	v_mfma_f32_16x16x32_bf16 v[120:123], v[172:175], v[188:191], v[120:123]
	v_mfma_f32_16x16x32_bf16 v[112:115], v[180:183], v[188:191], v[112:115]
	v_mfma_f32_16x16x32_bf16 v[104:107], v[172:175], v[196:199], v[104:107]
	v_mfma_f32_16x16x32_bf16 v[96:99], v[180:183], v[196:199], v[96:99]
	v_mfma_f32_16x16x32_bf16 v[88:91], v[172:175], v[204:207], v[88:91]
	v_mfma_f32_16x16x32_bf16 v[80:83], v[180:183], v[204:207], v[80:83]
	v_mfma_f32_16x16x32_bf16 v[72:75], v[172:175], v[212:215], v[72:75]
	v_mfma_f32_16x16x32_bf16 v[64:67], v[180:183], v[212:215], v[64:67]
	s_setprio 0
	s_barrier
	s_add_i32 s38, s63, s4
	s_add_u32 s98, s34, 0x80
	s_addc_u32 s99, s35, 0
	s_mov_b32 m0, s38
	ds_read_b128 v[184:187], v153 offset:49152
	ds_read_b128 v[188:191], v153 offset:50176
	ds_read_b128 v[192:195], v153 offset:51200
	ds_read_b128 v[196:199], v153 offset:52224
	ds_read_b128 v[200:203], v153 offset:53248
	ds_read_b128 v[204:207], v153 offset:54272
	ds_read_b128 v[208:211], v153 offset:55296
	ds_read_b128 v[212:215], v153 offset:56320
	global_load_lds_dwordx4 v132, s[98:99]
	s_add_i32 m0, s38, 0x2000
	s_add_u32 s34, s34, 0x80080
	s_addc_u32 s35, s35, 0
	s_add_i32 s38, s64, s4
	global_load_lds_dwordx4 v128, s[98:99]
	s_mov_b32 m0, s38
	s_nop 0
	global_load_lds_dwordx4 v132, s[34:35]
	s_add_i32 m0, s38, 0x2000
	s_nop 0
	global_load_lds_dwordx4 v128, s[34:35]
	s_waitcnt vmcnt(6)
	s_waitcnt lgkmcnt(0)
	s_barrier
	s_setprio 1
	v_mfma_f32_16x16x32_bf16 v[60:63], v[144:147], v[184:187], v[60:63]
	v_mfma_f32_16x16x32_bf16 v[52:55], v[160:163], v[184:187], v[52:55]
	v_mfma_f32_16x16x32_bf16 v[44:47], v[144:147], v[192:195], v[44:47]
	v_mfma_f32_16x16x32_bf16 v[36:39], v[160:163], v[192:195], v[36:39]
	v_mfma_f32_16x16x32_bf16 v[28:31], v[144:147], v[200:203], v[28:31]
	v_mfma_f32_16x16x32_bf16 v[20:23], v[160:163], v[200:203], v[20:23]
	v_mfma_f32_16x16x32_bf16 v[12:15], v[144:147], v[208:211], v[12:15]
	v_mfma_f32_16x16x32_bf16 v[4:7], v[160:163], v[208:211], v[4:7]
	v_mfma_f32_16x16x32_bf16 v[60:63], v[156:159], v[188:191], v[60:63]
	v_mfma_f32_16x16x32_bf16 v[52:55], v[164:167], v[188:191], v[52:55]
	v_mfma_f32_16x16x32_bf16 v[44:47], v[156:159], v[196:199], v[44:47]
	v_mfma_f32_16x16x32_bf16 v[36:39], v[164:167], v[196:199], v[36:39]
	v_mfma_f32_16x16x32_bf16 v[28:31], v[156:159], v[204:207], v[28:31]
	v_mfma_f32_16x16x32_bf16 v[20:23], v[164:167], v[204:207], v[20:23]
	v_mfma_f32_16x16x32_bf16 v[12:15], v[156:159], v[212:215], v[12:15]
	v_mfma_f32_16x16x32_bf16 v[4:7], v[164:167], v[212:215], v[4:7]
	v_mfma_f32_16x16x32_bf16 v[56:59], v[168:171], v[184:187], v[56:59]
	v_mfma_f32_16x16x32_bf16 v[48:51], v[176:179], v[184:187], v[48:51]
	v_mfma_f32_16x16x32_bf16 v[40:43], v[168:171], v[192:195], v[40:43]
	v_mfma_f32_16x16x32_bf16 v[32:35], v[176:179], v[192:195], v[32:35]
	v_mfma_f32_16x16x32_bf16 v[24:27], v[168:171], v[200:203], v[24:27]
	v_mfma_f32_16x16x32_bf16 v[16:19], v[176:179], v[200:203], v[16:19]
	v_mfma_f32_16x16x32_bf16 v[8:11], v[168:171], v[208:211], v[8:11]
	v_mfma_f32_16x16x32_bf16 v[0:3], v[176:179], v[208:211], v[0:3]
	v_mfma_f32_16x16x32_bf16 v[56:59], v[172:175], v[188:191], v[56:59]
	v_mfma_f32_16x16x32_bf16 v[48:51], v[180:183], v[188:191], v[48:51]
	v_mfma_f32_16x16x32_bf16 v[40:43], v[172:175], v[196:199], v[40:43]
	v_mfma_f32_16x16x32_bf16 v[32:35], v[180:183], v[196:199], v[32:35]
	v_mfma_f32_16x16x32_bf16 v[24:27], v[172:175], v[204:207], v[24:27]
	v_mfma_f32_16x16x32_bf16 v[16:19], v[180:183], v[204:207], v[16:19]
	v_mfma_f32_16x16x32_bf16 v[8:11], v[172:175], v[212:215], v[8:11]
	v_mfma_f32_16x16x32_bf16 v[0:3], v[180:183], v[212:215], v[0:3]
	s_setprio 0
	s_barrier
	s_add_i32 s62, s62, 2
	s_add_u32 s30, s30, 0x100
	s_addc_u32 s31, s31, 0
	s_add_u32 s60, s60, 0x100
	s_addc_u32 s61, s61, 0
	s_cmp_gt_u32 s62, 29
	s_cbranch_scc0 .LBB0_1824

; #define PG8_STAGE(bufoff, gbase, voff) do { _Pragma("unroll") for (int _i = 0; _i < 2; ++_i) \
;         __builtin_amdgcn_global_load_lds((const unsigned*)((const char*)(gbase) + (voff)[_i]), (PG8_LAS unsigned*)(lds + (bufoff) + ldsw + _i * 8192), 16, 0, 0); } while (0)
; #define PG8_LDA(dst, b, h) do { _Pragma("unroll") for (int m = 0; m < 4; ++m) _Pragma("unroll") for (int k = 0; k < 2; ++k) dst[m][k] = *(const PG8_LAS bf16x8*)(lds + PG8_SA(b, h) + aoff + m * 2048 + k * 1024); } while (0)
; #define PG8_LDB(dst, b, h) do { _Pragma("unroll") for (int n = 0; n < 2; ++n) _Pragma("unroll") for (int k = 0; k < 2; ++k) dst[n][k] = *(const PG8_LAS bf16x8*)(lds + PG8_SB(b, h) + boff + n * 2048 + k * 1024); } while (0)
; #define PG8_WAIT_V(n) asm volatile("s_waitcnt vmcnt(" #n ")" ::: "memory")
; #define PG8_WAIT_L(n) asm volatile("s_waitcnt lgkmcnt(" #n ")" ::: "memory")
; template <class Epi, class Sched, bool ALIGN_EPI = false, bool SP2 = false>
; __device__ __forceinline__ void gemm_phase(PG8_LAS unsigned char* lds, const Gemm g, const Sched& S, const Epi& E) {
;     ...
;         for (int t = 0; t < nt; t += 2) {
;             const bool last = (t == nt - 2);
;             if constexpr (Epi::HAS_MID) { if (t == E.mid_t) E.mid(acc, cur, wr, wc, fr, fq); }
;             const char* a1 = cA + (size_t)(t + 1) * kstep;
;             const char* a2 = last ? nA : cA + (size_t)(t + 2) * kstep; const char* b2 = last ? nB : cB + (size_t)(t + 2) * kstep;
;             const char* a3 = a2 + kstep; const char* b3 = b2 + kstep;
;             if (last && has_next) S.a_ready(nxt);
;             if constexpr (SP2) {
;             PG8_LDB(B0, 0, 0); PG8_LDB(B1, 0, 1); PG8_SCHED; PG8_LDA(At, 0, 0); PG8_STAGE(PG8_SA(1, 1), a1 + hstepA, voffA);
;             PG8_WAIT_V(8); PG8_WAIT_L(0); PG8_BAR; PG8_MMA(0, 0, At, B0); PG8_MMA(0, 1, At, B1); PG8_BAR; PG8_SCHED;
;             PG8_LDA(At, 0, 1); PG8_STAGE(PG8_SB(0, 0), b2, voffB); PG8_STAGE(PG8_SB(0, 1), b2 + hstepB, voffB); PG8_STAGE(PG8_SA(0, 0), a2, voffA);
;             PG8_WAIT_V(8); PG8_WAIT_L(0); PG8_BAR; PG8_MMA(1, 0, At, B0); PG8_MMA(1, 1, At, B1); PG8_BAR; PG8_SCHED;
;             PG8_LDB(B0, 1, 0); PG8_LDB(B1, 1, 1); PG8_SCHED; PG8_LDA(At, 1, 0); PG8_STAGE(PG8_SA(0, 1), a2 + hstepA, voffA);
;             PG8_WAIT_V(8); PG8_WAIT_L(0); PG8_BAR; PG8_MMA(0, 0, At, B0); PG8_MMA(0, 1, At, B1); PG8_BAR; PG8_SCHED;
.Lp7h_loop:
	ds_read_b128 v[144:147], v151
	ds_read_b128 v[156:159], v151 offset:1024
	ds_read_b128 v[160:163], v151 offset:2048
	ds_read_b128 v[164:167], v151 offset:3072
	ds_read_b128 v[168:171], v152
	ds_read_b128 v[172:175], v152 offset:1024
	ds_read_b128 v[176:179], v152 offset:2048
	ds_read_b128 v[180:183], v152 offset:3072
	s_add_u32 s34, s30, 0xfff80080
	s_addc_u32 s35, s31, -1
	s_cmp_eq_u32 s62, 28
	s_cselect_b32 s39, s21, s35
	s_cselect_b32 s38, s25, s34
	s_cselect_b32 s35, s23, s61
	s_cselect_b32 s34, s59, s60
	s_add_i32 m0, s6, 0xc000
	s_nop 0
	global_load_lds_dwordx4 v136, s[30:31]
	s_add_i32 m0, s6, 0xe000
	s_nop 0
	global_load_lds_dwordx4 v138, s[30:31]
	s_waitcnt vmcnt(6)
	s_waitcnt lgkmcnt(0)
	s_barrier
	s_setprio 1
	s_waitcnt lgkmcnt(0)
	v_mfma_f32_16x16x32_bf16 v[56:59], v[80:83], v[184:187], v[56:59]
	v_mfma_f32_16x16x32_bf16 v[48:51], v[88:91], v[184:187], v[48:51]
	v_mfma_f32_16x16x32_bf16 v[40:43], v[80:83], v[192:195], v[40:43]
	v_mfma_f32_16x16x32_bf16 v[32:35], v[88:91], v[192:195], v[32:35]
	v_mfma_f32_16x16x32_bf16 v[24:27], v[80:83], v[200:203], v[24:27]
	v_mfma_f32_16x16x32_bf16 v[16:19], v[88:91], v[200:203], v[16:19]
	v_mfma_f32_16x16x32_bf16 v[8:11], v[80:83], v[208:211], v[8:11]
	v_mfma_f32_16x16x32_bf16 v[0:3], v[88:91], v[208:211], v[0:3]
	v_mfma_f32_16x16x32_bf16 v[56:59], v[84:87], v[188:191], v[56:59]
	v_mfma_f32_16x16x32_bf16 v[48:51], v[92:95], v[188:191], v[48:51]
	v_mfma_f32_16x16x32_bf16 v[40:43], v[84:87], v[196:199], v[40:43]
	v_mfma_f32_16x16x32_bf16 v[32:35], v[92:95], v[196:199], v[32:35]
	v_mfma_f32_16x16x32_bf16 v[24:27], v[84:87], v[204:207], v[24:27]
	v_mfma_f32_16x16x32_bf16 v[16:19], v[92:95], v[204:207], v[16:19]
	v_mfma_f32_16x16x32_bf16 v[8:11], v[84:87], v[212:215], v[8:11]
	v_mfma_f32_16x16x32_bf16 v[0:3], v[92:95], v[212:215], v[0:3]
	s_setprio 0
	s_barrier
	s_add_i32 s63, s53, s4
	s_mov_b32 m0, s63
	ds_read_b128 v[184:187], v153 offset:16384
	ds_read_b128 v[188:191], v153 offset:17408
	ds_read_b128 v[192:195], v153 offset:18432
	ds_read_b128 v[196:199], v153 offset:19456
	ds_read_b128 v[200:203], v153 offset:20480
	ds_read_b128 v[204:207], v153 offset:21504
	ds_read_b128 v[208:211], v153 offset:22528
	ds_read_b128 v[212:215], v153 offset:23552
	global_load_lds_dwordx4 v132, s[34:35]
	s_add_i32 m0, s63, 0x2000
	s_add_u32 s64, s34, 0x80000
	s_addc_u32 s65, s35, 0
	s_add_i32 s63, s54, s4
	global_load_lds_dwordx4 v128, s[34:35]
	s_mov_b32 m0, s63
	s_nop 0
	global_load_lds_dwordx4 v132, s[64:65]
	s_add_i32 m0, s63, 0x2000
	s_nop 0
	global_load_lds_dwordx4 v128, s[64:65]
	s_waitcnt vmcnt(6)
	s_waitcnt lgkmcnt(0)
	s_barrier
	s_setprio 1
	s_waitcnt lgkmcnt(0)
	v_mfma_f32_16x16x32_bf16 v[60:63], v[144:147], v[184:187], v[60:63]
	v_mfma_f32_16x16x32_bf16 v[52:55], v[160:163], v[184:187], v[52:55]
	v_mfma_f32_16x16x32_bf16 v[44:47], v[144:147], v[192:195], v[44:47]
	v_mfma_f32_16x16x32_bf16 v[36:39], v[160:163], v[192:195], v[36:39]
	v_mfma_f32_16x16x32_bf16 v[28:31], v[144:147], v[200:203], v[28:31]
	v_mfma_f32_16x16x32_bf16 v[20:23], v[160:163], v[200:203], v[20:23]
	v_mfma_f32_16x16x32_bf16 v[12:15], v[144:147], v[208:211], v[12:15]
	v_mfma_f32_16x16x32_bf16 v[4:7], v[160:163], v[208:211], v[4:7]
	v_mfma_f32_16x16x32_bf16 v[60:63], v[156:159], v[188:191], v[60:63]
	v_mfma_f32_16x16x32_bf16 v[52:55], v[164:167], v[188:191], v[52:55]
	v_mfma_f32_16x16x32_bf16 v[44:47], v[156:159], v[196:199], v[44:47]
	v_mfma_f32_16x16x32_bf16 v[36:39], v[164:167], v[196:199], v[36:39]
	v_mfma_f32_16x16x32_bf16 v[28:31], v[156:159], v[204:207], v[28:31]
	v_mfma_f32_16x16x32_bf16 v[20:23], v[164:167], v[204:207], v[20:23]
	v_mfma_f32_16x16x32_bf16 v[12:15], v[156:159], v[212:215], v[12:15]
	v_mfma_f32_16x16x32_bf16 v[4:7], v[164:167], v[212:215], v[4:7]
	s_setprio 0
	s_barrier
	s_add_i32 s63, 0, 0x18000
	v_add_u32_e32 v155, s63, v150
	s_add_i32 s64, 0, 0x1c000
	ds_read_b128 v[64:67], v155
	ds_read_b128 v[68:71], v155 offset:1024
	ds_read_b128 v[72:75], v155 offset:2048
	ds_read_b128 v[76:79], v155 offset:3072
	v_add_u32_e32 v155, s64, v150
	ds_read_b128 v[80:83], v155
	ds_read_b128 v[84:87], v155 offset:1024
	ds_read_b128 v[88:91], v155 offset:2048
	ds_read_b128 v[92:95], v155 offset:3072
	s_add_u32 s38, s38, 0x80000
	s_addc_u32 s39, s39, 0
	s_mov_b32 m0, s41
	s_nop 0
	global_load_lds_dwordx4 v134, s[38:39]
	s_mov_b32 m0, s42
	s_nop 0
	global_load_lds_dwordx4 v130, s[38:39]
	s_waitcnt vmcnt(6)
	s_waitcnt lgkmcnt(0)
	s_barrier
; #define PG8_STAGE(bufoff, gbase, voff) do { _Pragma("unroll") for (int _i = 0; _i < 2; ++_i) \
;         __builtin_amdgcn_global_load_lds((const unsigned*)((const char*)(gbase) + (voff)[_i]), (PG8_LAS unsigned*)(lds + (bufoff) + ldsw + _i * 8192), 16, 0, 0); } while (0)
; #define PG8_LDA(dst, b, h) do { _Pragma("unroll") for (int m = 0; m < 4; ++m) _Pragma("unroll") for (int k = 0; k < 2; ++k) dst[m][k] = *(const PG8_LAS bf16x8*)(lds + PG8_SA(b, h) + aoff + m * 2048 + k * 1024); } while (0)
; #define PG8_MMA(ai, bj, At, Bt) do { __builtin_amdgcn_s_setprio(1); _Pragma("unroll") for (int m = 0; m < 4; ++m) _Pragma("unroll") for (int n = 0; n < 2; ++n) _Pragma("unroll") for (int k = 0; k < 2; ++k) \
;         acc[ai][bj][m][n] = __builtin_amdgcn_mfma_f32_16x16x32_bf16(Bt[n][k], At[m][k], acc[ai][bj][m][n], 0, 0, 0); __builtin_amdgcn_s_setprio(0); } while (0)
; #define PG8_WAIT_V(n) asm volatile("s_waitcnt vmcnt(" #n ")" ::: "memory")
; #define PG8_WAIT_L(n) asm volatile("s_waitcnt lgkmcnt(" #n ")" ::: "memory")
; #define PG8_BAR __builtin_amdgcn_s_barrier()
; #define PG8_SCHED __builtin_amdgcn_sched_barrier(0)
; template <class Epi, class Sched, bool ALIGN_EPI = false, bool SP2 = false>
; __device__ __forceinline__ void gemm_phase(PG8_LAS unsigned char* lds, const Gemm g, const Sched& S, const Epi& E) {
;     ...
;             PG8_WAIT_V(8); PG8_WAIT_L(0); PG8_BAR; PG8_MMA(0, 0, At, B0); PG8_MMA(0, 1, At, B1); PG8_BAR; PG8_SCHED;
;             PG8_LDA(At, 1, 1); PG8_STAGE(PG8_SB(1, 0), b3, voffB); PG8_STAGE(PG8_SB(1, 1), b3 + hstepB, voffB); PG8_STAGE(PG8_SA(1, 0), a3, voffA);
;             PG8_WAIT_V(8); PG8_WAIT_L(0); PG8_BAR; PG8_MMA(1, 0, At, B0); PG8_MMA(1, 1, At, B1); PG8_BAR; PG8_SCHED;
	s_setprio 1
	s_waitcnt lgkmcnt(0)
	v_mfma_f32_16x16x32_bf16 v[56:59], v[168:171], v[184:187], v[56:59]
	v_mfma_f32_16x16x32_bf16 v[48:51], v[176:179], v[184:187], v[48:51]
	v_mfma_f32_16x16x32_bf16 v[40:43], v[168:171], v[192:195], v[40:43]
	v_mfma_f32_16x16x32_bf16 v[32:35], v[176:179], v[192:195], v[32:35]
	v_mfma_f32_16x16x32_bf16 v[24:27], v[168:171], v[200:203], v[24:27]
	v_mfma_f32_16x16x32_bf16 v[16:19], v[176:179], v[200:203], v[16:19]
	v_mfma_f32_16x16x32_bf16 v[8:11], v[168:171], v[208:211], v[8:11]
	v_mfma_f32_16x16x32_bf16 v[0:3], v[176:179], v[208:211], v[0:3]
	v_mfma_f32_16x16x32_bf16 v[56:59], v[172:175], v[188:191], v[56:59]
	v_mfma_f32_16x16x32_bf16 v[48:51], v[180:183], v[188:191], v[48:51]
	v_mfma_f32_16x16x32_bf16 v[40:43], v[172:175], v[196:199], v[40:43]
	v_mfma_f32_16x16x32_bf16 v[32:35], v[180:183], v[196:199], v[32:35]
	v_mfma_f32_16x16x32_bf16 v[24:27], v[172:175], v[204:207], v[24:27]
	v_mfma_f32_16x16x32_bf16 v[16:19], v[180:183], v[204:207], v[16:19]
	v_mfma_f32_16x16x32_bf16 v[8:11], v[172:175], v[212:215], v[8:11]
	v_mfma_f32_16x16x32_bf16 v[0:3], v[180:183], v[212:215], v[0:3]
	s_setprio 0
	s_barrier
	s_add_i32 s38, s63, s4
	s_add_u32 s98, s34, 0x80
	s_addc_u32 s99, s35, 0
	s_mov_b32 m0, s38
	ds_read_b128 v[184:187], v153 offset:49152
	ds_read_b128 v[188:191], v153 offset:50176
	ds_read_b128 v[192:195], v153 offset:51200
	ds_read_b128 v[196:199], v153 offset:52224
	ds_read_b128 v[200:203], v153 offset:53248
	ds_read_b128 v[204:207], v153 offset:54272
	ds_read_b128 v[208:211], v153 offset:55296
	ds_read_b128 v[212:215], v153 offset:56320
	global_load_lds_dwordx4 v132, s[98:99]
	s_add_i32 m0, s38, 0x2000
	s_add_u32 s34, s34, 0x80080
	s_addc_u32 s35, s35, 0
	s_add_i32 s38, s64, s4
	global_load_lds_dwordx4 v128, s[98:99]
	s_mov_b32 m0, s38
	s_nop 0
	global_load_lds_dwordx4 v132, s[34:35]
	s_add_i32 m0, s38, 0x2000
	s_nop 0
	global_load_lds_dwordx4 v128, s[34:35]
	s_waitcnt vmcnt(6)
	s_waitcnt lgkmcnt(0)
	s_barrier
	s_setprio 1
	s_waitcnt lgkmcnt(0)
	v_mfma_f32_16x16x32_bf16 v[60:63], v[64:67], v[184:187], v[60:63]
	v_mfma_f32_16x16x32_bf16 v[52:55], v[72:75], v[184:187], v[52:55]
	v_mfma_f32_16x16x32_bf16 v[44:47], v[64:67], v[192:195], v[44:47]
	v_mfma_f32_16x16x32_bf16 v[36:39], v[72:75], v[192:195], v[36:39]
	v_mfma_f32_16x16x32_bf16 v[28:31], v[64:67], v[200:203], v[28:31]
	v_mfma_f32_16x16x32_bf16 v[20:23], v[72:75], v[200:203], v[20:23]
	v_mfma_f32_16x16x32_bf16 v[12:15], v[64:67], v[208:211], v[12:15]
	v_mfma_f32_16x16x32_bf16 v[4:7], v[72:75], v[208:211], v[4:7]
	v_mfma_f32_16x16x32_bf16 v[60:63], v[68:71], v[188:191], v[60:63]
	v_mfma_f32_16x16x32_bf16 v[52:55], v[76:79], v[188:191], v[52:55]
	v_mfma_f32_16x16x32_bf16 v[44:47], v[68:71], v[196:199], v[44:47]
	v_mfma_f32_16x16x32_bf16 v[36:39], v[76:79], v[196:199], v[36:39]
	v_mfma_f32_16x16x32_bf16 v[28:31], v[68:71], v[204:207], v[28:31]
	v_mfma_f32_16x16x32_bf16 v[20:23], v[76:79], v[204:207], v[20:23]
	v_mfma_f32_16x16x32_bf16 v[12:15], v[68:71], v[212:215], v[12:15]
	v_mfma_f32_16x16x32_bf16 v[4:7], v[76:79], v[212:215], v[4:7]
	s_setprio 0
	s_barrier
	s_add_i32 s62, s62, 2
	s_add_u32 s30, s30, 0x100
	s_addc_u32 s31, s31, 0
	s_add_u32 s60, s60, 0x100
	s_addc_u32 s61, s61, 0
	s_cmp_gt_u32 s62, 29
	s_cbranch_scc0 .Lp7h_loop
	v_mfma_f32_16x16x32_bf16 v[56:59], v[80:83], v[184:187], v[56:59]
	v_mfma_f32_16x16x32_bf16 v[48:51], v[88:91], v[184:187], v[48:51]
	v_mfma_f32_16x16x32_bf16 v[40:43], v[80:83], v[192:195], v[40:43]
	v_mfma_f32_16x16x32_bf16 v[32:35], v[88:91], v[192:195], v[32:35]
	v_mfma_f32_16x16x32_bf16 v[24:27], v[80:83], v[200:203], v[24:27]
	v_mfma_f32_16x16x32_bf16 v[16:19], v[88:91], v[200:203], v[16:19]
	v_mfma_f32_16x16x32_bf16 v[8:11], v[80:83], v[208:211], v[8:11]
	v_mfma_f32_16x16x32_bf16 v[0:3], v[88:91], v[208:211], v[0:3]
	v_mfma_f32_16x16x32_bf16 v[56:59], v[84:87], v[188:191], v[56:59]
	v_mfma_f32_16x16x32_bf16 v[48:51], v[92:95], v[188:191], v[48:51]
	v_mfma_f32_16x16x32_bf16 v[40:43], v[84:87], v[196:199], v[40:43]
	v_mfma_f32_16x16x32_bf16 v[32:35], v[92:95], v[196:199], v[32:35]
	v_mfma_f32_16x16x32_bf16 v[24:27], v[84:87], v[204:207], v[24:27]
	v_mfma_f32_16x16x32_bf16 v[16:19], v[92:95], v[204:207], v[16:19]
	v_mfma_f32_16x16x32_bf16 v[8:11], v[84:87], v[212:215], v[8:11]
	v_mfma_f32_16x16x32_bf16 v[0:3], v[92:95], v[212:215], v[0:3]
	s_nop 15
	s_nop 15
	s_branch .Lp7_after_loop

; #define PG8_STAGE(bufoff, gbase, voff) do { _Pragma("unroll") for (int _i = 0; _i < 2; ++_i) \
;         __builtin_amdgcn_global_load_lds((const unsigned*)((const char*)(gbase) + (voff)[_i]), (PG8_LAS unsigned*)(lds + (bufoff) + ldsw + _i * 8192), 16, 0, 0); } while (0)
; #define PG8_LDA(dst, b, h) do { _Pragma("unroll") for (int m = 0; m < 4; ++m) _Pragma("unroll") for (int k = 0; k < 2; ++k) dst[m][k] = *(const PG8_LAS bf16x8*)(lds + PG8_SA(b, h) + aoff + m * 2048 + k * 1024); } while (0)
; #define PG8_LDB(dst, b, h) do { _Pragma("unroll") for (int n = 0; n < 2; ++n) _Pragma("unroll") for (int k = 0; k < 2; ++k) dst[n][k] = *(const PG8_LAS bf16x8*)(lds + PG8_SB(b, h) + boff + n * 2048 + k * 1024); } while (0)
; #define PG8_MMA(ai, bj, At, Bt) do { __builtin_amdgcn_s_setprio(1); _Pragma("unroll") for (int m = 0; m < 4; ++m) _Pragma("unroll") for (int n = 0; n < 2; ++n) _Pragma("unroll") for (int k = 0; k < 2; ++k) \
;         acc[ai][bj][m][n] = __builtin_amdgcn_mfma_f32_16x16x32_bf16(Bt[n][k], At[m][k], acc[ai][bj][m][n], 0, 0, 0); __builtin_amdgcn_s_setprio(0); } while (0)
; #define PG8_WAIT_V(n) asm volatile("s_waitcnt vmcnt(" #n ")" ::: "memory")
; #define PG8_WAIT_L(n) asm volatile("s_waitcnt lgkmcnt(" #n ")" ::: "memory")
; #define PG8_BAR __builtin_amdgcn_s_barrier()
; #define PG8_SCHED __builtin_amdgcn_sched_barrier(0)
; template <class Epi, class Sched, bool ALIGN_EPI = false, bool SP2 = false>
; __device__ __forceinline__ void gemm_phase(PG8_LAS unsigned char* lds, const Gemm g, const Sched& S, const Epi& E) {
;     ...
;             if constexpr (SP2) {
;             PG8_LDB(B0, 0, 0); PG8_LDB(B1, 0, 1); PG8_SCHED; PG8_LDA(At, 0, 0); PG8_STAGE(PG8_SA(1, 1), a1 + hstepA, voffA);
;             PG8_WAIT_V(8); PG8_WAIT_L(0); PG8_BAR; PG8_MMA(0, 0, At, B0); PG8_MMA(0, 1, At, B1); PG8_BAR; PG8_SCHED;
;             PG8_LDA(At, 0, 1); PG8_STAGE(PG8_SB(0, 0), b2, voffB); PG8_STAGE(PG8_SB(0, 1), b2 + hstepB, voffB); PG8_STAGE(PG8_SA(0, 0), a2, voffA);
;             PG8_WAIT_V(8); PG8_WAIT_L(0); PG8_BAR; PG8_MMA(1, 0, At, B0); PG8_MMA(1, 1, At, B1); PG8_BAR; PG8_SCHED;
;             PG8_LDB(B0, 1, 0); PG8_LDB(B1, 1, 1); PG8_SCHED; PG8_LDA(At, 1, 0); PG8_STAGE(PG8_SA(0, 1), a2 + hstepA, voffA);
;             PG8_WAIT_V(8); PG8_WAIT_L(0); PG8_BAR; PG8_MMA(0, 0, At, B0); PG8_MMA(0, 1, At, B1); PG8_BAR; PG8_SCHED;
.LBB0_1912:
	ds_read_b128 v[144:147], v151
	ds_read_b128 v[154:157], v151 offset:1024
	ds_read_b128 v[158:161], v151 offset:2048
	ds_read_b128 v[162:165], v151 offset:3072
	ds_read_b128 v[166:169], v152
	ds_read_b128 v[170:173], v152 offset:1024
	ds_read_b128 v[174:177], v152 offset:2048
	ds_read_b128 v[178:181], v152 offset:3072
	s_add_u32 s4, s40, 0x100
	s_addc_u32 s5, s41, 0
	s_cmpk_eq_i32 s65, 0x54
	s_cselect_b32 s47, s35, s5
	s_cselect_b32 s46, s34, s4
	s_cselect_b32 s43, s37, s64
	s_cselect_b32 s42, s36, s39
	ds_read_b128 v[182:185], v153
	ds_read_b128 v[186:189], v153 offset:1024
	ds_read_b128 v[190:193], v153 offset:2048
	ds_read_b128 v[194:197], v153 offset:3072
	ds_read_b128 v[198:201], v153 offset:4096
	ds_read_b128 v[202:205], v153 offset:5120
	ds_read_b128 v[206:209], v153 offset:6144
	ds_read_b128 v[210:213], v153 offset:7168
	s_add_u32 s98, s40, 0x80
	s_addc_u32 s99, s41, 0
	s_mov_b32 m0, s55
	s_nop 0
	global_load_lds_dwordx4 v128, s[98:99]
	s_mov_b32 m0, s56
	s_nop 0
	global_load_lds_dwordx4 v132, s[98:99]
	s_add_i32 m0, s50, 0xc000
	s_nop 0
	global_load_lds_dwordx4 v136, s[40:41]
	s_add_i32 m0, s50, 0xe000
	s_nop 0
	global_load_lds_dwordx4 v138, s[40:41]
	s_waitcnt vmcnt(8)
	s_waitcnt lgkmcnt(0)
	s_barrier
	s_setprio 1
	v_mfma_f32_16x16x32_bf16 v[120:123], v[144:147], v[182:185], v[120:123]
	v_mfma_f32_16x16x32_bf16 v[124:127], v[158:161], v[182:185], v[124:127]
	v_mfma_f32_16x16x32_bf16 v[104:107], v[144:147], v[190:193], v[104:107]
	v_mfma_f32_16x16x32_bf16 v[108:111], v[158:161], v[190:193], v[108:111]
	v_mfma_f32_16x16x32_bf16 v[88:91], v[144:147], v[198:201], v[88:91]
	v_mfma_f32_16x16x32_bf16 v[92:95], v[158:161], v[198:201], v[92:95]
	v_mfma_f32_16x16x32_bf16 v[72:75], v[144:147], v[206:209], v[72:75]
	v_mfma_f32_16x16x32_bf16 v[76:79], v[158:161], v[206:209], v[76:79]
	v_mfma_f32_16x16x32_bf16 v[120:123], v[154:157], v[186:189], v[120:123]
	v_mfma_f32_16x16x32_bf16 v[124:127], v[162:165], v[186:189], v[124:127]
	v_mfma_f32_16x16x32_bf16 v[104:107], v[154:157], v[194:197], v[104:107]
	v_mfma_f32_16x16x32_bf16 v[108:111], v[162:165], v[194:197], v[108:111]
	v_mfma_f32_16x16x32_bf16 v[88:91], v[154:157], v[202:205], v[88:91]
	v_mfma_f32_16x16x32_bf16 v[92:95], v[162:165], v[202:205], v[92:95]
	v_mfma_f32_16x16x32_bf16 v[72:75], v[154:157], v[210:213], v[72:75]
	v_mfma_f32_16x16x32_bf16 v[76:79], v[162:165], v[210:213], v[76:79]
	v_mfma_f32_16x16x32_bf16 v[112:115], v[166:169], v[182:185], v[112:115]
	v_mfma_f32_16x16x32_bf16 v[116:119], v[174:177], v[182:185], v[116:119]
	v_mfma_f32_16x16x32_bf16 v[96:99], v[166:169], v[190:193], v[96:99]
	v_mfma_f32_16x16x32_bf16 v[100:103], v[174:177], v[190:193], v[100:103]
	v_mfma_f32_16x16x32_bf16 v[80:83], v[166:169], v[198:201], v[80:83]
	v_mfma_f32_16x16x32_bf16 v[84:87], v[174:177], v[198:201], v[84:87]
	v_mfma_f32_16x16x32_bf16 v[64:67], v[166:169], v[206:209], v[64:67]
	v_mfma_f32_16x16x32_bf16 v[68:71], v[174:177], v[206:209], v[68:71]
	v_mfma_f32_16x16x32_bf16 v[112:115], v[170:173], v[186:189], v[112:115]
	v_mfma_f32_16x16x32_bf16 v[116:119], v[178:181], v[186:189], v[116:119]
	v_mfma_f32_16x16x32_bf16 v[96:99], v[170:173], v[194:197], v[96:99]
	v_mfma_f32_16x16x32_bf16 v[100:103], v[178:181], v[194:197], v[100:103]
	v_mfma_f32_16x16x32_bf16 v[80:83], v[170:173], v[202:205], v[80:83]
	v_mfma_f32_16x16x32_bf16 v[84:87], v[178:181], v[202:205], v[84:87]
	v_mfma_f32_16x16x32_bf16 v[64:67], v[170:173], v[210:213], v[64:67]
	v_mfma_f32_16x16x32_bf16 v[68:71], v[178:181], v[210:213], v[68:71]
	s_setprio 0
	s_barrier
	s_add_i32 s40, s58, s33
	s_mov_b32 m0, s40
	ds_read_b128 v[182:185], v153 offset:16384
	ds_read_b128 v[186:189], v153 offset:17408
	ds_read_b128 v[190:193], v153 offset:18432
	ds_read_b128 v[194:197], v153 offset:19456
	ds_read_b128 v[198:201], v153 offset:20480
	ds_read_b128 v[202:205], v153 offset:21504
	ds_read_b128 v[206:209], v153 offset:22528
	ds_read_b128 v[210:213], v153 offset:23552
	global_load_lds_dwordx4 v130, s[42:43]
	s_add_i32 m0, s40, 0x2000
	s_add_u32 s40, s42, 0x160000
	s_addc_u32 s41, s43, 0
	s_add_i32 s66, s59, s33
	global_load_lds_dwordx4 v134, s[42:43]
	s_mov_b32 m0, s66
	s_nop 0
	global_load_lds_dwordx4 v130, s[40:41]
	s_add_i32 m0, s66, 0x2000
	s_nop 0
	global_load_lds_dwordx4 v134, s[40:41]
	s_waitcnt vmcnt(6)
	s_waitcnt lgkmcnt(0)
	s_barrier
	s_setprio 1
	v_mfma_f32_16x16x32_bf16 v[56:59], v[144:147], v[182:185], v[56:59]
	v_mfma_f32_16x16x32_bf16 v[60:63], v[158:161], v[182:185], v[60:63]
	v_mfma_f32_16x16x32_bf16 v[40:43], v[144:147], v[190:193], v[40:43]
	v_mfma_f32_16x16x32_bf16 v[44:47], v[158:161], v[190:193], v[44:47]
	v_mfma_f32_16x16x32_bf16 v[24:27], v[144:147], v[198:201], v[24:27]
	v_mfma_f32_16x16x32_bf16 v[28:31], v[158:161], v[198:201], v[28:31]
	v_mfma_f32_16x16x32_bf16 v[8:11], v[144:147], v[206:209], v[8:11]
	v_mfma_f32_16x16x32_bf16 v[12:15], v[158:161], v[206:209], v[12:15]
	v_mfma_f32_16x16x32_bf16 v[56:59], v[154:157], v[186:189], v[56:59]
	v_mfma_f32_16x16x32_bf16 v[60:63], v[162:165], v[186:189], v[60:63]
	v_mfma_f32_16x16x32_bf16 v[40:43], v[154:157], v[194:197], v[40:43]
	v_mfma_f32_16x16x32_bf16 v[44:47], v[162:165], v[194:197], v[44:47]
	v_mfma_f32_16x16x32_bf16 v[24:27], v[154:157], v[202:205], v[24:27]
	v_mfma_f32_16x16x32_bf16 v[28:31], v[162:165], v[202:205], v[28:31]
	v_mfma_f32_16x16x32_bf16 v[8:11], v[154:157], v[210:213], v[8:11]
	v_mfma_f32_16x16x32_bf16 v[12:15], v[162:165], v[210:213], v[12:15]
	v_mfma_f32_16x16x32_bf16 v[48:51], v[166:169], v[182:185], v[48:51]
	v_mfma_f32_16x16x32_bf16 v[52:55], v[174:177], v[182:185], v[52:55]
	v_mfma_f32_16x16x32_bf16 v[32:35], v[166:169], v[190:193], v[32:35]
	v_mfma_f32_16x16x32_bf16 v[36:39], v[174:177], v[190:193], v[36:39]
	v_mfma_f32_16x16x32_bf16 v[16:19], v[166:169], v[198:201], v[16:19]
	v_mfma_f32_16x16x32_bf16 v[20:23], v[174:177], v[198:201], v[20:23]
	v_mfma_f32_16x16x32_bf16 v[4:7], v[166:169], v[206:209], v[4:7]
	v_mfma_f32_16x16x32_bf16 v[0:3], v[174:177], v[206:209], v[0:3]
	v_mfma_f32_16x16x32_bf16 v[48:51], v[170:173], v[186:189], v[48:51]
	v_mfma_f32_16x16x32_bf16 v[52:55], v[178:181], v[186:189], v[52:55]
	v_mfma_f32_16x16x32_bf16 v[32:35], v[170:173], v[194:197], v[32:35]
	v_mfma_f32_16x16x32_bf16 v[36:39], v[178:181], v[194:197], v[36:39]
	v_mfma_f32_16x16x32_bf16 v[16:19], v[170:173], v[202:205], v[16:19]
	v_mfma_f32_16x16x32_bf16 v[20:23], v[178:181], v[202:205], v[20:23]
	v_mfma_f32_16x16x32_bf16 v[4:7], v[170:173], v[210:213], v[4:7]
	v_mfma_f32_16x16x32_bf16 v[0:3], v[178:181], v[210:213], v[0:3]
	s_setprio 0
	s_barrier
; #define PG8_STAGE(bufoff, gbase, voff) do { _Pragma("unroll") for (int _i = 0; _i < 2; ++_i) \
;         __builtin_amdgcn_global_load_lds((const unsigned*)((const char*)(gbase) + (voff)[_i]), (PG8_LAS unsigned*)(lds + (bufoff) + ldsw + _i * 8192), 16, 0, 0); } while (0)
; #define PG8_LDA(dst, b, h) do { _Pragma("unroll") for (int m = 0; m < 4; ++m) _Pragma("unroll") for (int k = 0; k < 2; ++k) dst[m][k] = *(const PG8_LAS bf16x8*)(lds + PG8_SA(b, h) + aoff + m * 2048 + k * 1024); } while (0)
; #define PG8_LDB(dst, b, h) do { _Pragma("unroll") for (int n = 0; n < 2; ++n) _Pragma("unroll") for (int k = 0; k < 2; ++k) dst[n][k] = *(const PG8_LAS bf16x8*)(lds + PG8_SB(b, h) + boff + n * 2048 + k * 1024); } while (0)
; #define PG8_MMA(ai, bj, At, Bt) do { __builtin_amdgcn_s_setprio(1); _Pragma("unroll") for (int m = 0; m < 4; ++m) _Pragma("unroll") for (int n = 0; n < 2; ++n) _Pragma("unroll") for (int k = 0; k < 2; ++k) \
;         acc[ai][bj][m][n] = __builtin_amdgcn_mfma_f32_16x16x32_bf16(Bt[n][k], At[m][k], acc[ai][bj][m][n], 0, 0, 0); __builtin_amdgcn_s_setprio(0); } while (0)
; #define PG8_WAIT_V(n) asm volatile("s_waitcnt vmcnt(" #n ")" ::: "memory")
; #define PG8_WAIT_L(n) asm volatile("s_waitcnt lgkmcnt(" #n ")" ::: "memory")
; #define PG8_BAR __builtin_amdgcn_s_barrier()
; #define PG8_SCHED __builtin_amdgcn_sched_barrier(0)
; template <class Epi, class Sched, bool ALIGN_EPI = false, bool SP2 = false>
; __device__ __forceinline__ void gemm_phase(PG8_LAS unsigned char* lds, const Gemm g, const Sched& S, const Epi& E) {
;     ...
;             PG8_LDB(B0, 1, 0); PG8_LDB(B1, 1, 1); PG8_SCHED; PG8_LDA(At, 1, 0); PG8_STAGE(PG8_SA(0, 1), a2 + hstepA, voffA);
;             PG8_WAIT_V(8); PG8_WAIT_L(0); PG8_BAR; PG8_MMA(0, 0, At, B0); PG8_MMA(0, 1, At, B1); PG8_BAR; PG8_SCHED;
;             PG8_LDA(At, 1, 1); PG8_STAGE(PG8_SB(1, 0), b3, voffB); PG8_STAGE(PG8_SB(1, 1), b3 + hstepB, voffB); PG8_STAGE(PG8_SA(1, 0), a3, voffA);
;             PG8_WAIT_V(8); PG8_WAIT_L(0); PG8_BAR; PG8_MMA(1, 0, At, B0); PG8_MMA(1, 1, At, B1); PG8_BAR; PG8_SCHED;
	s_add_i32 s66, 0, 0x18000
	s_add_i32 s67, 0, 0x1c000
	v_add_u32_e32 v162, s66, v150
	v_add_u32_e32 v178, s67, v150
	ds_read_b128 v[144:147], v162
	ds_read_b128 v[154:157], v162 offset:1024
	ds_read_b128 v[158:161], v162 offset:2048
	ds_read_b128 v[162:165], v162 offset:3072
	ds_read_b128 v[166:169], v178
	ds_read_b128 v[170:173], v178 offset:1024
	ds_read_b128 v[174:177], v178 offset:2048
	ds_read_b128 v[178:181], v178 offset:3072
	s_add_u32 s40, s46, 0x160000
	s_addc_u32 s41, s47, 0
	ds_read_b128 v[182:185], v153 offset:32768
	ds_read_b128 v[186:189], v153 offset:33792
	ds_read_b128 v[190:193], v153 offset:34816
	ds_read_b128 v[194:197], v153 offset:35840
	ds_read_b128 v[198:201], v153 offset:36864
	ds_read_b128 v[202:205], v153 offset:37888
	ds_read_b128 v[206:209], v153 offset:38912
	ds_read_b128 v[210:213], v153 offset:39936
	s_mov_b32 m0, s50
	s_nop 0
	global_load_lds_dwordx4 v128, s[46:47]
	s_mov_b32 m0, s51
	s_nop 0
	global_load_lds_dwordx4 v132, s[46:47]
	s_mov_b32 m0, s52
	s_nop 0
	global_load_lds_dwordx4 v128, s[40:41]
	s_mov_b32 m0, s53
	s_nop 0
	global_load_lds_dwordx4 v132, s[40:41]
	s_waitcnt vmcnt(8)
	s_waitcnt lgkmcnt(0)
	s_barrier
	s_setprio 1
	v_mfma_f32_16x16x32_bf16 v[120:123], v[144:147], v[182:185], v[120:123]
	v_mfma_f32_16x16x32_bf16 v[124:127], v[158:161], v[182:185], v[124:127]
	v_mfma_f32_16x16x32_bf16 v[104:107], v[144:147], v[190:193], v[104:107]
	v_mfma_f32_16x16x32_bf16 v[108:111], v[158:161], v[190:193], v[108:111]
	v_mfma_f32_16x16x32_bf16 v[88:91], v[144:147], v[198:201], v[88:91]
	v_mfma_f32_16x16x32_bf16 v[92:95], v[158:161], v[198:201], v[92:95]
	v_mfma_f32_16x16x32_bf16 v[72:75], v[144:147], v[206:209], v[72:75]
	v_mfma_f32_16x16x32_bf16 v[76:79], v[158:161], v[206:209], v[76:79]
	v_mfma_f32_16x16x32_bf16 v[120:123], v[154:157], v[186:189], v[120:123]
	v_mfma_f32_16x16x32_bf16 v[124:127], v[162:165], v[186:189], v[124:127]
	v_mfma_f32_16x16x32_bf16 v[104:107], v[154:157], v[194:197], v[104:107]
	v_mfma_f32_16x16x32_bf16 v[108:111], v[162:165], v[194:197], v[108:111]
	v_mfma_f32_16x16x32_bf16 v[88:91], v[154:157], v[202:205], v[88:91]
	v_mfma_f32_16x16x32_bf16 v[92:95], v[162:165], v[202:205], v[92:95]
	v_mfma_f32_16x16x32_bf16 v[72:75], v[154:157], v[210:213], v[72:75]
	v_mfma_f32_16x16x32_bf16 v[76:79], v[162:165], v[210:213], v[76:79]
	v_mfma_f32_16x16x32_bf16 v[112:115], v[166:169], v[182:185], v[112:115]
	v_mfma_f32_16x16x32_bf16 v[116:119], v[174:177], v[182:185], v[116:119]
	v_mfma_f32_16x16x32_bf16 v[96:99], v[166:169], v[190:193], v[96:99]
	v_mfma_f32_16x16x32_bf16 v[100:103], v[174:177], v[190:193], v[100:103]
	v_mfma_f32_16x16x32_bf16 v[80:83], v[166:169], v[198:201], v[80:83]
	v_mfma_f32_16x16x32_bf16 v[84:87], v[174:177], v[198:201], v[84:87]
	v_mfma_f32_16x16x32_bf16 v[64:67], v[166:169], v[206:209], v[64:67]
	v_mfma_f32_16x16x32_bf16 v[68:71], v[174:177], v[206:209], v[68:71]
	v_mfma_f32_16x16x32_bf16 v[112:115], v[170:173], v[186:189], v[112:115]
	v_mfma_f32_16x16x32_bf16 v[116:119], v[178:181], v[186:189], v[116:119]
	v_mfma_f32_16x16x32_bf16 v[96:99], v[170:173], v[194:197], v[96:99]
	v_mfma_f32_16x16x32_bf16 v[100:103], v[178:181], v[194:197], v[100:103]
	v_mfma_f32_16x16x32_bf16 v[80:83], v[170:173], v[202:205], v[80:83]
	v_mfma_f32_16x16x32_bf16 v[84:87], v[178:181], v[202:205], v[84:87]
	v_mfma_f32_16x16x32_bf16 v[64:67], v[170:173], v[210:213], v[64:67]
	v_mfma_f32_16x16x32_bf16 v[68:71], v[178:181], v[210:213], v[68:71]
	s_setprio 0
	s_barrier
	s_add_i32 s40, s66, s33
	s_add_u32 s98, s42, 0x80
	s_addc_u32 s99, s43, 0
	s_mov_b32 m0, s40
	ds_read_b128 v[182:185], v153 offset:49152
	ds_read_b128 v[186:189], v153 offset:50176
	ds_read_b128 v[190:193], v153 offset:51200
	ds_read_b128 v[194:197], v153 offset:52224
	ds_read_b128 v[198:201], v153 offset:53248
	ds_read_b128 v[202:205], v153 offset:54272
	ds_read_b128 v[206:209], v153 offset:55296
	ds_read_b128 v[210:213], v153 offset:56320
	global_load_lds_dwordx4 v130, s[98:99]
	s_add_i32 m0, s40, 0x2000
	s_add_u32 s40, s42, 0x160080
	s_addc_u32 s41, s43, 0
	s_add_i32 s42, s67, s33
	global_load_lds_dwordx4 v134, s[98:99]
	s_mov_b32 m0, s42
	s_nop 0
	global_load_lds_dwordx4 v130, s[40:41]
	s_add_i32 m0, s42, 0x2000
	s_nop 0
	global_load_lds_dwordx4 v134, s[40:41]
	s_waitcnt vmcnt(6)
	s_waitcnt lgkmcnt(0)
	s_barrier
	s_setprio 1
	v_mfma_f32_16x16x32_bf16 v[56:59], v[144:147], v[182:185], v[56:59]
	v_mfma_f32_16x16x32_bf16 v[60:63], v[158:161], v[182:185], v[60:63]
	v_mfma_f32_16x16x32_bf16 v[40:43], v[144:147], v[190:193], v[40:43]
	v_mfma_f32_16x16x32_bf16 v[44:47], v[158:161], v[190:193], v[44:47]
	v_mfma_f32_16x16x32_bf16 v[24:27], v[144:147], v[198:201], v[24:27]
	v_mfma_f32_16x16x32_bf16 v[28:31], v[158:161], v[198:201], v[28:31]
	v_mfma_f32_16x16x32_bf16 v[8:11], v[144:147], v[206:209], v[8:11]
	v_mfma_f32_16x16x32_bf16 v[12:15], v[158:161], v[206:209], v[12:15]
	v_mfma_f32_16x16x32_bf16 v[56:59], v[154:157], v[186:189], v[56:59]
	v_mfma_f32_16x16x32_bf16 v[60:63], v[162:165], v[186:189], v[60:63]
	v_mfma_f32_16x16x32_bf16 v[40:43], v[154:157], v[194:197], v[40:43]
	v_mfma_f32_16x16x32_bf16 v[44:47], v[162:165], v[194:197], v[44:47]
	v_mfma_f32_16x16x32_bf16 v[24:27], v[154:157], v[202:205], v[24:27]
	v_mfma_f32_16x16x32_bf16 v[28:31], v[162:165], v[202:205], v[28:31]
	v_mfma_f32_16x16x32_bf16 v[8:11], v[154:157], v[210:213], v[8:11]
	v_mfma_f32_16x16x32_bf16 v[12:15], v[162:165], v[210:213], v[12:15]
	v_mfma_f32_16x16x32_bf16 v[48:51], v[166:169], v[182:185], v[48:51]
	v_mfma_f32_16x16x32_bf16 v[52:55], v[174:177], v[182:185], v[52:55]
	v_mfma_f32_16x16x32_bf16 v[32:35], v[166:169], v[190:193], v[32:35]
	v_mfma_f32_16x16x32_bf16 v[36:39], v[174:177], v[190:193], v[36:39]
	v_mfma_f32_16x16x32_bf16 v[16:19], v[166:169], v[198:201], v[16:19]
	v_mfma_f32_16x16x32_bf16 v[20:23], v[174:177], v[198:201], v[20:23]
	v_mfma_f32_16x16x32_bf16 v[4:7], v[166:169], v[206:209], v[4:7]
	v_mfma_f32_16x16x32_bf16 v[0:3], v[174:177], v[206:209], v[0:3]
	v_mfma_f32_16x16x32_bf16 v[48:51], v[170:173], v[186:189], v[48:51]
	v_mfma_f32_16x16x32_bf16 v[52:55], v[178:181], v[186:189], v[52:55]
	v_mfma_f32_16x16x32_bf16 v[32:35], v[170:173], v[194:197], v[32:35]
	v_mfma_f32_16x16x32_bf16 v[36:39], v[178:181], v[194:197], v[36:39]
	v_mfma_f32_16x16x32_bf16 v[16:19], v[170:173], v[202:205], v[16:19]
	v_mfma_f32_16x16x32_bf16 v[20:23], v[178:181], v[202:205], v[20:23]
	v_mfma_f32_16x16x32_bf16 v[4:7], v[170:173], v[210:213], v[4:7]
	v_mfma_f32_16x16x32_bf16 v[0:3], v[178:181], v[210:213], v[0:3]
	s_setprio 0
	s_barrier
	s_add_i32 s65, s65, 2
	s_add_u32 s39, s39, 0x100
	s_addc_u32 s64, s64, 0
	s_cmpk_gt_u32 s65, 0x55
	s_mov_b64 s[40:41], s[4:5]
	s_cbranch_scc0 .LBB0_1912
	s_and_b64 vcc, exec, s[14:15]
	s_cbranch_vccz .LBB0_1915
	s_barrier
